# P0 x->xb/rstd1 loop restructured (16 rows/wave, nt loads issued 4 rows ahead, xor-butterfly sum via DPP + 4 readlanes in the baseline order instead of 6 ds_bpermute round trips); on top of v_rsl
# speedup vs baseline: 1.0036x; 1.0036x over previous
; __device__ __forceinline__ unsigned pk2(float lo, float hi) { return f2bf(lo) | (f2bf(hi) << 16); }
; __device__ __forceinline__ void phase_prologue(const Params& p, LAS unsigned char* lds) {
;     ...
;     { const float* x = p.in[I_X]; bf16* xb = (bf16*)(ws + WS_XB); float* rstd = (float*)(ws + WS_RSTD1);
;       constexpr int UR = 4;
;       for (int row0 = gw; row0 < T; row0 += UR * NGW) { f32x4 v[UR][8]; float s[UR];
; #pragma unroll
;           for (int u = 0; u < UR; ++u) { const f32x4* xr = (const f32x4*)(x + (size_t)(row0 + u * NGW) * DM) + lane;
; #pragma unroll
;               for (int j = 0; j < 8; ++j) v[u][j] = __builtin_nontemporal_load(xr + 64 * j); }
; #pragma unroll
;           for (int u = 0; u < UR; ++u) { const int row = row0 + u * NGW; s[u] = 0.f;
; #pragma unroll
;               for (int j = 0; j < 8; ++j) s[u] += (v[u][j][0] * v[u][j][0] + v[u][j][1] * v[u][j][1]) + (v[u][j][2] * v[u][j][2] + v[u][j][3] * v[u][j][3]);
;               s[u] = wave_sum(s[u]); if (lane == 0) rstd[row] = 1.0f / sqrtf(s[u] * (1.0f / DM) + 1e-6f);
;               u32x2* o = (u32x2*)(xb + (size_t)row * DM) + lane;
; #pragma unroll
;               for (int j = 0; j < 8; ++j) { u32x2 w; w.x = pk2(v[u][j][0], v[u][j][1]); w.y = pk2(v[u][j][2], v[u][j][3]); o[64 * j] = w; } } } }
.LBB0_305:
	s_or_b64 exec, exec, s[0:1]
	s_mov_b32 s0, 0x8000
	v_cmp_gt_i32_e32 vcc, s0, v130
	s_and_saveexec_b64 s[10:11], vcc
	s_cbranch_execz .LBB0_316
	v_readfirstlane_b32 s3, v130
	v_and_b32_e32 v4, 63, v144
	v_readlane_b32 s0, v244, 0
	v_lshlrev_b32_e32 v1, 4, v4
	v_lshlrev_b32_e32 v3, 3, v4
	v_add_u32_e32 v2, 0x1000, v1
	v_mov_b32_e32 v4, 0
	v_mov_b32_e32 v5, 0x7fff
	v_mov_b32_e32 v6, 0xffff0000
	v_mov_b32_e32 v7, 0xf800000
	v_mov_b32_e32 v136, 0x358637bd
	v_mov_b32_e32 v137, 0x260
	s_lshl_b32 s5, s0, 3
	s_mul_i32 s4, s5, 0
	s_add_u32 s4, s4, s3
	s_lshl_b32 s4, s4, 13
	s_add_u32 s12, s68, s4
	s_addc_u32 s13, s69, 0
	global_load_dwordx4 v[8:11], v1, s[12:13] nt
	global_load_dwordx4 v[12:15], v1, s[12:13] offset:1024 nt
	global_load_dwordx4 v[16:19], v1, s[12:13] offset:2048 nt
	global_load_dwordx4 v[20:23], v1, s[12:13] offset:3072 nt
	global_load_dwordx4 v[24:27], v2, s[12:13] nt
	global_load_dwordx4 v[28:31], v2, s[12:13] offset:1024 nt
	global_load_dwordx4 v[32:35], v2, s[12:13] offset:2048 nt
	global_load_dwordx4 v[36:39], v2, s[12:13] offset:3072 nt
	s_mul_i32 s4, s5, 1
	s_add_u32 s4, s4, s3
	s_lshl_b32 s4, s4, 13
	s_add_u32 s14, s68, s4
	s_addc_u32 s15, s69, 0
	global_load_dwordx4 v[40:43], v1, s[14:15] nt
	global_load_dwordx4 v[44:47], v1, s[14:15] offset:1024 nt
	global_load_dwordx4 v[48:51], v1, s[14:15] offset:2048 nt
	global_load_dwordx4 v[52:55], v1, s[14:15] offset:3072 nt
	global_load_dwordx4 v[56:59], v2, s[14:15] nt
	global_load_dwordx4 v[60:63], v2, s[14:15] offset:1024 nt
	global_load_dwordx4 v[64:67], v2, s[14:15] offset:2048 nt
	global_load_dwordx4 v[68:71], v2, s[14:15] offset:3072 nt
	s_mul_i32 s4, s5, 2
	s_add_u32 s4, s4, s3
	s_lshl_b32 s4, s4, 13
	s_add_u32 s12, s68, s4
	s_addc_u32 s13, s69, 0
	global_load_dwordx4 v[72:75], v1, s[12:13] nt
	global_load_dwordx4 v[76:79], v1, s[12:13] offset:1024 nt
	global_load_dwordx4 v[80:83], v1, s[12:13] offset:2048 nt
	global_load_dwordx4 v[84:87], v1, s[12:13] offset:3072 nt
	global_load_dwordx4 v[88:91], v2, s[12:13] nt
	global_load_dwordx4 v[92:95], v2, s[12:13] offset:1024 nt
	global_load_dwordx4 v[96:99], v2, s[12:13] offset:2048 nt
	global_load_dwordx4 v[100:103], v2, s[12:13] offset:3072 nt
	s_mul_i32 s4, s5, 3
	s_add_u32 s4, s4, s3
	s_lshl_b32 s4, s4, 13
	s_add_u32 s14, s68, s4
	s_addc_u32 s15, s69, 0
	global_load_dwordx4 v[104:107], v1, s[14:15] nt
	global_load_dwordx4 v[108:111], v1, s[14:15] offset:1024 nt
	global_load_dwordx4 v[112:115], v1, s[14:15] offset:2048 nt
	global_load_dwordx4 v[116:119], v1, s[14:15] offset:3072 nt
	global_load_dwordx4 v[120:123], v2, s[14:15] nt
	global_load_dwordx4 v[124:127], v2, s[14:15] offset:1024 nt
	global_load_dwordx4 v[128:131], v2, s[14:15] offset:2048 nt
	global_load_dwordx4 v[132:135], v2, s[14:15] offset:3072 nt
	s_waitcnt vmcnt(31)
	v_mul_f32_e32 v138, v9, v9
	v_mul_f32_e32 v139, v11, v11
	v_fmac_f32_e32 v138, v8, v8
	v_fmac_f32_e32 v139, v10, v10
	v_add_f32_e32 v140, v138, v139
	s_waitcnt vmcnt(30)
	v_mul_f32_e32 v138, v13, v13
	v_mul_f32_e32 v139, v15, v15
	v_fmac_f32_e32 v138, v12, v12
	v_fmac_f32_e32 v139, v14, v14
	v_add_f32_e32 v141, v138, v139
	v_add_f32_e32 v140, v140, v141
	s_waitcnt vmcnt(29)
	v_mul_f32_e32 v138, v17, v17
	v_mul_f32_e32 v139, v19, v19
	v_fmac_f32_e32 v138, v16, v16
	v_fmac_f32_e32 v139, v18, v18
	v_add_f32_e32 v141, v138, v139
	v_add_f32_e32 v140, v140, v141
	s_waitcnt vmcnt(28)
	v_mul_f32_e32 v138, v21, v21
	v_mul_f32_e32 v139, v23, v23
	v_fmac_f32_e32 v138, v20, v20
	v_fmac_f32_e32 v139, v22, v22
	v_add_f32_e32 v141, v138, v139
	v_add_f32_e32 v140, v140, v141
	s_waitcnt vmcnt(27)
	v_mul_f32_e32 v138, v25, v25
	v_mul_f32_e32 v139, v27, v27
	v_fmac_f32_e32 v138, v24, v24
	v_fmac_f32_e32 v139, v26, v26
	v_add_f32_e32 v141, v138, v139
	v_add_f32_e32 v140, v140, v141
	s_waitcnt vmcnt(26)
	v_mul_f32_e32 v138, v29, v29
	v_mul_f32_e32 v139, v31, v31
	v_fmac_f32_e32 v138, v28, v28
	v_fmac_f32_e32 v139, v30, v30
	v_add_f32_e32 v141, v138, v139
	v_add_f32_e32 v140, v140, v141
	s_waitcnt vmcnt(25)
	v_mul_f32_e32 v138, v33, v33
	v_mul_f32_e32 v139, v35, v35
	v_fmac_f32_e32 v138, v32, v32
	v_fmac_f32_e32 v139, v34, v34
	v_add_f32_e32 v141, v138, v139
	v_add_f32_e32 v140, v140, v141
	s_waitcnt vmcnt(24)
	v_mul_f32_e32 v138, v37, v37
	v_mul_f32_e32 v139, v39, v39
	v_fmac_f32_e32 v138, v36, v36
	v_fmac_f32_e32 v139, v38, v38
	v_add_f32_e32 v141, v138, v139
	v_add_f32_e32 v140, v140, v141
	s_nop 1
	v_add_f32_dpp v140, v140, v140 quad_perm:[1,0,3,2] row_mask:0xf bank_mask:0xf
	s_nop 1
	v_add_f32_dpp v140, v140, v140 quad_perm:[2,3,0,1] row_mask:0xf bank_mask:0xf
	s_nop 1
	v_add_f32_dpp v140, v140, v140 row_half_mirror row_mask:0xf bank_mask:0xf
	s_nop 1
	v_add_f32_dpp v140, v140, v140 row_mirror row_mask:0xf bank_mask:0xf
	s_nop 1
	v_readlane_b32 s38, v140, 0
	v_readlane_b32 s39, v140, 16
	v_readlane_b32 s52, v140, 32
	v_readlane_b32 s53, v140, 48
	s_nop 1
	v_mov_b32_e32 v161, s39
	v_mov_b32_e32 v163, s53
	v_add_f32_e32 v161, s38, v161
	v_add_f32_e32 v163, s52, v163
	v_add_f32_e32 v146, v161, v163
	v_fmamk_f32 v147, v146, 0x3a000000, v136
	v_mul_f32_e32 v148, 0x4f800000, v147
	v_cmp_gt_f32_e32 vcc, v7, v147
	s_nop 1
	v_cndmask_b32_e32 v149, v147, v148, vcc
	v_sqrt_f32_e32 v150, v149
	s_nop 0
	v_add_u32_e32 v151, -1, v150
	v_add_u32_e32 v152, 1, v150
	v_fma_f32 v153, -v151, v150, v149
	v_fma_f32 v154, -v152, v150, v149
	v_cmp_ge_f32_e64 s[0:1], 0, v153
	s_nop 1
	v_cndmask_b32_e64 v155, v150, v151, s[0:1]
	v_cmp_lt_f32_e64 s[0:1], 0, v154
	s_nop 1
	v_cndmask_b32_e64 v155, v155, v152, s[0:1]
	v_mul_f32_e32 v156, 0x37800000, v155
	v_cndmask_b32_e32 v155, v155, v156, vcc
	v_cmp_class_f32_e32 vcc, v149, v137
; __device__ __forceinline__ unsigned pk2(float lo, float hi) { return f2bf(lo) | (f2bf(hi) << 16); }
; __device__ __forceinline__ void phase_prologue(const Params& p, LAS unsigned char* lds) {
;     ...
;           for (int u = 0; u < UR; ++u) { const int row = row0 + u * NGW; s[u] = 0.f;
; #pragma unroll
;               for (int j = 0; j < 8; ++j) s[u] += (v[u][j][0] * v[u][j][0] + v[u][j][1] * v[u][j][1]) + (v[u][j][2] * v[u][j][2] + v[u][j][3] * v[u][j][3]);
;               s[u] = wave_sum(s[u]); if (lane == 0) rstd[row] = 1.0f / sqrtf(s[u] * (1.0f / DM) + 1e-6f);
;               u32x2* o = (u32x2*)(xb + (size_t)row * DM) + lane;
; #pragma unroll
;               for (int j = 0; j < 8; ++j) { u32x2 w; w.x = pk2(v[u][j][0], v[u][j][1]); w.y = pk2(v[u][j][2], v[u][j][3]); o[64 * j] = w; } } } }
	s_nop 1
	v_cndmask_b32_e32 v157, v155, v149, vcc
	v_div_scale_f32 v158, s[0:1], v157, v157, 1.0
	v_rcp_f32_e32 v159, v158
	v_div_scale_f32 v160, vcc, 1.0, v157, 1.0
	v_fma_f32 v161, -v158, v159, 1.0
	v_fmac_f32_e32 v159, v161, v159
	v_mul_f32_e32 v162, v160, v159
	v_fma_f32 v163, -v158, v162, v160
	v_fmac_f32_e32 v162, v163, v159
	v_fma_f32 v161, -v158, v162, v160
	v_div_fmas_f32 v164, v161, v159, v162
	v_div_fixup_f32 v165, v164, v157, 1.0
	s_mul_i32 s4, s5, 0
	s_add_u32 s4, s4, s3
	s_lshl_b32 s33, s4, 2
	s_add_u32 s36, s28, s33
	s_addc_u32 s37, s29, 0
	s_add_u32 s36, s36, 0x7c00000
	s_addc_u32 s37, s37, 0
	s_lshl_b32 s33, s4, 12
	s_add_u32 s16, s28, s33
	s_addc_u32 s17, s29, 0
	s_add_u32 s16, s16, 0x8800000
	s_addc_u32 s17, s17, 0
	s_mov_b64 exec, 1
	global_store_dword v4, v165, s[36:37]
	s_mov_b64 exec, -1
	v_bfe_u32 v166, v8, 16, 1
	v_add3_u32 v8, v8, v166, v5
	v_bfe_u32 v166, v9, 16, 1
	v_add3_u32 v9, v9, v166, v5
	v_bfe_u32 v166, v10, 16, 1
	v_add3_u32 v10, v10, v166, v5
	v_bfe_u32 v166, v11, 16, 1
	v_add3_u32 v11, v11, v166, v5
	v_lshrrev_b32_e32 v8, 16, v8
	v_lshrrev_b32_e32 v10, 16, v10
	v_and_or_b32 v8, v9, v6, v8
	v_and_or_b32 v9, v11, v6, v10
	global_store_dwordx2 v3, v[8:9], s[16:17]
	v_bfe_u32 v166, v12, 16, 1
	v_add3_u32 v12, v12, v166, v5
	v_bfe_u32 v166, v13, 16, 1
	v_add3_u32 v13, v13, v166, v5
	v_bfe_u32 v166, v14, 16, 1
	v_add3_u32 v14, v14, v166, v5
	v_bfe_u32 v166, v15, 16, 1
	v_add3_u32 v15, v15, v166, v5
	v_lshrrev_b32_e32 v12, 16, v12
	v_lshrrev_b32_e32 v14, 16, v14
	v_and_or_b32 v12, v13, v6, v12
	v_and_or_b32 v13, v15, v6, v14
	global_store_dwordx2 v3, v[12:13], s[16:17] offset:512
	v_bfe_u32 v166, v16, 16, 1
	v_add3_u32 v16, v16, v166, v5
	v_bfe_u32 v166, v17, 16, 1
	v_add3_u32 v17, v17, v166, v5
	v_bfe_u32 v166, v18, 16, 1
	v_add3_u32 v18, v18, v166, v5
	v_bfe_u32 v166, v19, 16, 1
	v_add3_u32 v19, v19, v166, v5
	v_lshrrev_b32_e32 v16, 16, v16
	v_lshrrev_b32_e32 v18, 16, v18
	v_and_or_b32 v16, v17, v6, v16
	v_and_or_b32 v17, v19, v6, v18
	global_store_dwordx2 v3, v[16:17], s[16:17] offset:1024
	v_bfe_u32 v166, v20, 16, 1
	v_add3_u32 v20, v20, v166, v5
	v_bfe_u32 v166, v21, 16, 1
	v_add3_u32 v21, v21, v166, v5
	v_bfe_u32 v166, v22, 16, 1
	v_add3_u32 v22, v22, v166, v5
	v_bfe_u32 v166, v23, 16, 1
	v_add3_u32 v23, v23, v166, v5
	v_lshrrev_b32_e32 v20, 16, v20
	v_lshrrev_b32_e32 v22, 16, v22
	v_and_or_b32 v20, v21, v6, v20
	v_and_or_b32 v21, v23, v6, v22
	global_store_dwordx2 v3, v[20:21], s[16:17] offset:1536
	v_bfe_u32 v166, v24, 16, 1
	v_add3_u32 v24, v24, v166, v5
	v_bfe_u32 v166, v25, 16, 1
	v_add3_u32 v25, v25, v166, v5
	v_bfe_u32 v166, v26, 16, 1
	v_add3_u32 v26, v26, v166, v5
	v_bfe_u32 v166, v27, 16, 1
	v_add3_u32 v27, v27, v166, v5
	v_lshrrev_b32_e32 v24, 16, v24
	v_lshrrev_b32_e32 v26, 16, v26
	v_and_or_b32 v24, v25, v6, v24
	v_and_or_b32 v25, v27, v6, v26
	global_store_dwordx2 v3, v[24:25], s[16:17] offset:2048
	v_bfe_u32 v166, v28, 16, 1
	v_add3_u32 v28, v28, v166, v5
	v_bfe_u32 v166, v29, 16, 1
	v_add3_u32 v29, v29, v166, v5
	v_bfe_u32 v166, v30, 16, 1
	v_add3_u32 v30, v30, v166, v5
	v_bfe_u32 v166, v31, 16, 1
	v_add3_u32 v31, v31, v166, v5
	v_lshrrev_b32_e32 v28, 16, v28
	v_lshrrev_b32_e32 v30, 16, v30
	v_and_or_b32 v28, v29, v6, v28
	v_and_or_b32 v29, v31, v6, v30
	global_store_dwordx2 v3, v[28:29], s[16:17] offset:2560
	v_bfe_u32 v166, v32, 16, 1
	v_add3_u32 v32, v32, v166, v5
	v_bfe_u32 v166, v33, 16, 1
	v_add3_u32 v33, v33, v166, v5
	v_bfe_u32 v166, v34, 16, 1
	v_add3_u32 v34, v34, v166, v5
	v_bfe_u32 v166, v35, 16, 1
	v_add3_u32 v35, v35, v166, v5
	v_lshrrev_b32_e32 v32, 16, v32
	v_lshrrev_b32_e32 v34, 16, v34
	v_and_or_b32 v32, v33, v6, v32
	v_and_or_b32 v33, v35, v6, v34
	global_store_dwordx2 v3, v[32:33], s[16:17] offset:3072
	v_bfe_u32 v166, v36, 16, 1
	v_add3_u32 v36, v36, v166, v5
	v_bfe_u32 v166, v37, 16, 1
	v_add3_u32 v37, v37, v166, v5
	v_bfe_u32 v166, v38, 16, 1
	v_add3_u32 v38, v38, v166, v5
	v_bfe_u32 v166, v39, 16, 1
	v_add3_u32 v39, v39, v166, v5
	v_lshrrev_b32_e32 v36, 16, v36
	v_lshrrev_b32_e32 v38, 16, v38
	v_and_or_b32 v36, v37, v6, v36
	v_and_or_b32 v37, v39, v6, v38
	global_store_dwordx2 v3, v[36:37], s[16:17] offset:3584
	s_mul_i32 s4, s5, 4
	s_add_u32 s4, s4, s3
	s_lshl_b32 s4, s4, 13
	s_add_u32 s12, s68, s4
	s_addc_u32 s13, s69, 0
	global_load_dwordx4 v[8:11], v1, s[12:13] nt
	global_load_dwordx4 v[12:15], v1, s[12:13] offset:1024 nt
	global_load_dwordx4 v[16:19], v1, s[12:13] offset:2048 nt
	global_load_dwordx4 v[20:23], v1, s[12:13] offset:3072 nt
	global_load_dwordx4 v[24:27], v2, s[12:13] nt
	global_load_dwordx4 v[28:31], v2, s[12:13] offset:1024 nt
	global_load_dwordx4 v[32:35], v2, s[12:13] offset:2048 nt
	global_load_dwordx4 v[36:39], v2, s[12:13] offset:3072 nt
	s_waitcnt vmcnt(40)
	v_mul_f32_e32 v138, v41, v41
	v_mul_f32_e32 v139, v43, v43
	v_fmac_f32_e32 v138, v40, v40
	v_fmac_f32_e32 v139, v42, v42
	v_add_f32_e32 v140, v138, v139
	s_waitcnt vmcnt(39)
	v_mul_f32_e32 v138, v45, v45
	v_mul_f32_e32 v139, v47, v47
	v_fmac_f32_e32 v138, v44, v44
	v_fmac_f32_e32 v139, v46, v46
	v_add_f32_e32 v141, v138, v139
	v_add_f32_e32 v140, v140, v141
	s_waitcnt vmcnt(38)
	v_mul_f32_e32 v138, v49, v49
	v_mul_f32_e32 v139, v51, v51
	v_fmac_f32_e32 v138, v48, v48
	v_fmac_f32_e32 v139, v50, v50
	v_add_f32_e32 v141, v138, v139
	v_add_f32_e32 v140, v140, v141
	s_waitcnt vmcnt(37)
	v_mul_f32_e32 v138, v53, v53
	v_mul_f32_e32 v139, v55, v55
	v_fmac_f32_e32 v138, v52, v52
	v_fmac_f32_e32 v139, v54, v54
	v_add_f32_e32 v141, v138, v139
	v_add_f32_e32 v140, v140, v141
	s_waitcnt vmcnt(36)
; __device__ __forceinline__ unsigned pk2(float lo, float hi) { return f2bf(lo) | (f2bf(hi) << 16); }
; __device__ __forceinline__ void phase_prologue(const Params& p, LAS unsigned char* lds) {
;     ...
;           for (int u = 0; u < UR; ++u) { const int row = row0 + u * NGW; s[u] = 0.f;
; #pragma unroll
;               for (int j = 0; j < 8; ++j) s[u] += (v[u][j][0] * v[u][j][0] + v[u][j][1] * v[u][j][1]) + (v[u][j][2] * v[u][j][2] + v[u][j][3] * v[u][j][3]);
;               s[u] = wave_sum(s[u]); if (lane == 0) rstd[row] = 1.0f / sqrtf(s[u] * (1.0f / DM) + 1e-6f);
;               u32x2* o = (u32x2*)(xb + (size_t)row * DM) + lane;
; #pragma unroll
;               for (int j = 0; j < 8; ++j) { u32x2 w; w.x = pk2(v[u][j][0], v[u][j][1]); w.y = pk2(v[u][j][2], v[u][j][3]); o[64 * j] = w; } } } }
	v_mul_f32_e32 v138, v57, v57
	v_mul_f32_e32 v139, v59, v59
	v_fmac_f32_e32 v138, v56, v56
	v_fmac_f32_e32 v139, v58, v58
	v_add_f32_e32 v141, v138, v139
	v_add_f32_e32 v140, v140, v141
	s_waitcnt vmcnt(35)
	v_mul_f32_e32 v138, v61, v61
	v_mul_f32_e32 v139, v63, v63
	v_fmac_f32_e32 v138, v60, v60
	v_fmac_f32_e32 v139, v62, v62
	v_add_f32_e32 v141, v138, v139
	v_add_f32_e32 v140, v140, v141
	s_waitcnt vmcnt(34)
	v_mul_f32_e32 v138, v65, v65
	v_mul_f32_e32 v139, v67, v67
	v_fmac_f32_e32 v138, v64, v64
	v_fmac_f32_e32 v139, v66, v66
	v_add_f32_e32 v141, v138, v139
	v_add_f32_e32 v140, v140, v141
	s_waitcnt vmcnt(33)
	v_mul_f32_e32 v138, v69, v69
	v_mul_f32_e32 v139, v71, v71
	v_fmac_f32_e32 v138, v68, v68
	v_fmac_f32_e32 v139, v70, v70
	v_add_f32_e32 v141, v138, v139
	v_add_f32_e32 v140, v140, v141
	s_nop 1
	v_add_f32_dpp v140, v140, v140 quad_perm:[1,0,3,2] row_mask:0xf bank_mask:0xf
	s_nop 1
	v_add_f32_dpp v140, v140, v140 quad_perm:[2,3,0,1] row_mask:0xf bank_mask:0xf
	s_nop 1
	v_add_f32_dpp v140, v140, v140 row_half_mirror row_mask:0xf bank_mask:0xf
	s_nop 1
	v_add_f32_dpp v140, v140, v140 row_mirror row_mask:0xf bank_mask:0xf
	s_nop 1
	v_readlane_b32 s38, v140, 0
	v_readlane_b32 s39, v140, 16
	v_readlane_b32 s52, v140, 32
	v_readlane_b32 s53, v140, 48
	s_nop 1
	v_mov_b32_e32 v161, s39
	v_mov_b32_e32 v163, s53
	v_add_f32_e32 v161, s38, v161
	v_add_f32_e32 v163, s52, v163
	v_add_f32_e32 v146, v161, v163
	v_fmamk_f32 v147, v146, 0x3a000000, v136
	v_mul_f32_e32 v148, 0x4f800000, v147
	v_cmp_gt_f32_e32 vcc, v7, v147
	s_nop 1
	v_cndmask_b32_e32 v149, v147, v148, vcc
	v_sqrt_f32_e32 v150, v149
	s_nop 0
	v_add_u32_e32 v151, -1, v150
	v_add_u32_e32 v152, 1, v150
	v_fma_f32 v153, -v151, v150, v149
	v_fma_f32 v154, -v152, v150, v149
	v_cmp_ge_f32_e64 s[0:1], 0, v153
	s_nop 1
	v_cndmask_b32_e64 v155, v150, v151, s[0:1]
	v_cmp_lt_f32_e64 s[0:1], 0, v154
	s_nop 1
	v_cndmask_b32_e64 v155, v155, v152, s[0:1]
	v_mul_f32_e32 v156, 0x37800000, v155
	v_cndmask_b32_e32 v155, v155, v156, vcc
	v_cmp_class_f32_e32 vcc, v149, v137
	s_nop 1
	v_cndmask_b32_e32 v157, v155, v149, vcc
	v_div_scale_f32 v158, s[0:1], v157, v157, 1.0
	v_rcp_f32_e32 v159, v158
	v_div_scale_f32 v160, vcc, 1.0, v157, 1.0
	v_fma_f32 v161, -v158, v159, 1.0
	v_fmac_f32_e32 v159, v161, v159
	v_mul_f32_e32 v162, v160, v159
	v_fma_f32 v163, -v158, v162, v160
	v_fmac_f32_e32 v162, v163, v159
	v_fma_f32 v161, -v158, v162, v160
	v_div_fmas_f32 v164, v161, v159, v162
	v_div_fixup_f32 v165, v164, v157, 1.0
	s_mul_i32 s4, s5, 1
	s_add_u32 s4, s4, s3
	s_lshl_b32 s33, s4, 2
	s_add_u32 s36, s28, s33
	s_addc_u32 s37, s29, 0
	s_add_u32 s36, s36, 0x7c00000
	s_addc_u32 s37, s37, 0
	s_lshl_b32 s33, s4, 12
	s_add_u32 s18, s28, s33
	s_addc_u32 s19, s29, 0
	s_add_u32 s18, s18, 0x8800000
	s_addc_u32 s19, s19, 0
	s_mov_b64 exec, 1
	global_store_dword v4, v165, s[36:37]
	s_mov_b64 exec, -1
	v_bfe_u32 v166, v40, 16, 1
	v_add3_u32 v40, v40, v166, v5
	v_bfe_u32 v166, v41, 16, 1
	v_add3_u32 v41, v41, v166, v5
	v_bfe_u32 v166, v42, 16, 1
	v_add3_u32 v42, v42, v166, v5
	v_bfe_u32 v166, v43, 16, 1
	v_add3_u32 v43, v43, v166, v5
	v_lshrrev_b32_e32 v40, 16, v40
	v_lshrrev_b32_e32 v42, 16, v42
	v_and_or_b32 v40, v41, v6, v40
	v_and_or_b32 v41, v43, v6, v42
	global_store_dwordx2 v3, v[40:41], s[18:19]
	v_bfe_u32 v166, v44, 16, 1
	v_add3_u32 v44, v44, v166, v5
	v_bfe_u32 v166, v45, 16, 1
	v_add3_u32 v45, v45, v166, v5
	v_bfe_u32 v166, v46, 16, 1
	v_add3_u32 v46, v46, v166, v5
	v_bfe_u32 v166, v47, 16, 1
	v_add3_u32 v47, v47, v166, v5
	v_lshrrev_b32_e32 v44, 16, v44
	v_lshrrev_b32_e32 v46, 16, v46
	v_and_or_b32 v44, v45, v6, v44
	v_and_or_b32 v45, v47, v6, v46
	global_store_dwordx2 v3, v[44:45], s[18:19] offset:512
	v_bfe_u32 v166, v48, 16, 1
	v_add3_u32 v48, v48, v166, v5
	v_bfe_u32 v166, v49, 16, 1
	v_add3_u32 v49, v49, v166, v5
	v_bfe_u32 v166, v50, 16, 1
	v_add3_u32 v50, v50, v166, v5
	v_bfe_u32 v166, v51, 16, 1
	v_add3_u32 v51, v51, v166, v5
	v_lshrrev_b32_e32 v48, 16, v48
	v_lshrrev_b32_e32 v50, 16, v50
	v_and_or_b32 v48, v49, v6, v48
	v_and_or_b32 v49, v51, v6, v50
	global_store_dwordx2 v3, v[48:49], s[18:19] offset:1024
	v_bfe_u32 v166, v52, 16, 1
	v_add3_u32 v52, v52, v166, v5
	v_bfe_u32 v166, v53, 16, 1
	v_add3_u32 v53, v53, v166, v5
	v_bfe_u32 v166, v54, 16, 1
	v_add3_u32 v54, v54, v166, v5
	v_bfe_u32 v166, v55, 16, 1
	v_add3_u32 v55, v55, v166, v5
	v_lshrrev_b32_e32 v52, 16, v52
	v_lshrrev_b32_e32 v54, 16, v54
	v_and_or_b32 v52, v53, v6, v52
	v_and_or_b32 v53, v55, v6, v54
	global_store_dwordx2 v3, v[52:53], s[18:19] offset:1536
	v_bfe_u32 v166, v56, 16, 1
	v_add3_u32 v56, v56, v166, v5
	v_bfe_u32 v166, v57, 16, 1
	v_add3_u32 v57, v57, v166, v5
	v_bfe_u32 v166, v58, 16, 1
	v_add3_u32 v58, v58, v166, v5
	v_bfe_u32 v166, v59, 16, 1
	v_add3_u32 v59, v59, v166, v5
	v_lshrrev_b32_e32 v56, 16, v56
	v_lshrrev_b32_e32 v58, 16, v58
	v_and_or_b32 v56, v57, v6, v56
	v_and_or_b32 v57, v59, v6, v58
	global_store_dwordx2 v3, v[56:57], s[18:19] offset:2048
	v_bfe_u32 v166, v60, 16, 1
	v_add3_u32 v60, v60, v166, v5
	v_bfe_u32 v166, v61, 16, 1
	v_add3_u32 v61, v61, v166, v5
	v_bfe_u32 v166, v62, 16, 1
	v_add3_u32 v62, v62, v166, v5
	v_bfe_u32 v166, v63, 16, 1
	v_add3_u32 v63, v63, v166, v5
	v_lshrrev_b32_e32 v60, 16, v60
	v_lshrrev_b32_e32 v62, 16, v62
	v_and_or_b32 v60, v61, v6, v60
	v_and_or_b32 v61, v63, v6, v62
	global_store_dwordx2 v3, v[60:61], s[18:19] offset:2560
	v_bfe_u32 v166, v64, 16, 1
	v_add3_u32 v64, v64, v166, v5
	v_bfe_u32 v166, v65, 16, 1
	v_add3_u32 v65, v65, v166, v5
	v_bfe_u32 v166, v66, 16, 1
	v_add3_u32 v66, v66, v166, v5
	v_bfe_u32 v166, v67, 16, 1
	v_add3_u32 v67, v67, v166, v5
	v_lshrrev_b32_e32 v64, 16, v64
	v_lshrrev_b32_e32 v66, 16, v66
	v_and_or_b32 v64, v65, v6, v64
	v_and_or_b32 v65, v67, v6, v66
	global_store_dwordx2 v3, v[64:65], s[18:19] offset:3072
	v_bfe_u32 v166, v68, 16, 1
	v_add3_u32 v68, v68, v166, v5
	v_bfe_u32 v166, v69, 16, 1
	v_add3_u32 v69, v69, v166, v5
	v_bfe_u32 v166, v70, 16, 1
	v_add3_u32 v70, v70, v166, v5
	v_bfe_u32 v166, v71, 16, 1
	v_add3_u32 v71, v71, v166, v5
	v_lshrrev_b32_e32 v68, 16, v68
	v_lshrrev_b32_e32 v70, 16, v70
	v_and_or_b32 v68, v69, v6, v68
	v_and_or_b32 v69, v71, v6, v70
	global_store_dwordx2 v3, v[68:69], s[18:19] offset:3584
	s_mul_i32 s4, s5, 5
	s_add_u32 s4, s4, s3
	s_lshl_b32 s4, s4, 13
	s_add_u32 s14, s68, s4
	s_addc_u32 s15, s69, 0
	global_load_dwordx4 v[40:43], v1, s[14:15] nt
	global_load_dwordx4 v[44:47], v1, s[14:15] offset:1024 nt
	global_load_dwordx4 v[48:51], v1, s[14:15] offset:2048 nt
	global_load_dwordx4 v[52:55], v1, s[14:15] offset:3072 nt
	global_load_dwordx4 v[56:59], v2, s[14:15] nt
	global_load_dwordx4 v[60:63], v2, s[14:15] offset:1024 nt
	global_load_dwordx4 v[64:67], v2, s[14:15] offset:2048 nt
	global_load_dwordx4 v[68:71], v2, s[14:15] offset:3072 nt
	s_waitcnt vmcnt(49)
; __device__ __forceinline__ unsigned pk2(float lo, float hi) { return f2bf(lo) | (f2bf(hi) << 16); }
; __device__ __forceinline__ void phase_prologue(const Params& p, LAS unsigned char* lds) {
;     ...
;           for (int u = 0; u < UR; ++u) { const int row = row0 + u * NGW; s[u] = 0.f;
; #pragma unroll
;               for (int j = 0; j < 8; ++j) s[u] += (v[u][j][0] * v[u][j][0] + v[u][j][1] * v[u][j][1]) + (v[u][j][2] * v[u][j][2] + v[u][j][3] * v[u][j][3]);
;               s[u] = wave_sum(s[u]); if (lane == 0) rstd[row] = 1.0f / sqrtf(s[u] * (1.0f / DM) + 1e-6f);
;               u32x2* o = (u32x2*)(xb + (size_t)row * DM) + lane;
; #pragma unroll
;               for (int j = 0; j < 8; ++j) { u32x2 w; w.x = pk2(v[u][j][0], v[u][j][1]); w.y = pk2(v[u][j][2], v[u][j][3]); o[64 * j] = w; } } } }
	v_mul_f32_e32 v138, v73, v73
	v_mul_f32_e32 v139, v75, v75
	v_fmac_f32_e32 v138, v72, v72
	v_fmac_f32_e32 v139, v74, v74
	v_add_f32_e32 v140, v138, v139
	s_waitcnt vmcnt(48)
	v_mul_f32_e32 v138, v77, v77
	v_mul_f32_e32 v139, v79, v79
	v_fmac_f32_e32 v138, v76, v76
	v_fmac_f32_e32 v139, v78, v78
	v_add_f32_e32 v141, v138, v139
	v_add_f32_e32 v140, v140, v141
	s_waitcnt vmcnt(47)
	v_mul_f32_e32 v138, v81, v81
	v_mul_f32_e32 v139, v83, v83
	v_fmac_f32_e32 v138, v80, v80
	v_fmac_f32_e32 v139, v82, v82
	v_add_f32_e32 v141, v138, v139
	v_add_f32_e32 v140, v140, v141
	s_waitcnt vmcnt(46)
	v_mul_f32_e32 v138, v85, v85
	v_mul_f32_e32 v139, v87, v87
	v_fmac_f32_e32 v138, v84, v84
	v_fmac_f32_e32 v139, v86, v86
	v_add_f32_e32 v141, v138, v139
	v_add_f32_e32 v140, v140, v141
	s_waitcnt vmcnt(45)
	v_mul_f32_e32 v138, v89, v89
	v_mul_f32_e32 v139, v91, v91
	v_fmac_f32_e32 v138, v88, v88
	v_fmac_f32_e32 v139, v90, v90
	v_add_f32_e32 v141, v138, v139
	v_add_f32_e32 v140, v140, v141
	s_waitcnt vmcnt(44)
	v_mul_f32_e32 v138, v93, v93
	v_mul_f32_e32 v139, v95, v95
	v_fmac_f32_e32 v138, v92, v92
	v_fmac_f32_e32 v139, v94, v94
	v_add_f32_e32 v141, v138, v139
	v_add_f32_e32 v140, v140, v141
	s_waitcnt vmcnt(43)
	v_mul_f32_e32 v138, v97, v97
	v_mul_f32_e32 v139, v99, v99
	v_fmac_f32_e32 v138, v96, v96
	v_fmac_f32_e32 v139, v98, v98
	v_add_f32_e32 v141, v138, v139
	v_add_f32_e32 v140, v140, v141
	s_waitcnt vmcnt(42)
	v_mul_f32_e32 v138, v101, v101
	v_mul_f32_e32 v139, v103, v103
	v_fmac_f32_e32 v138, v100, v100
	v_fmac_f32_e32 v139, v102, v102
	v_add_f32_e32 v141, v138, v139
	v_add_f32_e32 v140, v140, v141
	s_nop 1
	v_add_f32_dpp v140, v140, v140 quad_perm:[1,0,3,2] row_mask:0xf bank_mask:0xf
	s_nop 1
	v_add_f32_dpp v140, v140, v140 quad_perm:[2,3,0,1] row_mask:0xf bank_mask:0xf
	s_nop 1
	v_add_f32_dpp v140, v140, v140 row_half_mirror row_mask:0xf bank_mask:0xf
	s_nop 1
	v_add_f32_dpp v140, v140, v140 row_mirror row_mask:0xf bank_mask:0xf
	s_nop 1
	v_readlane_b32 s38, v140, 0
	v_readlane_b32 s39, v140, 16
	v_readlane_b32 s52, v140, 32
	v_readlane_b32 s53, v140, 48
	s_nop 1
	v_mov_b32_e32 v161, s39
	v_mov_b32_e32 v163, s53
	v_add_f32_e32 v161, s38, v161
	v_add_f32_e32 v163, s52, v163
	v_add_f32_e32 v146, v161, v163
	v_fmamk_f32 v147, v146, 0x3a000000, v136
	v_mul_f32_e32 v148, 0x4f800000, v147
	v_cmp_gt_f32_e32 vcc, v7, v147
	s_nop 1
	v_cndmask_b32_e32 v149, v147, v148, vcc
	v_sqrt_f32_e32 v150, v149
	s_nop 0
	v_add_u32_e32 v151, -1, v150
	v_add_u32_e32 v152, 1, v150
	v_fma_f32 v153, -v151, v150, v149
	v_fma_f32 v154, -v152, v150, v149
	v_cmp_ge_f32_e64 s[0:1], 0, v153
	s_nop 1
	v_cndmask_b32_e64 v155, v150, v151, s[0:1]
	v_cmp_lt_f32_e64 s[0:1], 0, v154
	s_nop 1
	v_cndmask_b32_e64 v155, v155, v152, s[0:1]
	v_mul_f32_e32 v156, 0x37800000, v155
	v_cndmask_b32_e32 v155, v155, v156, vcc
	v_cmp_class_f32_e32 vcc, v149, v137
	s_nop 1
	v_cndmask_b32_e32 v157, v155, v149, vcc
	v_div_scale_f32 v158, s[0:1], v157, v157, 1.0
	v_rcp_f32_e32 v159, v158
	v_div_scale_f32 v160, vcc, 1.0, v157, 1.0
	v_fma_f32 v161, -v158, v159, 1.0
	v_fmac_f32_e32 v159, v161, v159
	v_mul_f32_e32 v162, v160, v159
	v_fma_f32 v163, -v158, v162, v160
	v_fmac_f32_e32 v162, v163, v159
	v_fma_f32 v161, -v158, v162, v160
	v_div_fmas_f32 v164, v161, v159, v162
	v_div_fixup_f32 v165, v164, v157, 1.0
	s_mul_i32 s4, s5, 2
	s_add_u32 s4, s4, s3
	s_lshl_b32 s33, s4, 2
	s_add_u32 s36, s28, s33
	s_addc_u32 s37, s29, 0
	s_add_u32 s36, s36, 0x7c00000
	s_addc_u32 s37, s37, 0
	s_lshl_b32 s33, s4, 12
	s_add_u32 s16, s28, s33
	s_addc_u32 s17, s29, 0
	s_add_u32 s16, s16, 0x8800000
	s_addc_u32 s17, s17, 0
	s_mov_b64 exec, 1
	global_store_dword v4, v165, s[36:37]
	s_mov_b64 exec, -1
	v_bfe_u32 v166, v72, 16, 1
	v_add3_u32 v72, v72, v166, v5
	v_bfe_u32 v166, v73, 16, 1
	v_add3_u32 v73, v73, v166, v5
	v_bfe_u32 v166, v74, 16, 1
	v_add3_u32 v74, v74, v166, v5
	v_bfe_u32 v166, v75, 16, 1
	v_add3_u32 v75, v75, v166, v5
	v_lshrrev_b32_e32 v72, 16, v72
	v_lshrrev_b32_e32 v74, 16, v74
	v_and_or_b32 v72, v73, v6, v72
	v_and_or_b32 v73, v75, v6, v74
	global_store_dwordx2 v3, v[72:73], s[16:17]
	v_bfe_u32 v166, v76, 16, 1
	v_add3_u32 v76, v76, v166, v5
	v_bfe_u32 v166, v77, 16, 1
	v_add3_u32 v77, v77, v166, v5
	v_bfe_u32 v166, v78, 16, 1
	v_add3_u32 v78, v78, v166, v5
	v_bfe_u32 v166, v79, 16, 1
	v_add3_u32 v79, v79, v166, v5
	v_lshrrev_b32_e32 v76, 16, v76
	v_lshrrev_b32_e32 v78, 16, v78
	v_and_or_b32 v76, v77, v6, v76
	v_and_or_b32 v77, v79, v6, v78
	global_store_dwordx2 v3, v[76:77], s[16:17] offset:512
	v_bfe_u32 v166, v80, 16, 1
	v_add3_u32 v80, v80, v166, v5
	v_bfe_u32 v166, v81, 16, 1
	v_add3_u32 v81, v81, v166, v5
	v_bfe_u32 v166, v82, 16, 1
	v_add3_u32 v82, v82, v166, v5
	v_bfe_u32 v166, v83, 16, 1
	v_add3_u32 v83, v83, v166, v5
	v_lshrrev_b32_e32 v80, 16, v80
	v_lshrrev_b32_e32 v82, 16, v82
	v_and_or_b32 v80, v81, v6, v80
	v_and_or_b32 v81, v83, v6, v82
	global_store_dwordx2 v3, v[80:81], s[16:17] offset:1024
	v_bfe_u32 v166, v84, 16, 1
	v_add3_u32 v84, v84, v166, v5
	v_bfe_u32 v166, v85, 16, 1
	v_add3_u32 v85, v85, v166, v5
	v_bfe_u32 v166, v86, 16, 1
	v_add3_u32 v86, v86, v166, v5
	v_bfe_u32 v166, v87, 16, 1
	v_add3_u32 v87, v87, v166, v5
	v_lshrrev_b32_e32 v84, 16, v84
	v_lshrrev_b32_e32 v86, 16, v86
	v_and_or_b32 v84, v85, v6, v84
	v_and_or_b32 v85, v87, v6, v86
	global_store_dwordx2 v3, v[84:85], s[16:17] offset:1536
	v_bfe_u32 v166, v88, 16, 1
	v_add3_u32 v88, v88, v166, v5
	v_bfe_u32 v166, v89, 16, 1
	v_add3_u32 v89, v89, v166, v5
	v_bfe_u32 v166, v90, 16, 1
	v_add3_u32 v90, v90, v166, v5
	v_bfe_u32 v166, v91, 16, 1
	v_add3_u32 v91, v91, v166, v5
	v_lshrrev_b32_e32 v88, 16, v88
	v_lshrrev_b32_e32 v90, 16, v90
; __device__ __forceinline__ unsigned pk2(float lo, float hi) { return f2bf(lo) | (f2bf(hi) << 16); }
; __device__ __forceinline__ void phase_prologue(const Params& p, LAS unsigned char* lds) {
;     ...
;           for (int u = 0; u < UR; ++u) { const int row = row0 + u * NGW; s[u] = 0.f;
; #pragma unroll
;               for (int j = 0; j < 8; ++j) s[u] += (v[u][j][0] * v[u][j][0] + v[u][j][1] * v[u][j][1]) + (v[u][j][2] * v[u][j][2] + v[u][j][3] * v[u][j][3]);
;               s[u] = wave_sum(s[u]); if (lane == 0) rstd[row] = 1.0f / sqrtf(s[u] * (1.0f / DM) + 1e-6f);
;               u32x2* o = (u32x2*)(xb + (size_t)row * DM) + lane;
; #pragma unroll
;               for (int j = 0; j < 8; ++j) { u32x2 w; w.x = pk2(v[u][j][0], v[u][j][1]); w.y = pk2(v[u][j][2], v[u][j][3]); o[64 * j] = w; } } } }
	v_and_or_b32 v88, v89, v6, v88
	v_and_or_b32 v89, v91, v6, v90
	global_store_dwordx2 v3, v[88:89], s[16:17] offset:2048
	v_bfe_u32 v166, v92, 16, 1
	v_add3_u32 v92, v92, v166, v5
	v_bfe_u32 v166, v93, 16, 1
	v_add3_u32 v93, v93, v166, v5
	v_bfe_u32 v166, v94, 16, 1
	v_add3_u32 v94, v94, v166, v5
	v_bfe_u32 v166, v95, 16, 1
	v_add3_u32 v95, v95, v166, v5
	v_lshrrev_b32_e32 v92, 16, v92
	v_lshrrev_b32_e32 v94, 16, v94
	v_and_or_b32 v92, v93, v6, v92
	v_and_or_b32 v93, v95, v6, v94
	global_store_dwordx2 v3, v[92:93], s[16:17] offset:2560
	v_bfe_u32 v166, v96, 16, 1
	v_add3_u32 v96, v96, v166, v5
	v_bfe_u32 v166, v97, 16, 1
	v_add3_u32 v97, v97, v166, v5
	v_bfe_u32 v166, v98, 16, 1
	v_add3_u32 v98, v98, v166, v5
	v_bfe_u32 v166, v99, 16, 1
	v_add3_u32 v99, v99, v166, v5
	v_lshrrev_b32_e32 v96, 16, v96
	v_lshrrev_b32_e32 v98, 16, v98
	v_and_or_b32 v96, v97, v6, v96
	v_and_or_b32 v97, v99, v6, v98
	global_store_dwordx2 v3, v[96:97], s[16:17] offset:3072
	v_bfe_u32 v166, v100, 16, 1
	v_add3_u32 v100, v100, v166, v5
	v_bfe_u32 v166, v101, 16, 1
	v_add3_u32 v101, v101, v166, v5
	v_bfe_u32 v166, v102, 16, 1
	v_add3_u32 v102, v102, v166, v5
	v_bfe_u32 v166, v103, 16, 1
	v_add3_u32 v103, v103, v166, v5
	v_lshrrev_b32_e32 v100, 16, v100
	v_lshrrev_b32_e32 v102, 16, v102
	v_and_or_b32 v100, v101, v6, v100
	v_and_or_b32 v101, v103, v6, v102
	global_store_dwordx2 v3, v[100:101], s[16:17] offset:3584
	s_mul_i32 s4, s5, 6
	s_add_u32 s4, s4, s3
	s_lshl_b32 s4, s4, 13
	s_add_u32 s12, s68, s4
	s_addc_u32 s13, s69, 0
	global_load_dwordx4 v[72:75], v1, s[12:13] nt
	global_load_dwordx4 v[76:79], v1, s[12:13] offset:1024 nt
	global_load_dwordx4 v[80:83], v1, s[12:13] offset:2048 nt
	global_load_dwordx4 v[84:87], v1, s[12:13] offset:3072 nt
	global_load_dwordx4 v[88:91], v2, s[12:13] nt
	global_load_dwordx4 v[92:95], v2, s[12:13] offset:1024 nt
	global_load_dwordx4 v[96:99], v2, s[12:13] offset:2048 nt
	global_load_dwordx4 v[100:103], v2, s[12:13] offset:3072 nt
	s_waitcnt vmcnt(58)
	v_mul_f32_e32 v138, v105, v105
	v_mul_f32_e32 v139, v107, v107
	v_fmac_f32_e32 v138, v104, v104
	v_fmac_f32_e32 v139, v106, v106
	v_add_f32_e32 v140, v138, v139
	s_waitcnt vmcnt(57)
	v_mul_f32_e32 v138, v109, v109
	v_mul_f32_e32 v139, v111, v111
	v_fmac_f32_e32 v138, v108, v108
	v_fmac_f32_e32 v139, v110, v110
	v_add_f32_e32 v141, v138, v139
	v_add_f32_e32 v140, v140, v141
	s_waitcnt vmcnt(56)
	v_mul_f32_e32 v138, v113, v113
	v_mul_f32_e32 v139, v115, v115
	v_fmac_f32_e32 v138, v112, v112
	v_fmac_f32_e32 v139, v114, v114
	v_add_f32_e32 v141, v138, v139
	v_add_f32_e32 v140, v140, v141
	s_waitcnt vmcnt(55)
	v_mul_f32_e32 v138, v117, v117
	v_mul_f32_e32 v139, v119, v119
	v_fmac_f32_e32 v138, v116, v116
	v_fmac_f32_e32 v139, v118, v118
	v_add_f32_e32 v141, v138, v139
	v_add_f32_e32 v140, v140, v141
	s_waitcnt vmcnt(54)
	v_mul_f32_e32 v138, v121, v121
	v_mul_f32_e32 v139, v123, v123
	v_fmac_f32_e32 v138, v120, v120
	v_fmac_f32_e32 v139, v122, v122
	v_add_f32_e32 v141, v138, v139
	v_add_f32_e32 v140, v140, v141
	s_waitcnt vmcnt(53)
	v_mul_f32_e32 v138, v125, v125
	v_mul_f32_e32 v139, v127, v127
	v_fmac_f32_e32 v138, v124, v124
	v_fmac_f32_e32 v139, v126, v126
	v_add_f32_e32 v141, v138, v139
	v_add_f32_e32 v140, v140, v141
	s_waitcnt vmcnt(52)
	v_mul_f32_e32 v138, v129, v129
	v_mul_f32_e32 v139, v131, v131
	v_fmac_f32_e32 v138, v128, v128
	v_fmac_f32_e32 v139, v130, v130
	v_add_f32_e32 v141, v138, v139
	v_add_f32_e32 v140, v140, v141
	s_waitcnt vmcnt(51)
	v_mul_f32_e32 v138, v133, v133
	v_mul_f32_e32 v139, v135, v135
	v_fmac_f32_e32 v138, v132, v132
	v_fmac_f32_e32 v139, v134, v134
	v_add_f32_e32 v141, v138, v139
	v_add_f32_e32 v140, v140, v141
	s_nop 1
	v_add_f32_dpp v140, v140, v140 quad_perm:[1,0,3,2] row_mask:0xf bank_mask:0xf
	s_nop 1
	v_add_f32_dpp v140, v140, v140 quad_perm:[2,3,0,1] row_mask:0xf bank_mask:0xf
	s_nop 1
	v_add_f32_dpp v140, v140, v140 row_half_mirror row_mask:0xf bank_mask:0xf
	s_nop 1
	v_add_f32_dpp v140, v140, v140 row_mirror row_mask:0xf bank_mask:0xf
	s_nop 1
	v_readlane_b32 s38, v140, 0
	v_readlane_b32 s39, v140, 16
	v_readlane_b32 s52, v140, 32
	v_readlane_b32 s53, v140, 48
	s_nop 1
	v_mov_b32_e32 v161, s39
	v_mov_b32_e32 v163, s53
	v_add_f32_e32 v161, s38, v161
	v_add_f32_e32 v163, s52, v163
	v_add_f32_e32 v146, v161, v163
	v_fmamk_f32 v147, v146, 0x3a000000, v136
	v_mul_f32_e32 v148, 0x4f800000, v147
	v_cmp_gt_f32_e32 vcc, v7, v147
	s_nop 1
	v_cndmask_b32_e32 v149, v147, v148, vcc
	v_sqrt_f32_e32 v150, v149
	s_nop 0
	v_add_u32_e32 v151, -1, v150
	v_add_u32_e32 v152, 1, v150
	v_fma_f32 v153, -v151, v150, v149
	v_fma_f32 v154, -v152, v150, v149
	v_cmp_ge_f32_e64 s[0:1], 0, v153
	s_nop 1
	v_cndmask_b32_e64 v155, v150, v151, s[0:1]
	v_cmp_lt_f32_e64 s[0:1], 0, v154
	s_nop 1
	v_cndmask_b32_e64 v155, v155, v152, s[0:1]
	v_mul_f32_e32 v156, 0x37800000, v155
	v_cndmask_b32_e32 v155, v155, v156, vcc
	v_cmp_class_f32_e32 vcc, v149, v137
	s_nop 1
	v_cndmask_b32_e32 v157, v155, v149, vcc
	v_div_scale_f32 v158, s[0:1], v157, v157, 1.0
	v_rcp_f32_e32 v159, v158
	v_div_scale_f32 v160, vcc, 1.0, v157, 1.0
	v_fma_f32 v161, -v158, v159, 1.0
	v_fmac_f32_e32 v159, v161, v159
	v_mul_f32_e32 v162, v160, v159
	v_fma_f32 v163, -v158, v162, v160
	v_fmac_f32_e32 v162, v163, v159
	v_fma_f32 v161, -v158, v162, v160
	v_div_fmas_f32 v164, v161, v159, v162
	v_div_fixup_f32 v165, v164, v157, 1.0
	s_mul_i32 s4, s5, 3
	s_add_u32 s4, s4, s3
	s_lshl_b32 s33, s4, 2
	s_add_u32 s36, s28, s33
	s_addc_u32 s37, s29, 0
	s_add_u32 s36, s36, 0x7c00000
	s_addc_u32 s37, s37, 0
	s_lshl_b32 s33, s4, 12
	s_add_u32 s18, s28, s33
	s_addc_u32 s19, s29, 0
	s_add_u32 s18, s18, 0x8800000
	s_addc_u32 s19, s19, 0
; __device__ __forceinline__ unsigned pk2(float lo, float hi) { return f2bf(lo) | (f2bf(hi) << 16); }
; __device__ __forceinline__ void phase_prologue(const Params& p, LAS unsigned char* lds) {
;     ...
;           for (int u = 0; u < UR; ++u) { const int row = row0 + u * NGW; s[u] = 0.f;
; #pragma unroll
;               for (int j = 0; j < 8; ++j) s[u] += (v[u][j][0] * v[u][j][0] + v[u][j][1] * v[u][j][1]) + (v[u][j][2] * v[u][j][2] + v[u][j][3] * v[u][j][3]);
;               s[u] = wave_sum(s[u]); if (lane == 0) rstd[row] = 1.0f / sqrtf(s[u] * (1.0f / DM) + 1e-6f);
;               u32x2* o = (u32x2*)(xb + (size_t)row * DM) + lane;
; #pragma unroll
;               for (int j = 0; j < 8; ++j) { u32x2 w; w.x = pk2(v[u][j][0], v[u][j][1]); w.y = pk2(v[u][j][2], v[u][j][3]); o[64 * j] = w; } } } }
	s_mov_b64 exec, 1
	global_store_dword v4, v165, s[36:37]
	s_mov_b64 exec, -1
	v_bfe_u32 v166, v104, 16, 1
	v_add3_u32 v104, v104, v166, v5
	v_bfe_u32 v166, v105, 16, 1
	v_add3_u32 v105, v105, v166, v5
	v_bfe_u32 v166, v106, 16, 1
	v_add3_u32 v106, v106, v166, v5
	v_bfe_u32 v166, v107, 16, 1
	v_add3_u32 v107, v107, v166, v5
	v_lshrrev_b32_e32 v104, 16, v104
	v_lshrrev_b32_e32 v106, 16, v106
	v_and_or_b32 v104, v105, v6, v104
	v_and_or_b32 v105, v107, v6, v106
	global_store_dwordx2 v3, v[104:105], s[18:19]
	v_bfe_u32 v166, v108, 16, 1
	v_add3_u32 v108, v108, v166, v5
	v_bfe_u32 v166, v109, 16, 1
	v_add3_u32 v109, v109, v166, v5
	v_bfe_u32 v166, v110, 16, 1
	v_add3_u32 v110, v110, v166, v5
	v_bfe_u32 v166, v111, 16, 1
	v_add3_u32 v111, v111, v166, v5
	v_lshrrev_b32_e32 v108, 16, v108
	v_lshrrev_b32_e32 v110, 16, v110
	v_and_or_b32 v108, v109, v6, v108
	v_and_or_b32 v109, v111, v6, v110
	global_store_dwordx2 v3, v[108:109], s[18:19] offset:512
	v_bfe_u32 v166, v112, 16, 1
	v_add3_u32 v112, v112, v166, v5
	v_bfe_u32 v166, v113, 16, 1
	v_add3_u32 v113, v113, v166, v5
	v_bfe_u32 v166, v114, 16, 1
	v_add3_u32 v114, v114, v166, v5
	v_bfe_u32 v166, v115, 16, 1
	v_add3_u32 v115, v115, v166, v5
	v_lshrrev_b32_e32 v112, 16, v112
	v_lshrrev_b32_e32 v114, 16, v114
	v_and_or_b32 v112, v113, v6, v112
	v_and_or_b32 v113, v115, v6, v114
	global_store_dwordx2 v3, v[112:113], s[18:19] offset:1024
	v_bfe_u32 v166, v116, 16, 1
	v_add3_u32 v116, v116, v166, v5
	v_bfe_u32 v166, v117, 16, 1
	v_add3_u32 v117, v117, v166, v5
	v_bfe_u32 v166, v118, 16, 1
	v_add3_u32 v118, v118, v166, v5
	v_bfe_u32 v166, v119, 16, 1
	v_add3_u32 v119, v119, v166, v5
	v_lshrrev_b32_e32 v116, 16, v116
	v_lshrrev_b32_e32 v118, 16, v118
	v_and_or_b32 v116, v117, v6, v116
	v_and_or_b32 v117, v119, v6, v118
	global_store_dwordx2 v3, v[116:117], s[18:19] offset:1536
	v_bfe_u32 v166, v120, 16, 1
	v_add3_u32 v120, v120, v166, v5
	v_bfe_u32 v166, v121, 16, 1
	v_add3_u32 v121, v121, v166, v5
	v_bfe_u32 v166, v122, 16, 1
	v_add3_u32 v122, v122, v166, v5
	v_bfe_u32 v166, v123, 16, 1
	v_add3_u32 v123, v123, v166, v5
	v_lshrrev_b32_e32 v120, 16, v120
	v_lshrrev_b32_e32 v122, 16, v122
	v_and_or_b32 v120, v121, v6, v120
	v_and_or_b32 v121, v123, v6, v122
	global_store_dwordx2 v3, v[120:121], s[18:19] offset:2048
	v_bfe_u32 v166, v124, 16, 1
	v_add3_u32 v124, v124, v166, v5
	v_bfe_u32 v166, v125, 16, 1
	v_add3_u32 v125, v125, v166, v5
	v_bfe_u32 v166, v126, 16, 1
	v_add3_u32 v126, v126, v166, v5
	v_bfe_u32 v166, v127, 16, 1
	v_add3_u32 v127, v127, v166, v5
	v_lshrrev_b32_e32 v124, 16, v124
	v_lshrrev_b32_e32 v126, 16, v126
	v_and_or_b32 v124, v125, v6, v124
	v_and_or_b32 v125, v127, v6, v126
	global_store_dwordx2 v3, v[124:125], s[18:19] offset:2560
	v_bfe_u32 v166, v128, 16, 1
	v_add3_u32 v128, v128, v166, v5
	v_bfe_u32 v166, v129, 16, 1
	v_add3_u32 v129, v129, v166, v5
	v_bfe_u32 v166, v130, 16, 1
	v_add3_u32 v130, v130, v166, v5
	v_bfe_u32 v166, v131, 16, 1
	v_add3_u32 v131, v131, v166, v5
	v_lshrrev_b32_e32 v128, 16, v128
	v_lshrrev_b32_e32 v130, 16, v130
	v_and_or_b32 v128, v129, v6, v128
	v_and_or_b32 v129, v131, v6, v130
	global_store_dwordx2 v3, v[128:129], s[18:19] offset:3072
	v_bfe_u32 v166, v132, 16, 1
	v_add3_u32 v132, v132, v166, v5
	v_bfe_u32 v166, v133, 16, 1
	v_add3_u32 v133, v133, v166, v5
	v_bfe_u32 v166, v134, 16, 1
	v_add3_u32 v134, v134, v166, v5
	v_bfe_u32 v166, v135, 16, 1
	v_add3_u32 v135, v135, v166, v5
	v_lshrrev_b32_e32 v132, 16, v132
	v_lshrrev_b32_e32 v134, 16, v134
	v_and_or_b32 v132, v133, v6, v132
	v_and_or_b32 v133, v135, v6, v134
	global_store_dwordx2 v3, v[132:133], s[18:19] offset:3584
	s_mul_i32 s4, s5, 7
	s_add_u32 s4, s4, s3
	s_lshl_b32 s4, s4, 13
	s_add_u32 s14, s68, s4
	s_addc_u32 s15, s69, 0
	s_waitcnt vmcnt(52)
	global_load_dwordx4 v[104:107], v1, s[14:15] nt
	global_load_dwordx4 v[108:111], v1, s[14:15] offset:1024 nt
	global_load_dwordx4 v[112:115], v1, s[14:15] offset:2048 nt
	global_load_dwordx4 v[116:119], v1, s[14:15] offset:3072 nt
	global_load_dwordx4 v[120:123], v2, s[14:15] nt
	global_load_dwordx4 v[124:127], v2, s[14:15] offset:1024 nt
	global_load_dwordx4 v[128:131], v2, s[14:15] offset:2048 nt
	global_load_dwordx4 v[132:135], v2, s[14:15] offset:3072 nt
	s_waitcnt vmcnt(58)
	v_mul_f32_e32 v138, v9, v9
	v_mul_f32_e32 v139, v11, v11
	v_fmac_f32_e32 v138, v8, v8
	v_fmac_f32_e32 v139, v10, v10
	v_add_f32_e32 v140, v138, v139
	s_waitcnt vmcnt(57)
	v_mul_f32_e32 v138, v13, v13
	v_mul_f32_e32 v139, v15, v15
	v_fmac_f32_e32 v138, v12, v12
	v_fmac_f32_e32 v139, v14, v14
	v_add_f32_e32 v141, v138, v139
	v_add_f32_e32 v140, v140, v141
	s_waitcnt vmcnt(56)
	v_mul_f32_e32 v138, v17, v17
	v_mul_f32_e32 v139, v19, v19
	v_fmac_f32_e32 v138, v16, v16
	v_fmac_f32_e32 v139, v18, v18
	v_add_f32_e32 v141, v138, v139
	v_add_f32_e32 v140, v140, v141
	s_waitcnt vmcnt(55)
	v_mul_f32_e32 v138, v21, v21
	v_mul_f32_e32 v139, v23, v23
	v_fmac_f32_e32 v138, v20, v20
	v_fmac_f32_e32 v139, v22, v22
	v_add_f32_e32 v141, v138, v139
	v_add_f32_e32 v140, v140, v141
	s_waitcnt vmcnt(54)
	v_mul_f32_e32 v138, v25, v25
	v_mul_f32_e32 v139, v27, v27
	v_fmac_f32_e32 v138, v24, v24
	v_fmac_f32_e32 v139, v26, v26
	v_add_f32_e32 v141, v138, v139
	v_add_f32_e32 v140, v140, v141
	s_waitcnt vmcnt(53)
	v_mul_f32_e32 v138, v29, v29
	v_mul_f32_e32 v139, v31, v31
	v_fmac_f32_e32 v138, v28, v28
	v_fmac_f32_e32 v139, v30, v30
	v_add_f32_e32 v141, v138, v139
	v_add_f32_e32 v140, v140, v141
	s_waitcnt vmcnt(52)
	v_mul_f32_e32 v138, v33, v33
	v_mul_f32_e32 v139, v35, v35
	v_fmac_f32_e32 v138, v32, v32
	v_fmac_f32_e32 v139, v34, v34
	v_add_f32_e32 v141, v138, v139
	v_add_f32_e32 v140, v140, v141
	s_waitcnt vmcnt(51)
; __device__ __forceinline__ unsigned pk2(float lo, float hi) { return f2bf(lo) | (f2bf(hi) << 16); }
; __device__ __forceinline__ void phase_prologue(const Params& p, LAS unsigned char* lds) {
;     ...
;           for (int u = 0; u < UR; ++u) { const int row = row0 + u * NGW; s[u] = 0.f;
; #pragma unroll
;               for (int j = 0; j < 8; ++j) s[u] += (v[u][j][0] * v[u][j][0] + v[u][j][1] * v[u][j][1]) + (v[u][j][2] * v[u][j][2] + v[u][j][3] * v[u][j][3]);
;               s[u] = wave_sum(s[u]); if (lane == 0) rstd[row] = 1.0f / sqrtf(s[u] * (1.0f / DM) + 1e-6f);
;               u32x2* o = (u32x2*)(xb + (size_t)row * DM) + lane;
; #pragma unroll
;               for (int j = 0; j < 8; ++j) { u32x2 w; w.x = pk2(v[u][j][0], v[u][j][1]); w.y = pk2(v[u][j][2], v[u][j][3]); o[64 * j] = w; } } } }
	v_mul_f32_e32 v138, v37, v37
	v_mul_f32_e32 v139, v39, v39
	v_fmac_f32_e32 v138, v36, v36
	v_fmac_f32_e32 v139, v38, v38
	v_add_f32_e32 v141, v138, v139
	v_add_f32_e32 v140, v140, v141
	s_nop 1
	v_add_f32_dpp v140, v140, v140 quad_perm:[1,0,3,2] row_mask:0xf bank_mask:0xf
	s_nop 1
	v_add_f32_dpp v140, v140, v140 quad_perm:[2,3,0,1] row_mask:0xf bank_mask:0xf
	s_nop 1
	v_add_f32_dpp v140, v140, v140 row_half_mirror row_mask:0xf bank_mask:0xf
	s_nop 1
	v_add_f32_dpp v140, v140, v140 row_mirror row_mask:0xf bank_mask:0xf
	s_nop 1
	v_readlane_b32 s38, v140, 0
	v_readlane_b32 s39, v140, 16
	v_readlane_b32 s52, v140, 32
	v_readlane_b32 s53, v140, 48
	s_nop 1
	v_mov_b32_e32 v161, s39
	v_mov_b32_e32 v163, s53
	v_add_f32_e32 v161, s38, v161
	v_add_f32_e32 v163, s52, v163
	v_add_f32_e32 v146, v161, v163
	v_fmamk_f32 v147, v146, 0x3a000000, v136
	v_mul_f32_e32 v148, 0x4f800000, v147
	v_cmp_gt_f32_e32 vcc, v7, v147
	s_nop 1
	v_cndmask_b32_e32 v149, v147, v148, vcc
	v_sqrt_f32_e32 v150, v149
	s_nop 0
	v_add_u32_e32 v151, -1, v150
	v_add_u32_e32 v152, 1, v150
	v_fma_f32 v153, -v151, v150, v149
	v_fma_f32 v154, -v152, v150, v149
	v_cmp_ge_f32_e64 s[0:1], 0, v153
	s_nop 1
	v_cndmask_b32_e64 v155, v150, v151, s[0:1]
	v_cmp_lt_f32_e64 s[0:1], 0, v154
	s_nop 1
	v_cndmask_b32_e64 v155, v155, v152, s[0:1]
	v_mul_f32_e32 v156, 0x37800000, v155
	v_cndmask_b32_e32 v155, v155, v156, vcc
	v_cmp_class_f32_e32 vcc, v149, v137
	s_nop 1
	v_cndmask_b32_e32 v157, v155, v149, vcc
	v_div_scale_f32 v158, s[0:1], v157, v157, 1.0
	v_rcp_f32_e32 v159, v158
	v_div_scale_f32 v160, vcc, 1.0, v157, 1.0
	v_fma_f32 v161, -v158, v159, 1.0
	v_fmac_f32_e32 v159, v161, v159
	v_mul_f32_e32 v162, v160, v159
	v_fma_f32 v163, -v158, v162, v160
	v_fmac_f32_e32 v162, v163, v159
	v_fma_f32 v161, -v158, v162, v160
	v_div_fmas_f32 v164, v161, v159, v162
	v_div_fixup_f32 v165, v164, v157, 1.0
	s_mul_i32 s4, s5, 4
	s_add_u32 s4, s4, s3
	s_lshl_b32 s33, s4, 2
	s_add_u32 s36, s28, s33
	s_addc_u32 s37, s29, 0
	s_add_u32 s36, s36, 0x7c00000
	s_addc_u32 s37, s37, 0
	s_lshl_b32 s33, s4, 12
	s_add_u32 s16, s28, s33
	s_addc_u32 s17, s29, 0
	s_add_u32 s16, s16, 0x8800000
	s_addc_u32 s17, s17, 0
	s_mov_b64 exec, 1
	global_store_dword v4, v165, s[36:37]
	s_mov_b64 exec, -1
	v_bfe_u32 v166, v8, 16, 1
	v_add3_u32 v8, v8, v166, v5
	v_bfe_u32 v166, v9, 16, 1
	v_add3_u32 v9, v9, v166, v5
	v_bfe_u32 v166, v10, 16, 1
	v_add3_u32 v10, v10, v166, v5
	v_bfe_u32 v166, v11, 16, 1
	v_add3_u32 v11, v11, v166, v5
	v_lshrrev_b32_e32 v8, 16, v8
	v_lshrrev_b32_e32 v10, 16, v10
	v_and_or_b32 v8, v9, v6, v8
	v_and_or_b32 v9, v11, v6, v10
	global_store_dwordx2 v3, v[8:9], s[16:17]
	v_bfe_u32 v166, v12, 16, 1
	v_add3_u32 v12, v12, v166, v5
	v_bfe_u32 v166, v13, 16, 1
	v_add3_u32 v13, v13, v166, v5
	v_bfe_u32 v166, v14, 16, 1
	v_add3_u32 v14, v14, v166, v5
	v_bfe_u32 v166, v15, 16, 1
	v_add3_u32 v15, v15, v166, v5
	v_lshrrev_b32_e32 v12, 16, v12
	v_lshrrev_b32_e32 v14, 16, v14
	v_and_or_b32 v12, v13, v6, v12
	v_and_or_b32 v13, v15, v6, v14
	global_store_dwordx2 v3, v[12:13], s[16:17] offset:512
	v_bfe_u32 v166, v16, 16, 1
	v_add3_u32 v16, v16, v166, v5
	v_bfe_u32 v166, v17, 16, 1
	v_add3_u32 v17, v17, v166, v5
	v_bfe_u32 v166, v18, 16, 1
	v_add3_u32 v18, v18, v166, v5
	v_bfe_u32 v166, v19, 16, 1
	v_add3_u32 v19, v19, v166, v5
	v_lshrrev_b32_e32 v16, 16, v16
	v_lshrrev_b32_e32 v18, 16, v18
	v_and_or_b32 v16, v17, v6, v16
	v_and_or_b32 v17, v19, v6, v18
	global_store_dwordx2 v3, v[16:17], s[16:17] offset:1024
	v_bfe_u32 v166, v20, 16, 1
	v_add3_u32 v20, v20, v166, v5
	v_bfe_u32 v166, v21, 16, 1
	v_add3_u32 v21, v21, v166, v5
	v_bfe_u32 v166, v22, 16, 1
	v_add3_u32 v22, v22, v166, v5
	v_bfe_u32 v166, v23, 16, 1
	v_add3_u32 v23, v23, v166, v5
	v_lshrrev_b32_e32 v20, 16, v20
	v_lshrrev_b32_e32 v22, 16, v22
	v_and_or_b32 v20, v21, v6, v20
	v_and_or_b32 v21, v23, v6, v22
	global_store_dwordx2 v3, v[20:21], s[16:17] offset:1536
	v_bfe_u32 v166, v24, 16, 1
	v_add3_u32 v24, v24, v166, v5
	v_bfe_u32 v166, v25, 16, 1
	v_add3_u32 v25, v25, v166, v5
	v_bfe_u32 v166, v26, 16, 1
	v_add3_u32 v26, v26, v166, v5
	v_bfe_u32 v166, v27, 16, 1
	v_add3_u32 v27, v27, v166, v5
	v_lshrrev_b32_e32 v24, 16, v24
	v_lshrrev_b32_e32 v26, 16, v26
	v_and_or_b32 v24, v25, v6, v24
	v_and_or_b32 v25, v27, v6, v26
	global_store_dwordx2 v3, v[24:25], s[16:17] offset:2048
	v_bfe_u32 v166, v28, 16, 1
	v_add3_u32 v28, v28, v166, v5
	v_bfe_u32 v166, v29, 16, 1
	v_add3_u32 v29, v29, v166, v5
	v_bfe_u32 v166, v30, 16, 1
	v_add3_u32 v30, v30, v166, v5
	v_bfe_u32 v166, v31, 16, 1
	v_add3_u32 v31, v31, v166, v5
	v_lshrrev_b32_e32 v28, 16, v28
	v_lshrrev_b32_e32 v30, 16, v30
	v_and_or_b32 v28, v29, v6, v28
	v_and_or_b32 v29, v31, v6, v30
	global_store_dwordx2 v3, v[28:29], s[16:17] offset:2560
	v_bfe_u32 v166, v32, 16, 1
	v_add3_u32 v32, v32, v166, v5
	v_bfe_u32 v166, v33, 16, 1
	v_add3_u32 v33, v33, v166, v5
	v_bfe_u32 v166, v34, 16, 1
	v_add3_u32 v34, v34, v166, v5
	v_bfe_u32 v166, v35, 16, 1
	v_add3_u32 v35, v35, v166, v5
	v_lshrrev_b32_e32 v32, 16, v32
	v_lshrrev_b32_e32 v34, 16, v34
	v_and_or_b32 v32, v33, v6, v32
	v_and_or_b32 v33, v35, v6, v34
	global_store_dwordx2 v3, v[32:33], s[16:17] offset:3072
	v_bfe_u32 v166, v36, 16, 1
	v_add3_u32 v36, v36, v166, v5
	v_bfe_u32 v166, v37, 16, 1
	v_add3_u32 v37, v37, v166, v5
	v_bfe_u32 v166, v38, 16, 1
	v_add3_u32 v38, v38, v166, v5
	v_bfe_u32 v166, v39, 16, 1
	v_add3_u32 v39, v39, v166, v5
	v_lshrrev_b32_e32 v36, 16, v36
	v_lshrrev_b32_e32 v38, 16, v38
	v_and_or_b32 v36, v37, v6, v36
	v_and_or_b32 v37, v39, v6, v38
	global_store_dwordx2 v3, v[36:37], s[16:17] offset:3584
	s_mul_i32 s4, s5, 8
	s_add_u32 s4, s4, s3
	s_lshl_b32 s4, s4, 13
	s_add_u32 s12, s68, s4
	s_addc_u32 s13, s69, 0
	s_waitcnt vmcnt(52)
; __device__ __forceinline__ unsigned pk2(float lo, float hi) { return f2bf(lo) | (f2bf(hi) << 16); }
; __device__ __forceinline__ void phase_prologue(const Params& p, LAS unsigned char* lds) {
;     ...
;           for (int u = 0; u < UR; ++u) { const int row = row0 + u * NGW; s[u] = 0.f;
; #pragma unroll
;               for (int j = 0; j < 8; ++j) s[u] += (v[u][j][0] * v[u][j][0] + v[u][j][1] * v[u][j][1]) + (v[u][j][2] * v[u][j][2] + v[u][j][3] * v[u][j][3]);
;               s[u] = wave_sum(s[u]); if (lane == 0) rstd[row] = 1.0f / sqrtf(s[u] * (1.0f / DM) + 1e-6f);
;               u32x2* o = (u32x2*)(xb + (size_t)row * DM) + lane;
; #pragma unroll
;               for (int j = 0; j < 8; ++j) { u32x2 w; w.x = pk2(v[u][j][0], v[u][j][1]); w.y = pk2(v[u][j][2], v[u][j][3]); o[64 * j] = w; } } } }
	global_load_dwordx4 v[8:11], v1, s[12:13] nt
	global_load_dwordx4 v[12:15], v1, s[12:13] offset:1024 nt
	global_load_dwordx4 v[16:19], v1, s[12:13] offset:2048 nt
	global_load_dwordx4 v[20:23], v1, s[12:13] offset:3072 nt
	global_load_dwordx4 v[24:27], v2, s[12:13] nt
	global_load_dwordx4 v[28:31], v2, s[12:13] offset:1024 nt
	global_load_dwordx4 v[32:35], v2, s[12:13] offset:2048 nt
	global_load_dwordx4 v[36:39], v2, s[12:13] offset:3072 nt
	s_waitcnt vmcnt(58)
	v_mul_f32_e32 v138, v41, v41
	v_mul_f32_e32 v139, v43, v43
	v_fmac_f32_e32 v138, v40, v40
	v_fmac_f32_e32 v139, v42, v42
	v_add_f32_e32 v140, v138, v139
	s_waitcnt vmcnt(57)
	v_mul_f32_e32 v138, v45, v45
	v_mul_f32_e32 v139, v47, v47
	v_fmac_f32_e32 v138, v44, v44
	v_fmac_f32_e32 v139, v46, v46
	v_add_f32_e32 v141, v138, v139
	v_add_f32_e32 v140, v140, v141
	s_waitcnt vmcnt(56)
	v_mul_f32_e32 v138, v49, v49
	v_mul_f32_e32 v139, v51, v51
	v_fmac_f32_e32 v138, v48, v48
	v_fmac_f32_e32 v139, v50, v50
	v_add_f32_e32 v141, v138, v139
	v_add_f32_e32 v140, v140, v141
	s_waitcnt vmcnt(55)
	v_mul_f32_e32 v138, v53, v53
	v_mul_f32_e32 v139, v55, v55
	v_fmac_f32_e32 v138, v52, v52
	v_fmac_f32_e32 v139, v54, v54
	v_add_f32_e32 v141, v138, v139
	v_add_f32_e32 v140, v140, v141
	s_waitcnt vmcnt(54)
	v_mul_f32_e32 v138, v57, v57
	v_mul_f32_e32 v139, v59, v59
	v_fmac_f32_e32 v138, v56, v56
	v_fmac_f32_e32 v139, v58, v58
	v_add_f32_e32 v141, v138, v139
	v_add_f32_e32 v140, v140, v141
	s_waitcnt vmcnt(53)
	v_mul_f32_e32 v138, v61, v61
	v_mul_f32_e32 v139, v63, v63
	v_fmac_f32_e32 v138, v60, v60
	v_fmac_f32_e32 v139, v62, v62
	v_add_f32_e32 v141, v138, v139
	v_add_f32_e32 v140, v140, v141
	s_waitcnt vmcnt(52)
	v_mul_f32_e32 v138, v65, v65
	v_mul_f32_e32 v139, v67, v67
	v_fmac_f32_e32 v138, v64, v64
	v_fmac_f32_e32 v139, v66, v66
	v_add_f32_e32 v141, v138, v139
	v_add_f32_e32 v140, v140, v141
	s_waitcnt vmcnt(51)
	v_mul_f32_e32 v138, v69, v69
	v_mul_f32_e32 v139, v71, v71
	v_fmac_f32_e32 v138, v68, v68
	v_fmac_f32_e32 v139, v70, v70
	v_add_f32_e32 v141, v138, v139
	v_add_f32_e32 v140, v140, v141
	s_nop 1
	v_add_f32_dpp v140, v140, v140 quad_perm:[1,0,3,2] row_mask:0xf bank_mask:0xf
	s_nop 1
	v_add_f32_dpp v140, v140, v140 quad_perm:[2,3,0,1] row_mask:0xf bank_mask:0xf
	s_nop 1
	v_add_f32_dpp v140, v140, v140 row_half_mirror row_mask:0xf bank_mask:0xf
	s_nop 1
	v_add_f32_dpp v140, v140, v140 row_mirror row_mask:0xf bank_mask:0xf
	s_nop 1
	v_readlane_b32 s38, v140, 0
	v_readlane_b32 s39, v140, 16
	v_readlane_b32 s52, v140, 32
	v_readlane_b32 s53, v140, 48
	s_nop 1
	v_mov_b32_e32 v161, s39
	v_mov_b32_e32 v163, s53
	v_add_f32_e32 v161, s38, v161
	v_add_f32_e32 v163, s52, v163
	v_add_f32_e32 v146, v161, v163
	v_fmamk_f32 v147, v146, 0x3a000000, v136
	v_mul_f32_e32 v148, 0x4f800000, v147
	v_cmp_gt_f32_e32 vcc, v7, v147
	s_nop 1
	v_cndmask_b32_e32 v149, v147, v148, vcc
	v_sqrt_f32_e32 v150, v149
	s_nop 0
	v_add_u32_e32 v151, -1, v150
	v_add_u32_e32 v152, 1, v150
	v_fma_f32 v153, -v151, v150, v149
	v_fma_f32 v154, -v152, v150, v149
	v_cmp_ge_f32_e64 s[0:1], 0, v153
	s_nop 1
	v_cndmask_b32_e64 v155, v150, v151, s[0:1]
	v_cmp_lt_f32_e64 s[0:1], 0, v154
	s_nop 1
	v_cndmask_b32_e64 v155, v155, v152, s[0:1]
	v_mul_f32_e32 v156, 0x37800000, v155
	v_cndmask_b32_e32 v155, v155, v156, vcc
	v_cmp_class_f32_e32 vcc, v149, v137
	s_nop 1
	v_cndmask_b32_e32 v157, v155, v149, vcc
	v_div_scale_f32 v158, s[0:1], v157, v157, 1.0
	v_rcp_f32_e32 v159, v158
	v_div_scale_f32 v160, vcc, 1.0, v157, 1.0
	v_fma_f32 v161, -v158, v159, 1.0
	v_fmac_f32_e32 v159, v161, v159
	v_mul_f32_e32 v162, v160, v159
	v_fma_f32 v163, -v158, v162, v160
	v_fmac_f32_e32 v162, v163, v159
	v_fma_f32 v161, -v158, v162, v160
	v_div_fmas_f32 v164, v161, v159, v162
	v_div_fixup_f32 v165, v164, v157, 1.0
	s_mul_i32 s4, s5, 5
	s_add_u32 s4, s4, s3
	s_lshl_b32 s33, s4, 2
	s_add_u32 s36, s28, s33
	s_addc_u32 s37, s29, 0
	s_add_u32 s36, s36, 0x7c00000
	s_addc_u32 s37, s37, 0
	s_lshl_b32 s33, s4, 12
	s_add_u32 s18, s28, s33
	s_addc_u32 s19, s29, 0
	s_add_u32 s18, s18, 0x8800000
	s_addc_u32 s19, s19, 0
	s_mov_b64 exec, 1
	global_store_dword v4, v165, s[36:37]
	s_mov_b64 exec, -1
	v_bfe_u32 v166, v40, 16, 1
	v_add3_u32 v40, v40, v166, v5
	v_bfe_u32 v166, v41, 16, 1
	v_add3_u32 v41, v41, v166, v5
	v_bfe_u32 v166, v42, 16, 1
	v_add3_u32 v42, v42, v166, v5
	v_bfe_u32 v166, v43, 16, 1
	v_add3_u32 v43, v43, v166, v5
	v_lshrrev_b32_e32 v40, 16, v40
	v_lshrrev_b32_e32 v42, 16, v42
	v_and_or_b32 v40, v41, v6, v40
	v_and_or_b32 v41, v43, v6, v42
	global_store_dwordx2 v3, v[40:41], s[18:19]
	v_bfe_u32 v166, v44, 16, 1
	v_add3_u32 v44, v44, v166, v5
	v_bfe_u32 v166, v45, 16, 1
	v_add3_u32 v45, v45, v166, v5
	v_bfe_u32 v166, v46, 16, 1
	v_add3_u32 v46, v46, v166, v5
	v_bfe_u32 v166, v47, 16, 1
	v_add3_u32 v47, v47, v166, v5
	v_lshrrev_b32_e32 v44, 16, v44
	v_lshrrev_b32_e32 v46, 16, v46
	v_and_or_b32 v44, v45, v6, v44
	v_and_or_b32 v45, v47, v6, v46
	global_store_dwordx2 v3, v[44:45], s[18:19] offset:512
	v_bfe_u32 v166, v48, 16, 1
	v_add3_u32 v48, v48, v166, v5
	v_bfe_u32 v166, v49, 16, 1
	v_add3_u32 v49, v49, v166, v5
	v_bfe_u32 v166, v50, 16, 1
	v_add3_u32 v50, v50, v166, v5
	v_bfe_u32 v166, v51, 16, 1
	v_add3_u32 v51, v51, v166, v5
	v_lshrrev_b32_e32 v48, 16, v48
	v_lshrrev_b32_e32 v50, 16, v50
	v_and_or_b32 v48, v49, v6, v48
	v_and_or_b32 v49, v51, v6, v50
	global_store_dwordx2 v3, v[48:49], s[18:19] offset:1024
	v_bfe_u32 v166, v52, 16, 1
	v_add3_u32 v52, v52, v166, v5
	v_bfe_u32 v166, v53, 16, 1
	v_add3_u32 v53, v53, v166, v5
	v_bfe_u32 v166, v54, 16, 1
	v_add3_u32 v54, v54, v166, v5
	v_bfe_u32 v166, v55, 16, 1
	v_add3_u32 v55, v55, v166, v5
	v_lshrrev_b32_e32 v52, 16, v52
; __device__ __forceinline__ unsigned pk2(float lo, float hi) { return f2bf(lo) | (f2bf(hi) << 16); }
; __device__ __forceinline__ void phase_prologue(const Params& p, LAS unsigned char* lds) {
;     ...
;           for (int u = 0; u < UR; ++u) { const int row = row0 + u * NGW; s[u] = 0.f;
; #pragma unroll
;               for (int j = 0; j < 8; ++j) s[u] += (v[u][j][0] * v[u][j][0] + v[u][j][1] * v[u][j][1]) + (v[u][j][2] * v[u][j][2] + v[u][j][3] * v[u][j][3]);
;               s[u] = wave_sum(s[u]); if (lane == 0) rstd[row] = 1.0f / sqrtf(s[u] * (1.0f / DM) + 1e-6f);
;               u32x2* o = (u32x2*)(xb + (size_t)row * DM) + lane;
; #pragma unroll
;               for (int j = 0; j < 8; ++j) { u32x2 w; w.x = pk2(v[u][j][0], v[u][j][1]); w.y = pk2(v[u][j][2], v[u][j][3]); o[64 * j] = w; } } } }
	v_lshrrev_b32_e32 v54, 16, v54
	v_and_or_b32 v52, v53, v6, v52
	v_and_or_b32 v53, v55, v6, v54
	global_store_dwordx2 v3, v[52:53], s[18:19] offset:1536
	v_bfe_u32 v166, v56, 16, 1
	v_add3_u32 v56, v56, v166, v5
	v_bfe_u32 v166, v57, 16, 1
	v_add3_u32 v57, v57, v166, v5
	v_bfe_u32 v166, v58, 16, 1
	v_add3_u32 v58, v58, v166, v5
	v_bfe_u32 v166, v59, 16, 1
	v_add3_u32 v59, v59, v166, v5
	v_lshrrev_b32_e32 v56, 16, v56
	v_lshrrev_b32_e32 v58, 16, v58
	v_and_or_b32 v56, v57, v6, v56
	v_and_or_b32 v57, v59, v6, v58
	global_store_dwordx2 v3, v[56:57], s[18:19] offset:2048
	v_bfe_u32 v166, v60, 16, 1
	v_add3_u32 v60, v60, v166, v5
	v_bfe_u32 v166, v61, 16, 1
	v_add3_u32 v61, v61, v166, v5
	v_bfe_u32 v166, v62, 16, 1
	v_add3_u32 v62, v62, v166, v5
	v_bfe_u32 v166, v63, 16, 1
	v_add3_u32 v63, v63, v166, v5
	v_lshrrev_b32_e32 v60, 16, v60
	v_lshrrev_b32_e32 v62, 16, v62
	v_and_or_b32 v60, v61, v6, v60
	v_and_or_b32 v61, v63, v6, v62
	global_store_dwordx2 v3, v[60:61], s[18:19] offset:2560
	v_bfe_u32 v166, v64, 16, 1
	v_add3_u32 v64, v64, v166, v5
	v_bfe_u32 v166, v65, 16, 1
	v_add3_u32 v65, v65, v166, v5
	v_bfe_u32 v166, v66, 16, 1
	v_add3_u32 v66, v66, v166, v5
	v_bfe_u32 v166, v67, 16, 1
	v_add3_u32 v67, v67, v166, v5
	v_lshrrev_b32_e32 v64, 16, v64
	v_lshrrev_b32_e32 v66, 16, v66
	v_and_or_b32 v64, v65, v6, v64
	v_and_or_b32 v65, v67, v6, v66
	global_store_dwordx2 v3, v[64:65], s[18:19] offset:3072
	v_bfe_u32 v166, v68, 16, 1
	v_add3_u32 v68, v68, v166, v5
	v_bfe_u32 v166, v69, 16, 1
	v_add3_u32 v69, v69, v166, v5
	v_bfe_u32 v166, v70, 16, 1
	v_add3_u32 v70, v70, v166, v5
	v_bfe_u32 v166, v71, 16, 1
	v_add3_u32 v71, v71, v166, v5
	v_lshrrev_b32_e32 v68, 16, v68
	v_lshrrev_b32_e32 v70, 16, v70
	v_and_or_b32 v68, v69, v6, v68
	v_and_or_b32 v69, v71, v6, v70
	global_store_dwordx2 v3, v[68:69], s[18:19] offset:3584
	s_mul_i32 s4, s5, 9
	s_add_u32 s4, s4, s3
	s_lshl_b32 s4, s4, 13
	s_add_u32 s14, s68, s4
	s_addc_u32 s15, s69, 0
	s_waitcnt vmcnt(52)
	global_load_dwordx4 v[40:43], v1, s[14:15] nt
	global_load_dwordx4 v[44:47], v1, s[14:15] offset:1024 nt
	global_load_dwordx4 v[48:51], v1, s[14:15] offset:2048 nt
	global_load_dwordx4 v[52:55], v1, s[14:15] offset:3072 nt
	global_load_dwordx4 v[56:59], v2, s[14:15] nt
	global_load_dwordx4 v[60:63], v2, s[14:15] offset:1024 nt
	global_load_dwordx4 v[64:67], v2, s[14:15] offset:2048 nt
	global_load_dwordx4 v[68:71], v2, s[14:15] offset:3072 nt
	s_waitcnt vmcnt(58)
	v_mul_f32_e32 v138, v73, v73
	v_mul_f32_e32 v139, v75, v75
	v_fmac_f32_e32 v138, v72, v72
	v_fmac_f32_e32 v139, v74, v74
	v_add_f32_e32 v140, v138, v139
	s_waitcnt vmcnt(57)
	v_mul_f32_e32 v138, v77, v77
	v_mul_f32_e32 v139, v79, v79
	v_fmac_f32_e32 v138, v76, v76
	v_fmac_f32_e32 v139, v78, v78
	v_add_f32_e32 v141, v138, v139
	v_add_f32_e32 v140, v140, v141
	s_waitcnt vmcnt(56)
	v_mul_f32_e32 v138, v81, v81
	v_mul_f32_e32 v139, v83, v83
	v_fmac_f32_e32 v138, v80, v80
	v_fmac_f32_e32 v139, v82, v82
	v_add_f32_e32 v141, v138, v139
	v_add_f32_e32 v140, v140, v141
	s_waitcnt vmcnt(55)
	v_mul_f32_e32 v138, v85, v85
	v_mul_f32_e32 v139, v87, v87
	v_fmac_f32_e32 v138, v84, v84
	v_fmac_f32_e32 v139, v86, v86
	v_add_f32_e32 v141, v138, v139
	v_add_f32_e32 v140, v140, v141
	s_waitcnt vmcnt(54)
	v_mul_f32_e32 v138, v89, v89
	v_mul_f32_e32 v139, v91, v91
	v_fmac_f32_e32 v138, v88, v88
	v_fmac_f32_e32 v139, v90, v90
	v_add_f32_e32 v141, v138, v139
	v_add_f32_e32 v140, v140, v141
	s_waitcnt vmcnt(53)
	v_mul_f32_e32 v138, v93, v93
	v_mul_f32_e32 v139, v95, v95
	v_fmac_f32_e32 v138, v92, v92
	v_fmac_f32_e32 v139, v94, v94
	v_add_f32_e32 v141, v138, v139
	v_add_f32_e32 v140, v140, v141
	s_waitcnt vmcnt(52)
	v_mul_f32_e32 v138, v97, v97
	v_mul_f32_e32 v139, v99, v99
	v_fmac_f32_e32 v138, v96, v96
	v_fmac_f32_e32 v139, v98, v98
	v_add_f32_e32 v141, v138, v139
	v_add_f32_e32 v140, v140, v141
	s_waitcnt vmcnt(51)
	v_mul_f32_e32 v138, v101, v101
	v_mul_f32_e32 v139, v103, v103
	v_fmac_f32_e32 v138, v100, v100
	v_fmac_f32_e32 v139, v102, v102
	v_add_f32_e32 v141, v138, v139
	v_add_f32_e32 v140, v140, v141
	s_nop 1
	v_add_f32_dpp v140, v140, v140 quad_perm:[1,0,3,2] row_mask:0xf bank_mask:0xf
	s_nop 1
	v_add_f32_dpp v140, v140, v140 quad_perm:[2,3,0,1] row_mask:0xf bank_mask:0xf
	s_nop 1
	v_add_f32_dpp v140, v140, v140 row_half_mirror row_mask:0xf bank_mask:0xf
	s_nop 1
	v_add_f32_dpp v140, v140, v140 row_mirror row_mask:0xf bank_mask:0xf
	s_nop 1
	v_readlane_b32 s38, v140, 0
	v_readlane_b32 s39, v140, 16
	v_readlane_b32 s52, v140, 32
	v_readlane_b32 s53, v140, 48
	s_nop 1
	v_mov_b32_e32 v161, s39
	v_mov_b32_e32 v163, s53
	v_add_f32_e32 v161, s38, v161
	v_add_f32_e32 v163, s52, v163
	v_add_f32_e32 v146, v161, v163
	v_fmamk_f32 v147, v146, 0x3a000000, v136
	v_mul_f32_e32 v148, 0x4f800000, v147
	v_cmp_gt_f32_e32 vcc, v7, v147
	s_nop 1
	v_cndmask_b32_e32 v149, v147, v148, vcc
	v_sqrt_f32_e32 v150, v149
	s_nop 0
	v_add_u32_e32 v151, -1, v150
	v_add_u32_e32 v152, 1, v150
	v_fma_f32 v153, -v151, v150, v149
	v_fma_f32 v154, -v152, v150, v149
	v_cmp_ge_f32_e64 s[0:1], 0, v153
	s_nop 1
	v_cndmask_b32_e64 v155, v150, v151, s[0:1]
	v_cmp_lt_f32_e64 s[0:1], 0, v154
	s_nop 1
	v_cndmask_b32_e64 v155, v155, v152, s[0:1]
	v_mul_f32_e32 v156, 0x37800000, v155
	v_cndmask_b32_e32 v155, v155, v156, vcc
	v_cmp_class_f32_e32 vcc, v149, v137
	s_nop 1
	v_cndmask_b32_e32 v157, v155, v149, vcc
	v_div_scale_f32 v158, s[0:1], v157, v157, 1.0
	v_rcp_f32_e32 v159, v158
	v_div_scale_f32 v160, vcc, 1.0, v157, 1.0
	v_fma_f32 v161, -v158, v159, 1.0
	v_fmac_f32_e32 v159, v161, v159
	v_mul_f32_e32 v162, v160, v159
	v_fma_f32 v163, -v158, v162, v160
	v_fmac_f32_e32 v162, v163, v159
	v_fma_f32 v161, -v158, v162, v160
; __device__ __forceinline__ unsigned pk2(float lo, float hi) { return f2bf(lo) | (f2bf(hi) << 16); }
; __device__ __forceinline__ void phase_prologue(const Params& p, LAS unsigned char* lds) {
;     ...
;           for (int u = 0; u < UR; ++u) { const int row = row0 + u * NGW; s[u] = 0.f;
; #pragma unroll
;               for (int j = 0; j < 8; ++j) s[u] += (v[u][j][0] * v[u][j][0] + v[u][j][1] * v[u][j][1]) + (v[u][j][2] * v[u][j][2] + v[u][j][3] * v[u][j][3]);
;               s[u] = wave_sum(s[u]); if (lane == 0) rstd[row] = 1.0f / sqrtf(s[u] * (1.0f / DM) + 1e-6f);
;               u32x2* o = (u32x2*)(xb + (size_t)row * DM) + lane;
; #pragma unroll
;               for (int j = 0; j < 8; ++j) { u32x2 w; w.x = pk2(v[u][j][0], v[u][j][1]); w.y = pk2(v[u][j][2], v[u][j][3]); o[64 * j] = w; } } } }
	v_div_fmas_f32 v164, v161, v159, v162
	v_div_fixup_f32 v165, v164, v157, 1.0
	s_mul_i32 s4, s5, 6
	s_add_u32 s4, s4, s3
	s_lshl_b32 s33, s4, 2
	s_add_u32 s36, s28, s33
	s_addc_u32 s37, s29, 0
	s_add_u32 s36, s36, 0x7c00000
	s_addc_u32 s37, s37, 0
	s_lshl_b32 s33, s4, 12
	s_add_u32 s16, s28, s33
	s_addc_u32 s17, s29, 0
	s_add_u32 s16, s16, 0x8800000
	s_addc_u32 s17, s17, 0
	s_mov_b64 exec, 1
	global_store_dword v4, v165, s[36:37]
	s_mov_b64 exec, -1
	v_bfe_u32 v166, v72, 16, 1
	v_add3_u32 v72, v72, v166, v5
	v_bfe_u32 v166, v73, 16, 1
	v_add3_u32 v73, v73, v166, v5
	v_bfe_u32 v166, v74, 16, 1
	v_add3_u32 v74, v74, v166, v5
	v_bfe_u32 v166, v75, 16, 1
	v_add3_u32 v75, v75, v166, v5
	v_lshrrev_b32_e32 v72, 16, v72
	v_lshrrev_b32_e32 v74, 16, v74
	v_and_or_b32 v72, v73, v6, v72
	v_and_or_b32 v73, v75, v6, v74
	global_store_dwordx2 v3, v[72:73], s[16:17]
	v_bfe_u32 v166, v76, 16, 1
	v_add3_u32 v76, v76, v166, v5
	v_bfe_u32 v166, v77, 16, 1
	v_add3_u32 v77, v77, v166, v5
	v_bfe_u32 v166, v78, 16, 1
	v_add3_u32 v78, v78, v166, v5
	v_bfe_u32 v166, v79, 16, 1
	v_add3_u32 v79, v79, v166, v5
	v_lshrrev_b32_e32 v76, 16, v76
	v_lshrrev_b32_e32 v78, 16, v78
	v_and_or_b32 v76, v77, v6, v76
	v_and_or_b32 v77, v79, v6, v78
	global_store_dwordx2 v3, v[76:77], s[16:17] offset:512
	v_bfe_u32 v166, v80, 16, 1
	v_add3_u32 v80, v80, v166, v5
	v_bfe_u32 v166, v81, 16, 1
	v_add3_u32 v81, v81, v166, v5
	v_bfe_u32 v166, v82, 16, 1
	v_add3_u32 v82, v82, v166, v5
	v_bfe_u32 v166, v83, 16, 1
	v_add3_u32 v83, v83, v166, v5
	v_lshrrev_b32_e32 v80, 16, v80
	v_lshrrev_b32_e32 v82, 16, v82
	v_and_or_b32 v80, v81, v6, v80
	v_and_or_b32 v81, v83, v6, v82
	global_store_dwordx2 v3, v[80:81], s[16:17] offset:1024
	v_bfe_u32 v166, v84, 16, 1
	v_add3_u32 v84, v84, v166, v5
	v_bfe_u32 v166, v85, 16, 1
	v_add3_u32 v85, v85, v166, v5
	v_bfe_u32 v166, v86, 16, 1
	v_add3_u32 v86, v86, v166, v5
	v_bfe_u32 v166, v87, 16, 1
	v_add3_u32 v87, v87, v166, v5
	v_lshrrev_b32_e32 v84, 16, v84
	v_lshrrev_b32_e32 v86, 16, v86
	v_and_or_b32 v84, v85, v6, v84
	v_and_or_b32 v85, v87, v6, v86
	global_store_dwordx2 v3, v[84:85], s[16:17] offset:1536
	v_bfe_u32 v166, v88, 16, 1
	v_add3_u32 v88, v88, v166, v5
	v_bfe_u32 v166, v89, 16, 1
	v_add3_u32 v89, v89, v166, v5
	v_bfe_u32 v166, v90, 16, 1
	v_add3_u32 v90, v90, v166, v5
	v_bfe_u32 v166, v91, 16, 1
	v_add3_u32 v91, v91, v166, v5
	v_lshrrev_b32_e32 v88, 16, v88
	v_lshrrev_b32_e32 v90, 16, v90
	v_and_or_b32 v88, v89, v6, v88
	v_and_or_b32 v89, v91, v6, v90
	global_store_dwordx2 v3, v[88:89], s[16:17] offset:2048
	v_bfe_u32 v166, v92, 16, 1
	v_add3_u32 v92, v92, v166, v5
	v_bfe_u32 v166, v93, 16, 1
	v_add3_u32 v93, v93, v166, v5
	v_bfe_u32 v166, v94, 16, 1
	v_add3_u32 v94, v94, v166, v5
	v_bfe_u32 v166, v95, 16, 1
	v_add3_u32 v95, v95, v166, v5
	v_lshrrev_b32_e32 v92, 16, v92
	v_lshrrev_b32_e32 v94, 16, v94
	v_and_or_b32 v92, v93, v6, v92
	v_and_or_b32 v93, v95, v6, v94
	global_store_dwordx2 v3, v[92:93], s[16:17] offset:2560
	v_bfe_u32 v166, v96, 16, 1
	v_add3_u32 v96, v96, v166, v5
	v_bfe_u32 v166, v97, 16, 1
	v_add3_u32 v97, v97, v166, v5
	v_bfe_u32 v166, v98, 16, 1
	v_add3_u32 v98, v98, v166, v5
	v_bfe_u32 v166, v99, 16, 1
	v_add3_u32 v99, v99, v166, v5
	v_lshrrev_b32_e32 v96, 16, v96
	v_lshrrev_b32_e32 v98, 16, v98
	v_and_or_b32 v96, v97, v6, v96
	v_and_or_b32 v97, v99, v6, v98
	global_store_dwordx2 v3, v[96:97], s[16:17] offset:3072
	v_bfe_u32 v166, v100, 16, 1
	v_add3_u32 v100, v100, v166, v5
	v_bfe_u32 v166, v101, 16, 1
	v_add3_u32 v101, v101, v166, v5
	v_bfe_u32 v166, v102, 16, 1
	v_add3_u32 v102, v102, v166, v5
	v_bfe_u32 v166, v103, 16, 1
	v_add3_u32 v103, v103, v166, v5
	v_lshrrev_b32_e32 v100, 16, v100
	v_lshrrev_b32_e32 v102, 16, v102
	v_and_or_b32 v100, v101, v6, v100
	v_and_or_b32 v101, v103, v6, v102
	global_store_dwordx2 v3, v[100:101], s[16:17] offset:3584
	s_mul_i32 s4, s5, 10
	s_add_u32 s4, s4, s3
	s_lshl_b32 s4, s4, 13
	s_add_u32 s12, s68, s4
	s_addc_u32 s13, s69, 0
	s_waitcnt vmcnt(52)
	global_load_dwordx4 v[72:75], v1, s[12:13] nt
	global_load_dwordx4 v[76:79], v1, s[12:13] offset:1024 nt
	global_load_dwordx4 v[80:83], v1, s[12:13] offset:2048 nt
	global_load_dwordx4 v[84:87], v1, s[12:13] offset:3072 nt
	global_load_dwordx4 v[88:91], v2, s[12:13] nt
	global_load_dwordx4 v[92:95], v2, s[12:13] offset:1024 nt
	global_load_dwordx4 v[96:99], v2, s[12:13] offset:2048 nt
	global_load_dwordx4 v[100:103], v2, s[12:13] offset:3072 nt
	s_waitcnt vmcnt(58)
	v_mul_f32_e32 v138, v105, v105
	v_mul_f32_e32 v139, v107, v107
	v_fmac_f32_e32 v138, v104, v104
	v_fmac_f32_e32 v139, v106, v106
	v_add_f32_e32 v140, v138, v139
	s_waitcnt vmcnt(57)
	v_mul_f32_e32 v138, v109, v109
	v_mul_f32_e32 v139, v111, v111
	v_fmac_f32_e32 v138, v108, v108
	v_fmac_f32_e32 v139, v110, v110
	v_add_f32_e32 v141, v138, v139
	v_add_f32_e32 v140, v140, v141
	s_waitcnt vmcnt(56)
	v_mul_f32_e32 v138, v113, v113
	v_mul_f32_e32 v139, v115, v115
	v_fmac_f32_e32 v138, v112, v112
	v_fmac_f32_e32 v139, v114, v114
	v_add_f32_e32 v141, v138, v139
	v_add_f32_e32 v140, v140, v141
	s_waitcnt vmcnt(55)
	v_mul_f32_e32 v138, v117, v117
	v_mul_f32_e32 v139, v119, v119
	v_fmac_f32_e32 v138, v116, v116
	v_fmac_f32_e32 v139, v118, v118
	v_add_f32_e32 v141, v138, v139
	v_add_f32_e32 v140, v140, v141
	s_waitcnt vmcnt(54)
	v_mul_f32_e32 v138, v121, v121
	v_mul_f32_e32 v139, v123, v123
	v_fmac_f32_e32 v138, v120, v120
	v_fmac_f32_e32 v139, v122, v122
	v_add_f32_e32 v141, v138, v139
	v_add_f32_e32 v140, v140, v141
	s_waitcnt vmcnt(53)
	v_mul_f32_e32 v138, v125, v125
	v_mul_f32_e32 v139, v127, v127
	v_fmac_f32_e32 v138, v124, v124
	v_fmac_f32_e32 v139, v126, v126
	v_add_f32_e32 v141, v138, v139
	v_add_f32_e32 v140, v140, v141
	s_waitcnt vmcnt(52)
; __device__ __forceinline__ unsigned pk2(float lo, float hi) { return f2bf(lo) | (f2bf(hi) << 16); }
; __device__ __forceinline__ void phase_prologue(const Params& p, LAS unsigned char* lds) {
;     ...
;           for (int u = 0; u < UR; ++u) { const int row = row0 + u * NGW; s[u] = 0.f;
; #pragma unroll
;               for (int j = 0; j < 8; ++j) s[u] += (v[u][j][0] * v[u][j][0] + v[u][j][1] * v[u][j][1]) + (v[u][j][2] * v[u][j][2] + v[u][j][3] * v[u][j][3]);
;               s[u] = wave_sum(s[u]); if (lane == 0) rstd[row] = 1.0f / sqrtf(s[u] * (1.0f / DM) + 1e-6f);
;               u32x2* o = (u32x2*)(xb + (size_t)row * DM) + lane;
; #pragma unroll
;               for (int j = 0; j < 8; ++j) { u32x2 w; w.x = pk2(v[u][j][0], v[u][j][1]); w.y = pk2(v[u][j][2], v[u][j][3]); o[64 * j] = w; } } } }
	v_mul_f32_e32 v138, v129, v129
	v_mul_f32_e32 v139, v131, v131
	v_fmac_f32_e32 v138, v128, v128
	v_fmac_f32_e32 v139, v130, v130
	v_add_f32_e32 v141, v138, v139
	v_add_f32_e32 v140, v140, v141
	s_waitcnt vmcnt(51)
	v_mul_f32_e32 v138, v133, v133
	v_mul_f32_e32 v139, v135, v135
	v_fmac_f32_e32 v138, v132, v132
	v_fmac_f32_e32 v139, v134, v134
	v_add_f32_e32 v141, v138, v139
	v_add_f32_e32 v140, v140, v141
	s_nop 1
	v_add_f32_dpp v140, v140, v140 quad_perm:[1,0,3,2] row_mask:0xf bank_mask:0xf
	s_nop 1
	v_add_f32_dpp v140, v140, v140 quad_perm:[2,3,0,1] row_mask:0xf bank_mask:0xf
	s_nop 1
	v_add_f32_dpp v140, v140, v140 row_half_mirror row_mask:0xf bank_mask:0xf
	s_nop 1
	v_add_f32_dpp v140, v140, v140 row_mirror row_mask:0xf bank_mask:0xf
	s_nop 1
	v_readlane_b32 s38, v140, 0
	v_readlane_b32 s39, v140, 16
	v_readlane_b32 s52, v140, 32
	v_readlane_b32 s53, v140, 48
	s_nop 1
	v_mov_b32_e32 v161, s39
	v_mov_b32_e32 v163, s53
	v_add_f32_e32 v161, s38, v161
	v_add_f32_e32 v163, s52, v163
	v_add_f32_e32 v146, v161, v163
	v_fmamk_f32 v147, v146, 0x3a000000, v136
	v_mul_f32_e32 v148, 0x4f800000, v147
	v_cmp_gt_f32_e32 vcc, v7, v147
	s_nop 1
	v_cndmask_b32_e32 v149, v147, v148, vcc
	v_sqrt_f32_e32 v150, v149
	s_nop 0
	v_add_u32_e32 v151, -1, v150
	v_add_u32_e32 v152, 1, v150
	v_fma_f32 v153, -v151, v150, v149
	v_fma_f32 v154, -v152, v150, v149
	v_cmp_ge_f32_e64 s[0:1], 0, v153
	s_nop 1
	v_cndmask_b32_e64 v155, v150, v151, s[0:1]
	v_cmp_lt_f32_e64 s[0:1], 0, v154
	s_nop 1
	v_cndmask_b32_e64 v155, v155, v152, s[0:1]
	v_mul_f32_e32 v156, 0x37800000, v155
	v_cndmask_b32_e32 v155, v155, v156, vcc
	v_cmp_class_f32_e32 vcc, v149, v137
	s_nop 1
	v_cndmask_b32_e32 v157, v155, v149, vcc
	v_div_scale_f32 v158, s[0:1], v157, v157, 1.0
	v_rcp_f32_e32 v159, v158
	v_div_scale_f32 v160, vcc, 1.0, v157, 1.0
	v_fma_f32 v161, -v158, v159, 1.0
	v_fmac_f32_e32 v159, v161, v159
	v_mul_f32_e32 v162, v160, v159
	v_fma_f32 v163, -v158, v162, v160
	v_fmac_f32_e32 v162, v163, v159
	v_fma_f32 v161, -v158, v162, v160
	v_div_fmas_f32 v164, v161, v159, v162
	v_div_fixup_f32 v165, v164, v157, 1.0
	s_mul_i32 s4, s5, 7
	s_add_u32 s4, s4, s3
	s_lshl_b32 s33, s4, 2
	s_add_u32 s36, s28, s33
	s_addc_u32 s37, s29, 0
	s_add_u32 s36, s36, 0x7c00000
	s_addc_u32 s37, s37, 0
	s_lshl_b32 s33, s4, 12
	s_add_u32 s18, s28, s33
	s_addc_u32 s19, s29, 0
	s_add_u32 s18, s18, 0x8800000
	s_addc_u32 s19, s19, 0
	s_mov_b64 exec, 1
	global_store_dword v4, v165, s[36:37]
	s_mov_b64 exec, -1
	v_bfe_u32 v166, v104, 16, 1
	v_add3_u32 v104, v104, v166, v5
	v_bfe_u32 v166, v105, 16, 1
	v_add3_u32 v105, v105, v166, v5
	v_bfe_u32 v166, v106, 16, 1
	v_add3_u32 v106, v106, v166, v5
	v_bfe_u32 v166, v107, 16, 1
	v_add3_u32 v107, v107, v166, v5
	v_lshrrev_b32_e32 v104, 16, v104
	v_lshrrev_b32_e32 v106, 16, v106
	v_and_or_b32 v104, v105, v6, v104
	v_and_or_b32 v105, v107, v6, v106
	global_store_dwordx2 v3, v[104:105], s[18:19]
	v_bfe_u32 v166, v108, 16, 1
	v_add3_u32 v108, v108, v166, v5
	v_bfe_u32 v166, v109, 16, 1
	v_add3_u32 v109, v109, v166, v5
	v_bfe_u32 v166, v110, 16, 1
	v_add3_u32 v110, v110, v166, v5
	v_bfe_u32 v166, v111, 16, 1
	v_add3_u32 v111, v111, v166, v5
	v_lshrrev_b32_e32 v108, 16, v108
	v_lshrrev_b32_e32 v110, 16, v110
	v_and_or_b32 v108, v109, v6, v108
	v_and_or_b32 v109, v111, v6, v110
	global_store_dwordx2 v3, v[108:109], s[18:19] offset:512
	v_bfe_u32 v166, v112, 16, 1
	v_add3_u32 v112, v112, v166, v5
	v_bfe_u32 v166, v113, 16, 1
	v_add3_u32 v113, v113, v166, v5
	v_bfe_u32 v166, v114, 16, 1
	v_add3_u32 v114, v114, v166, v5
	v_bfe_u32 v166, v115, 16, 1
	v_add3_u32 v115, v115, v166, v5
	v_lshrrev_b32_e32 v112, 16, v112
	v_lshrrev_b32_e32 v114, 16, v114
	v_and_or_b32 v112, v113, v6, v112
	v_and_or_b32 v113, v115, v6, v114
	global_store_dwordx2 v3, v[112:113], s[18:19] offset:1024
	v_bfe_u32 v166, v116, 16, 1
	v_add3_u32 v116, v116, v166, v5
	v_bfe_u32 v166, v117, 16, 1
	v_add3_u32 v117, v117, v166, v5
	v_bfe_u32 v166, v118, 16, 1
	v_add3_u32 v118, v118, v166, v5
	v_bfe_u32 v166, v119, 16, 1
	v_add3_u32 v119, v119, v166, v5
	v_lshrrev_b32_e32 v116, 16, v116
	v_lshrrev_b32_e32 v118, 16, v118
	v_and_or_b32 v116, v117, v6, v116
	v_and_or_b32 v117, v119, v6, v118
	global_store_dwordx2 v3, v[116:117], s[18:19] offset:1536
	v_bfe_u32 v166, v120, 16, 1
	v_add3_u32 v120, v120, v166, v5
	v_bfe_u32 v166, v121, 16, 1
	v_add3_u32 v121, v121, v166, v5
	v_bfe_u32 v166, v122, 16, 1
	v_add3_u32 v122, v122, v166, v5
	v_bfe_u32 v166, v123, 16, 1
	v_add3_u32 v123, v123, v166, v5
	v_lshrrev_b32_e32 v120, 16, v120
	v_lshrrev_b32_e32 v122, 16, v122
	v_and_or_b32 v120, v121, v6, v120
	v_and_or_b32 v121, v123, v6, v122
	global_store_dwordx2 v3, v[120:121], s[18:19] offset:2048
	v_bfe_u32 v166, v124, 16, 1
	v_add3_u32 v124, v124, v166, v5
	v_bfe_u32 v166, v125, 16, 1
	v_add3_u32 v125, v125, v166, v5
	v_bfe_u32 v166, v126, 16, 1
	v_add3_u32 v126, v126, v166, v5
	v_bfe_u32 v166, v127, 16, 1
	v_add3_u32 v127, v127, v166, v5
	v_lshrrev_b32_e32 v124, 16, v124
	v_lshrrev_b32_e32 v126, 16, v126
	v_and_or_b32 v124, v125, v6, v124
	v_and_or_b32 v125, v127, v6, v126
	global_store_dwordx2 v3, v[124:125], s[18:19] offset:2560
	v_bfe_u32 v166, v128, 16, 1
	v_add3_u32 v128, v128, v166, v5
	v_bfe_u32 v166, v129, 16, 1
	v_add3_u32 v129, v129, v166, v5
	v_bfe_u32 v166, v130, 16, 1
	v_add3_u32 v130, v130, v166, v5
	v_bfe_u32 v166, v131, 16, 1
	v_add3_u32 v131, v131, v166, v5
	v_lshrrev_b32_e32 v128, 16, v128
	v_lshrrev_b32_e32 v130, 16, v130
	v_and_or_b32 v128, v129, v6, v128
	v_and_or_b32 v129, v131, v6, v130
	global_store_dwordx2 v3, v[128:129], s[18:19] offset:3072
	v_bfe_u32 v166, v132, 16, 1
	v_add3_u32 v132, v132, v166, v5
	v_bfe_u32 v166, v133, 16, 1
	v_add3_u32 v133, v133, v166, v5
	v_bfe_u32 v166, v134, 16, 1
	v_add3_u32 v134, v134, v166, v5
	v_bfe_u32 v166, v135, 16, 1
	v_add3_u32 v135, v135, v166, v5
	v_lshrrev_b32_e32 v132, 16, v132
	v_lshrrev_b32_e32 v134, 16, v134
	v_and_or_b32 v132, v133, v6, v132
	v_and_or_b32 v133, v135, v6, v134
	global_store_dwordx2 v3, v[132:133], s[18:19] offset:3584
	s_mul_i32 s4, s5, 11
	s_add_u32 s4, s4, s3
	s_lshl_b32 s4, s4, 13
	s_add_u32 s14, s68, s4
	s_addc_u32 s15, s69, 0
	s_waitcnt vmcnt(52)
; __device__ __forceinline__ unsigned pk2(float lo, float hi) { return f2bf(lo) | (f2bf(hi) << 16); }
; __device__ __forceinline__ void phase_prologue(const Params& p, LAS unsigned char* lds) {
;     ...
;           for (int u = 0; u < UR; ++u) { const int row = row0 + u * NGW; s[u] = 0.f;
; #pragma unroll
;               for (int j = 0; j < 8; ++j) s[u] += (v[u][j][0] * v[u][j][0] + v[u][j][1] * v[u][j][1]) + (v[u][j][2] * v[u][j][2] + v[u][j][3] * v[u][j][3]);
;               s[u] = wave_sum(s[u]); if (lane == 0) rstd[row] = 1.0f / sqrtf(s[u] * (1.0f / DM) + 1e-6f);
;               u32x2* o = (u32x2*)(xb + (size_t)row * DM) + lane;
; #pragma unroll
;               for (int j = 0; j < 8; ++j) { u32x2 w; w.x = pk2(v[u][j][0], v[u][j][1]); w.y = pk2(v[u][j][2], v[u][j][3]); o[64 * j] = w; } } } }
	global_load_dwordx4 v[104:107], v1, s[14:15] nt
	global_load_dwordx4 v[108:111], v1, s[14:15] offset:1024 nt
	global_load_dwordx4 v[112:115], v1, s[14:15] offset:2048 nt
	global_load_dwordx4 v[116:119], v1, s[14:15] offset:3072 nt
	global_load_dwordx4 v[120:123], v2, s[14:15] nt
	global_load_dwordx4 v[124:127], v2, s[14:15] offset:1024 nt
	global_load_dwordx4 v[128:131], v2, s[14:15] offset:2048 nt
	global_load_dwordx4 v[132:135], v2, s[14:15] offset:3072 nt
	s_waitcnt vmcnt(58)
	v_mul_f32_e32 v138, v9, v9
	v_mul_f32_e32 v139, v11, v11
	v_fmac_f32_e32 v138, v8, v8
	v_fmac_f32_e32 v139, v10, v10
	v_add_f32_e32 v140, v138, v139
	s_waitcnt vmcnt(57)
	v_mul_f32_e32 v138, v13, v13
	v_mul_f32_e32 v139, v15, v15
	v_fmac_f32_e32 v138, v12, v12
	v_fmac_f32_e32 v139, v14, v14
	v_add_f32_e32 v141, v138, v139
	v_add_f32_e32 v140, v140, v141
	s_waitcnt vmcnt(56)
	v_mul_f32_e32 v138, v17, v17
	v_mul_f32_e32 v139, v19, v19
	v_fmac_f32_e32 v138, v16, v16
	v_fmac_f32_e32 v139, v18, v18
	v_add_f32_e32 v141, v138, v139
	v_add_f32_e32 v140, v140, v141
	s_waitcnt vmcnt(55)
	v_mul_f32_e32 v138, v21, v21
	v_mul_f32_e32 v139, v23, v23
	v_fmac_f32_e32 v138, v20, v20
	v_fmac_f32_e32 v139, v22, v22
	v_add_f32_e32 v141, v138, v139
	v_add_f32_e32 v140, v140, v141
	s_waitcnt vmcnt(54)
	v_mul_f32_e32 v138, v25, v25
	v_mul_f32_e32 v139, v27, v27
	v_fmac_f32_e32 v138, v24, v24
	v_fmac_f32_e32 v139, v26, v26
	v_add_f32_e32 v141, v138, v139
	v_add_f32_e32 v140, v140, v141
	s_waitcnt vmcnt(53)
	v_mul_f32_e32 v138, v29, v29
	v_mul_f32_e32 v139, v31, v31
	v_fmac_f32_e32 v138, v28, v28
	v_fmac_f32_e32 v139, v30, v30
	v_add_f32_e32 v141, v138, v139
	v_add_f32_e32 v140, v140, v141
	s_waitcnt vmcnt(52)
	v_mul_f32_e32 v138, v33, v33
	v_mul_f32_e32 v139, v35, v35
	v_fmac_f32_e32 v138, v32, v32
	v_fmac_f32_e32 v139, v34, v34
	v_add_f32_e32 v141, v138, v139
	v_add_f32_e32 v140, v140, v141
	s_waitcnt vmcnt(51)
	v_mul_f32_e32 v138, v37, v37
	v_mul_f32_e32 v139, v39, v39
	v_fmac_f32_e32 v138, v36, v36
	v_fmac_f32_e32 v139, v38, v38
	v_add_f32_e32 v141, v138, v139
	v_add_f32_e32 v140, v140, v141
	s_nop 1
	v_add_f32_dpp v140, v140, v140 quad_perm:[1,0,3,2] row_mask:0xf bank_mask:0xf
	s_nop 1
	v_add_f32_dpp v140, v140, v140 quad_perm:[2,3,0,1] row_mask:0xf bank_mask:0xf
	s_nop 1
	v_add_f32_dpp v140, v140, v140 row_half_mirror row_mask:0xf bank_mask:0xf
	s_nop 1
	v_add_f32_dpp v140, v140, v140 row_mirror row_mask:0xf bank_mask:0xf
	s_nop 1
	v_readlane_b32 s38, v140, 0
	v_readlane_b32 s39, v140, 16
	v_readlane_b32 s52, v140, 32
	v_readlane_b32 s53, v140, 48
	s_nop 1
	v_mov_b32_e32 v161, s39
	v_mov_b32_e32 v163, s53
	v_add_f32_e32 v161, s38, v161
	v_add_f32_e32 v163, s52, v163
	v_add_f32_e32 v146, v161, v163
	v_fmamk_f32 v147, v146, 0x3a000000, v136
	v_mul_f32_e32 v148, 0x4f800000, v147
	v_cmp_gt_f32_e32 vcc, v7, v147
	s_nop 1
	v_cndmask_b32_e32 v149, v147, v148, vcc
	v_sqrt_f32_e32 v150, v149
	s_nop 0
	v_add_u32_e32 v151, -1, v150
	v_add_u32_e32 v152, 1, v150
	v_fma_f32 v153, -v151, v150, v149
	v_fma_f32 v154, -v152, v150, v149
	v_cmp_ge_f32_e64 s[0:1], 0, v153
	s_nop 1
	v_cndmask_b32_e64 v155, v150, v151, s[0:1]
	v_cmp_lt_f32_e64 s[0:1], 0, v154
	s_nop 1
	v_cndmask_b32_e64 v155, v155, v152, s[0:1]
	v_mul_f32_e32 v156, 0x37800000, v155
	v_cndmask_b32_e32 v155, v155, v156, vcc
	v_cmp_class_f32_e32 vcc, v149, v137
	s_nop 1
	v_cndmask_b32_e32 v157, v155, v149, vcc
	v_div_scale_f32 v158, s[0:1], v157, v157, 1.0
	v_rcp_f32_e32 v159, v158
	v_div_scale_f32 v160, vcc, 1.0, v157, 1.0
	v_fma_f32 v161, -v158, v159, 1.0
	v_fmac_f32_e32 v159, v161, v159
	v_mul_f32_e32 v162, v160, v159
	v_fma_f32 v163, -v158, v162, v160
	v_fmac_f32_e32 v162, v163, v159
	v_fma_f32 v161, -v158, v162, v160
	v_div_fmas_f32 v164, v161, v159, v162
	v_div_fixup_f32 v165, v164, v157, 1.0
	s_mul_i32 s4, s5, 8
	s_add_u32 s4, s4, s3
	s_lshl_b32 s33, s4, 2
	s_add_u32 s36, s28, s33
	s_addc_u32 s37, s29, 0
	s_add_u32 s36, s36, 0x7c00000
	s_addc_u32 s37, s37, 0
	s_lshl_b32 s33, s4, 12
	s_add_u32 s16, s28, s33
	s_addc_u32 s17, s29, 0
	s_add_u32 s16, s16, 0x8800000
	s_addc_u32 s17, s17, 0
	s_mov_b64 exec, 1
	global_store_dword v4, v165, s[36:37]
	s_mov_b64 exec, -1
	v_bfe_u32 v166, v8, 16, 1
	v_add3_u32 v8, v8, v166, v5
	v_bfe_u32 v166, v9, 16, 1
	v_add3_u32 v9, v9, v166, v5
	v_bfe_u32 v166, v10, 16, 1
	v_add3_u32 v10, v10, v166, v5
	v_bfe_u32 v166, v11, 16, 1
	v_add3_u32 v11, v11, v166, v5
	v_lshrrev_b32_e32 v8, 16, v8
	v_lshrrev_b32_e32 v10, 16, v10
	v_and_or_b32 v8, v9, v6, v8
	v_and_or_b32 v9, v11, v6, v10
	global_store_dwordx2 v3, v[8:9], s[16:17]
	v_bfe_u32 v166, v12, 16, 1
	v_add3_u32 v12, v12, v166, v5
	v_bfe_u32 v166, v13, 16, 1
	v_add3_u32 v13, v13, v166, v5
	v_bfe_u32 v166, v14, 16, 1
	v_add3_u32 v14, v14, v166, v5
	v_bfe_u32 v166, v15, 16, 1
	v_add3_u32 v15, v15, v166, v5
	v_lshrrev_b32_e32 v12, 16, v12
	v_lshrrev_b32_e32 v14, 16, v14
	v_and_or_b32 v12, v13, v6, v12
	v_and_or_b32 v13, v15, v6, v14
	global_store_dwordx2 v3, v[12:13], s[16:17] offset:512
	v_bfe_u32 v166, v16, 16, 1
	v_add3_u32 v16, v16, v166, v5
	v_bfe_u32 v166, v17, 16, 1
	v_add3_u32 v17, v17, v166, v5
	v_bfe_u32 v166, v18, 16, 1
	v_add3_u32 v18, v18, v166, v5
	v_bfe_u32 v166, v19, 16, 1
	v_add3_u32 v19, v19, v166, v5
	v_lshrrev_b32_e32 v16, 16, v16
	v_lshrrev_b32_e32 v18, 16, v18
	v_and_or_b32 v16, v17, v6, v16
	v_and_or_b32 v17, v19, v6, v18
	global_store_dwordx2 v3, v[16:17], s[16:17] offset:1024
	v_bfe_u32 v166, v20, 16, 1
	v_add3_u32 v20, v20, v166, v5
	v_bfe_u32 v166, v21, 16, 1
	v_add3_u32 v21, v21, v166, v5
	v_bfe_u32 v166, v22, 16, 1
	v_add3_u32 v22, v22, v166, v5
	v_bfe_u32 v166, v23, 16, 1
	v_add3_u32 v23, v23, v166, v5
	v_lshrrev_b32_e32 v20, 16, v20
; __device__ __forceinline__ unsigned pk2(float lo, float hi) { return f2bf(lo) | (f2bf(hi) << 16); }
; __device__ __forceinline__ void phase_prologue(const Params& p, LAS unsigned char* lds) {
;     ...
;           for (int u = 0; u < UR; ++u) { const int row = row0 + u * NGW; s[u] = 0.f;
; #pragma unroll
;               for (int j = 0; j < 8; ++j) s[u] += (v[u][j][0] * v[u][j][0] + v[u][j][1] * v[u][j][1]) + (v[u][j][2] * v[u][j][2] + v[u][j][3] * v[u][j][3]);
;               s[u] = wave_sum(s[u]); if (lane == 0) rstd[row] = 1.0f / sqrtf(s[u] * (1.0f / DM) + 1e-6f);
;               u32x2* o = (u32x2*)(xb + (size_t)row * DM) + lane;
; #pragma unroll
;               for (int j = 0; j < 8; ++j) { u32x2 w; w.x = pk2(v[u][j][0], v[u][j][1]); w.y = pk2(v[u][j][2], v[u][j][3]); o[64 * j] = w; } } } }
	v_lshrrev_b32_e32 v22, 16, v22
	v_and_or_b32 v20, v21, v6, v20
	v_and_or_b32 v21, v23, v6, v22
	global_store_dwordx2 v3, v[20:21], s[16:17] offset:1536
	v_bfe_u32 v166, v24, 16, 1
	v_add3_u32 v24, v24, v166, v5
	v_bfe_u32 v166, v25, 16, 1
	v_add3_u32 v25, v25, v166, v5
	v_bfe_u32 v166, v26, 16, 1
	v_add3_u32 v26, v26, v166, v5
	v_bfe_u32 v166, v27, 16, 1
	v_add3_u32 v27, v27, v166, v5
	v_lshrrev_b32_e32 v24, 16, v24
	v_lshrrev_b32_e32 v26, 16, v26
	v_and_or_b32 v24, v25, v6, v24
	v_and_or_b32 v25, v27, v6, v26
	global_store_dwordx2 v3, v[24:25], s[16:17] offset:2048
	v_bfe_u32 v166, v28, 16, 1
	v_add3_u32 v28, v28, v166, v5
	v_bfe_u32 v166, v29, 16, 1
	v_add3_u32 v29, v29, v166, v5
	v_bfe_u32 v166, v30, 16, 1
	v_add3_u32 v30, v30, v166, v5
	v_bfe_u32 v166, v31, 16, 1
	v_add3_u32 v31, v31, v166, v5
	v_lshrrev_b32_e32 v28, 16, v28
	v_lshrrev_b32_e32 v30, 16, v30
	v_and_or_b32 v28, v29, v6, v28
	v_and_or_b32 v29, v31, v6, v30
	global_store_dwordx2 v3, v[28:29], s[16:17] offset:2560
	v_bfe_u32 v166, v32, 16, 1
	v_add3_u32 v32, v32, v166, v5
	v_bfe_u32 v166, v33, 16, 1
	v_add3_u32 v33, v33, v166, v5
	v_bfe_u32 v166, v34, 16, 1
	v_add3_u32 v34, v34, v166, v5
	v_bfe_u32 v166, v35, 16, 1
	v_add3_u32 v35, v35, v166, v5
	v_lshrrev_b32_e32 v32, 16, v32
	v_lshrrev_b32_e32 v34, 16, v34
	v_and_or_b32 v32, v33, v6, v32
	v_and_or_b32 v33, v35, v6, v34
	global_store_dwordx2 v3, v[32:33], s[16:17] offset:3072
	v_bfe_u32 v166, v36, 16, 1
	v_add3_u32 v36, v36, v166, v5
	v_bfe_u32 v166, v37, 16, 1
	v_add3_u32 v37, v37, v166, v5
	v_bfe_u32 v166, v38, 16, 1
	v_add3_u32 v38, v38, v166, v5
	v_bfe_u32 v166, v39, 16, 1
	v_add3_u32 v39, v39, v166, v5
	v_lshrrev_b32_e32 v36, 16, v36
	v_lshrrev_b32_e32 v38, 16, v38
	v_and_or_b32 v36, v37, v6, v36
	v_and_or_b32 v37, v39, v6, v38
	global_store_dwordx2 v3, v[36:37], s[16:17] offset:3584
	s_mul_i32 s4, s5, 12
	s_add_u32 s4, s4, s3
	s_lshl_b32 s4, s4, 13
	s_add_u32 s12, s68, s4
	s_addc_u32 s13, s69, 0
	s_waitcnt vmcnt(52)
	global_load_dwordx4 v[8:11], v1, s[12:13] nt
	global_load_dwordx4 v[12:15], v1, s[12:13] offset:1024 nt
	global_load_dwordx4 v[16:19], v1, s[12:13] offset:2048 nt
	global_load_dwordx4 v[20:23], v1, s[12:13] offset:3072 nt
	global_load_dwordx4 v[24:27], v2, s[12:13] nt
	global_load_dwordx4 v[28:31], v2, s[12:13] offset:1024 nt
	global_load_dwordx4 v[32:35], v2, s[12:13] offset:2048 nt
	global_load_dwordx4 v[36:39], v2, s[12:13] offset:3072 nt
	s_waitcnt vmcnt(58)
	v_mul_f32_e32 v138, v41, v41
	v_mul_f32_e32 v139, v43, v43
	v_fmac_f32_e32 v138, v40, v40
	v_fmac_f32_e32 v139, v42, v42
	v_add_f32_e32 v140, v138, v139
	s_waitcnt vmcnt(57)
	v_mul_f32_e32 v138, v45, v45
	v_mul_f32_e32 v139, v47, v47
	v_fmac_f32_e32 v138, v44, v44
	v_fmac_f32_e32 v139, v46, v46
	v_add_f32_e32 v141, v138, v139
	v_add_f32_e32 v140, v140, v141
	s_waitcnt vmcnt(56)
	v_mul_f32_e32 v138, v49, v49
	v_mul_f32_e32 v139, v51, v51
	v_fmac_f32_e32 v138, v48, v48
	v_fmac_f32_e32 v139, v50, v50
	v_add_f32_e32 v141, v138, v139
	v_add_f32_e32 v140, v140, v141
	s_waitcnt vmcnt(55)
	v_mul_f32_e32 v138, v53, v53
	v_mul_f32_e32 v139, v55, v55
	v_fmac_f32_e32 v138, v52, v52
	v_fmac_f32_e32 v139, v54, v54
	v_add_f32_e32 v141, v138, v139
	v_add_f32_e32 v140, v140, v141
	s_waitcnt vmcnt(54)
	v_mul_f32_e32 v138, v57, v57
	v_mul_f32_e32 v139, v59, v59
	v_fmac_f32_e32 v138, v56, v56
	v_fmac_f32_e32 v139, v58, v58
	v_add_f32_e32 v141, v138, v139
	v_add_f32_e32 v140, v140, v141
	s_waitcnt vmcnt(53)
	v_mul_f32_e32 v138, v61, v61
	v_mul_f32_e32 v139, v63, v63
	v_fmac_f32_e32 v138, v60, v60
	v_fmac_f32_e32 v139, v62, v62
	v_add_f32_e32 v141, v138, v139
	v_add_f32_e32 v140, v140, v141
	s_waitcnt vmcnt(52)
	v_mul_f32_e32 v138, v65, v65
	v_mul_f32_e32 v139, v67, v67
	v_fmac_f32_e32 v138, v64, v64
	v_fmac_f32_e32 v139, v66, v66
	v_add_f32_e32 v141, v138, v139
	v_add_f32_e32 v140, v140, v141
	s_waitcnt vmcnt(51)
	v_mul_f32_e32 v138, v69, v69
	v_mul_f32_e32 v139, v71, v71
	v_fmac_f32_e32 v138, v68, v68
	v_fmac_f32_e32 v139, v70, v70
	v_add_f32_e32 v141, v138, v139
	v_add_f32_e32 v140, v140, v141
	s_nop 1
	v_add_f32_dpp v140, v140, v140 quad_perm:[1,0,3,2] row_mask:0xf bank_mask:0xf
	s_nop 1
	v_add_f32_dpp v140, v140, v140 quad_perm:[2,3,0,1] row_mask:0xf bank_mask:0xf
	s_nop 1
	v_add_f32_dpp v140, v140, v140 row_half_mirror row_mask:0xf bank_mask:0xf
	s_nop 1
	v_add_f32_dpp v140, v140, v140 row_mirror row_mask:0xf bank_mask:0xf
	s_nop 1
	v_readlane_b32 s38, v140, 0
	v_readlane_b32 s39, v140, 16
	v_readlane_b32 s52, v140, 32
	v_readlane_b32 s53, v140, 48
	s_nop 1
	v_mov_b32_e32 v161, s39
	v_mov_b32_e32 v163, s53
	v_add_f32_e32 v161, s38, v161
	v_add_f32_e32 v163, s52, v163
	v_add_f32_e32 v146, v161, v163
	v_fmamk_f32 v147, v146, 0x3a000000, v136
	v_mul_f32_e32 v148, 0x4f800000, v147
	v_cmp_gt_f32_e32 vcc, v7, v147
	s_nop 1
	v_cndmask_b32_e32 v149, v147, v148, vcc
	v_sqrt_f32_e32 v150, v149
	s_nop 0
	v_add_u32_e32 v151, -1, v150
	v_add_u32_e32 v152, 1, v150
	v_fma_f32 v153, -v151, v150, v149
	v_fma_f32 v154, -v152, v150, v149
	v_cmp_ge_f32_e64 s[0:1], 0, v153
	s_nop 1
	v_cndmask_b32_e64 v155, v150, v151, s[0:1]
	v_cmp_lt_f32_e64 s[0:1], 0, v154
	s_nop 1
	v_cndmask_b32_e64 v155, v155, v152, s[0:1]
	v_mul_f32_e32 v156, 0x37800000, v155
	v_cndmask_b32_e32 v155, v155, v156, vcc
	v_cmp_class_f32_e32 vcc, v149, v137
	s_nop 1
	v_cndmask_b32_e32 v157, v155, v149, vcc
	v_div_scale_f32 v158, s[0:1], v157, v157, 1.0
	v_rcp_f32_e32 v159, v158
	v_div_scale_f32 v160, vcc, 1.0, v157, 1.0
	v_fma_f32 v161, -v158, v159, 1.0
	v_fmac_f32_e32 v159, v161, v159
	v_mul_f32_e32 v162, v160, v159
	v_fma_f32 v163, -v158, v162, v160
	v_fmac_f32_e32 v162, v163, v159
	v_fma_f32 v161, -v158, v162, v160
; __device__ __forceinline__ unsigned pk2(float lo, float hi) { return f2bf(lo) | (f2bf(hi) << 16); }
; __device__ __forceinline__ void phase_prologue(const Params& p, LAS unsigned char* lds) {
;     ...
;           for (int u = 0; u < UR; ++u) { const int row = row0 + u * NGW; s[u] = 0.f;
; #pragma unroll
;               for (int j = 0; j < 8; ++j) s[u] += (v[u][j][0] * v[u][j][0] + v[u][j][1] * v[u][j][1]) + (v[u][j][2] * v[u][j][2] + v[u][j][3] * v[u][j][3]);
;               s[u] = wave_sum(s[u]); if (lane == 0) rstd[row] = 1.0f / sqrtf(s[u] * (1.0f / DM) + 1e-6f);
;               u32x2* o = (u32x2*)(xb + (size_t)row * DM) + lane;
; #pragma unroll
;               for (int j = 0; j < 8; ++j) { u32x2 w; w.x = pk2(v[u][j][0], v[u][j][1]); w.y = pk2(v[u][j][2], v[u][j][3]); o[64 * j] = w; } } } }
	v_div_fmas_f32 v164, v161, v159, v162
	v_div_fixup_f32 v165, v164, v157, 1.0
	s_mul_i32 s4, s5, 9
	s_add_u32 s4, s4, s3
	s_lshl_b32 s33, s4, 2
	s_add_u32 s36, s28, s33
	s_addc_u32 s37, s29, 0
	s_add_u32 s36, s36, 0x7c00000
	s_addc_u32 s37, s37, 0
	s_lshl_b32 s33, s4, 12
	s_add_u32 s18, s28, s33
	s_addc_u32 s19, s29, 0
	s_add_u32 s18, s18, 0x8800000
	s_addc_u32 s19, s19, 0
	s_mov_b64 exec, 1
	global_store_dword v4, v165, s[36:37]
	s_mov_b64 exec, -1
	v_bfe_u32 v166, v40, 16, 1
	v_add3_u32 v40, v40, v166, v5
	v_bfe_u32 v166, v41, 16, 1
	v_add3_u32 v41, v41, v166, v5
	v_bfe_u32 v166, v42, 16, 1
	v_add3_u32 v42, v42, v166, v5
	v_bfe_u32 v166, v43, 16, 1
	v_add3_u32 v43, v43, v166, v5
	v_lshrrev_b32_e32 v40, 16, v40
	v_lshrrev_b32_e32 v42, 16, v42
	v_and_or_b32 v40, v41, v6, v40
	v_and_or_b32 v41, v43, v6, v42
	global_store_dwordx2 v3, v[40:41], s[18:19]
	v_bfe_u32 v166, v44, 16, 1
	v_add3_u32 v44, v44, v166, v5
	v_bfe_u32 v166, v45, 16, 1
	v_add3_u32 v45, v45, v166, v5
	v_bfe_u32 v166, v46, 16, 1
	v_add3_u32 v46, v46, v166, v5
	v_bfe_u32 v166, v47, 16, 1
	v_add3_u32 v47, v47, v166, v5
	v_lshrrev_b32_e32 v44, 16, v44
	v_lshrrev_b32_e32 v46, 16, v46
	v_and_or_b32 v44, v45, v6, v44
	v_and_or_b32 v45, v47, v6, v46
	global_store_dwordx2 v3, v[44:45], s[18:19] offset:512
	v_bfe_u32 v166, v48, 16, 1
	v_add3_u32 v48, v48, v166, v5
	v_bfe_u32 v166, v49, 16, 1
	v_add3_u32 v49, v49, v166, v5
	v_bfe_u32 v166, v50, 16, 1
	v_add3_u32 v50, v50, v166, v5
	v_bfe_u32 v166, v51, 16, 1
	v_add3_u32 v51, v51, v166, v5
	v_lshrrev_b32_e32 v48, 16, v48
	v_lshrrev_b32_e32 v50, 16, v50
	v_and_or_b32 v48, v49, v6, v48
	v_and_or_b32 v49, v51, v6, v50
	global_store_dwordx2 v3, v[48:49], s[18:19] offset:1024
	v_bfe_u32 v166, v52, 16, 1
	v_add3_u32 v52, v52, v166, v5
	v_bfe_u32 v166, v53, 16, 1
	v_add3_u32 v53, v53, v166, v5
	v_bfe_u32 v166, v54, 16, 1
	v_add3_u32 v54, v54, v166, v5
	v_bfe_u32 v166, v55, 16, 1
	v_add3_u32 v55, v55, v166, v5
	v_lshrrev_b32_e32 v52, 16, v52
	v_lshrrev_b32_e32 v54, 16, v54
	v_and_or_b32 v52, v53, v6, v52
	v_and_or_b32 v53, v55, v6, v54
	global_store_dwordx2 v3, v[52:53], s[18:19] offset:1536
	v_bfe_u32 v166, v56, 16, 1
	v_add3_u32 v56, v56, v166, v5
	v_bfe_u32 v166, v57, 16, 1
	v_add3_u32 v57, v57, v166, v5
	v_bfe_u32 v166, v58, 16, 1
	v_add3_u32 v58, v58, v166, v5
	v_bfe_u32 v166, v59, 16, 1
	v_add3_u32 v59, v59, v166, v5
	v_lshrrev_b32_e32 v56, 16, v56
	v_lshrrev_b32_e32 v58, 16, v58
	v_and_or_b32 v56, v57, v6, v56
	v_and_or_b32 v57, v59, v6, v58
	global_store_dwordx2 v3, v[56:57], s[18:19] offset:2048
	v_bfe_u32 v166, v60, 16, 1
	v_add3_u32 v60, v60, v166, v5
	v_bfe_u32 v166, v61, 16, 1
	v_add3_u32 v61, v61, v166, v5
	v_bfe_u32 v166, v62, 16, 1
	v_add3_u32 v62, v62, v166, v5
	v_bfe_u32 v166, v63, 16, 1
	v_add3_u32 v63, v63, v166, v5
	v_lshrrev_b32_e32 v60, 16, v60
	v_lshrrev_b32_e32 v62, 16, v62
	v_and_or_b32 v60, v61, v6, v60
	v_and_or_b32 v61, v63, v6, v62
	global_store_dwordx2 v3, v[60:61], s[18:19] offset:2560
	v_bfe_u32 v166, v64, 16, 1
	v_add3_u32 v64, v64, v166, v5
	v_bfe_u32 v166, v65, 16, 1
	v_add3_u32 v65, v65, v166, v5
	v_bfe_u32 v166, v66, 16, 1
	v_add3_u32 v66, v66, v166, v5
	v_bfe_u32 v166, v67, 16, 1
	v_add3_u32 v67, v67, v166, v5
	v_lshrrev_b32_e32 v64, 16, v64
	v_lshrrev_b32_e32 v66, 16, v66
	v_and_or_b32 v64, v65, v6, v64
	v_and_or_b32 v65, v67, v6, v66
	global_store_dwordx2 v3, v[64:65], s[18:19] offset:3072
	v_bfe_u32 v166, v68, 16, 1
	v_add3_u32 v68, v68, v166, v5
	v_bfe_u32 v166, v69, 16, 1
	v_add3_u32 v69, v69, v166, v5
	v_bfe_u32 v166, v70, 16, 1
	v_add3_u32 v70, v70, v166, v5
	v_bfe_u32 v166, v71, 16, 1
	v_add3_u32 v71, v71, v166, v5
	v_lshrrev_b32_e32 v68, 16, v68
	v_lshrrev_b32_e32 v70, 16, v70
	v_and_or_b32 v68, v69, v6, v68
	v_and_or_b32 v69, v71, v6, v70
	global_store_dwordx2 v3, v[68:69], s[18:19] offset:3584
	s_mul_i32 s4, s5, 13
	s_add_u32 s4, s4, s3
	s_lshl_b32 s4, s4, 13
	s_add_u32 s14, s68, s4
	s_addc_u32 s15, s69, 0
	s_waitcnt vmcnt(52)
	global_load_dwordx4 v[40:43], v1, s[14:15] nt
	global_load_dwordx4 v[44:47], v1, s[14:15] offset:1024 nt
	global_load_dwordx4 v[48:51], v1, s[14:15] offset:2048 nt
	global_load_dwordx4 v[52:55], v1, s[14:15] offset:3072 nt
	global_load_dwordx4 v[56:59], v2, s[14:15] nt
	global_load_dwordx4 v[60:63], v2, s[14:15] offset:1024 nt
	global_load_dwordx4 v[64:67], v2, s[14:15] offset:2048 nt
	global_load_dwordx4 v[68:71], v2, s[14:15] offset:3072 nt
	s_waitcnt vmcnt(58)
	v_mul_f32_e32 v138, v73, v73
	v_mul_f32_e32 v139, v75, v75
	v_fmac_f32_e32 v138, v72, v72
	v_fmac_f32_e32 v139, v74, v74
	v_add_f32_e32 v140, v138, v139
	s_waitcnt vmcnt(57)
	v_mul_f32_e32 v138, v77, v77
	v_mul_f32_e32 v139, v79, v79
	v_fmac_f32_e32 v138, v76, v76
	v_fmac_f32_e32 v139, v78, v78
	v_add_f32_e32 v141, v138, v139
	v_add_f32_e32 v140, v140, v141
	s_waitcnt vmcnt(56)
	v_mul_f32_e32 v138, v81, v81
	v_mul_f32_e32 v139, v83, v83
	v_fmac_f32_e32 v138, v80, v80
	v_fmac_f32_e32 v139, v82, v82
	v_add_f32_e32 v141, v138, v139
	v_add_f32_e32 v140, v140, v141
	s_waitcnt vmcnt(55)
	v_mul_f32_e32 v138, v85, v85
	v_mul_f32_e32 v139, v87, v87
	v_fmac_f32_e32 v138, v84, v84
	v_fmac_f32_e32 v139, v86, v86
	v_add_f32_e32 v141, v138, v139
	v_add_f32_e32 v140, v140, v141
	s_waitcnt vmcnt(54)
	v_mul_f32_e32 v138, v89, v89
	v_mul_f32_e32 v139, v91, v91
	v_fmac_f32_e32 v138, v88, v88
	v_fmac_f32_e32 v139, v90, v90
	v_add_f32_e32 v141, v138, v139
	v_add_f32_e32 v140, v140, v141
	s_waitcnt vmcnt(53)
	v_mul_f32_e32 v138, v93, v93
	v_mul_f32_e32 v139, v95, v95
	v_fmac_f32_e32 v138, v92, v92
	v_fmac_f32_e32 v139, v94, v94
	v_add_f32_e32 v141, v138, v139
	v_add_f32_e32 v140, v140, v141
	s_waitcnt vmcnt(52)
; __device__ __forceinline__ unsigned pk2(float lo, float hi) { return f2bf(lo) | (f2bf(hi) << 16); }
; __device__ __forceinline__ void phase_prologue(const Params& p, LAS unsigned char* lds) {
;     ...
;           for (int u = 0; u < UR; ++u) { const int row = row0 + u * NGW; s[u] = 0.f;
; #pragma unroll
;               for (int j = 0; j < 8; ++j) s[u] += (v[u][j][0] * v[u][j][0] + v[u][j][1] * v[u][j][1]) + (v[u][j][2] * v[u][j][2] + v[u][j][3] * v[u][j][3]);
;               s[u] = wave_sum(s[u]); if (lane == 0) rstd[row] = 1.0f / sqrtf(s[u] * (1.0f / DM) + 1e-6f);
;               u32x2* o = (u32x2*)(xb + (size_t)row * DM) + lane;
; #pragma unroll
;               for (int j = 0; j < 8; ++j) { u32x2 w; w.x = pk2(v[u][j][0], v[u][j][1]); w.y = pk2(v[u][j][2], v[u][j][3]); o[64 * j] = w; } } } }
	v_mul_f32_e32 v138, v97, v97
	v_mul_f32_e32 v139, v99, v99
	v_fmac_f32_e32 v138, v96, v96
	v_fmac_f32_e32 v139, v98, v98
	v_add_f32_e32 v141, v138, v139
	v_add_f32_e32 v140, v140, v141
	s_waitcnt vmcnt(51)
	v_mul_f32_e32 v138, v101, v101
	v_mul_f32_e32 v139, v103, v103
	v_fmac_f32_e32 v138, v100, v100
	v_fmac_f32_e32 v139, v102, v102
	v_add_f32_e32 v141, v138, v139
	v_add_f32_e32 v140, v140, v141
	s_nop 1
	v_add_f32_dpp v140, v140, v140 quad_perm:[1,0,3,2] row_mask:0xf bank_mask:0xf
	s_nop 1
	v_add_f32_dpp v140, v140, v140 quad_perm:[2,3,0,1] row_mask:0xf bank_mask:0xf
	s_nop 1
	v_add_f32_dpp v140, v140, v140 row_half_mirror row_mask:0xf bank_mask:0xf
	s_nop 1
	v_add_f32_dpp v140, v140, v140 row_mirror row_mask:0xf bank_mask:0xf
	s_nop 1
	v_readlane_b32 s38, v140, 0
	v_readlane_b32 s39, v140, 16
	v_readlane_b32 s52, v140, 32
	v_readlane_b32 s53, v140, 48
	s_nop 1
	v_mov_b32_e32 v161, s39
	v_mov_b32_e32 v163, s53
	v_add_f32_e32 v161, s38, v161
	v_add_f32_e32 v163, s52, v163
	v_add_f32_e32 v146, v161, v163
	v_fmamk_f32 v147, v146, 0x3a000000, v136
	v_mul_f32_e32 v148, 0x4f800000, v147
	v_cmp_gt_f32_e32 vcc, v7, v147
	s_nop 1
	v_cndmask_b32_e32 v149, v147, v148, vcc
	v_sqrt_f32_e32 v150, v149
	s_nop 0
	v_add_u32_e32 v151, -1, v150
	v_add_u32_e32 v152, 1, v150
	v_fma_f32 v153, -v151, v150, v149
	v_fma_f32 v154, -v152, v150, v149
	v_cmp_ge_f32_e64 s[0:1], 0, v153
	s_nop 1
	v_cndmask_b32_e64 v155, v150, v151, s[0:1]
	v_cmp_lt_f32_e64 s[0:1], 0, v154
	s_nop 1
	v_cndmask_b32_e64 v155, v155, v152, s[0:1]
	v_mul_f32_e32 v156, 0x37800000, v155
	v_cndmask_b32_e32 v155, v155, v156, vcc
	v_cmp_class_f32_e32 vcc, v149, v137
	s_nop 1
	v_cndmask_b32_e32 v157, v155, v149, vcc
	v_div_scale_f32 v158, s[0:1], v157, v157, 1.0
	v_rcp_f32_e32 v159, v158
	v_div_scale_f32 v160, vcc, 1.0, v157, 1.0
	v_fma_f32 v161, -v158, v159, 1.0
	v_fmac_f32_e32 v159, v161, v159
	v_mul_f32_e32 v162, v160, v159
	v_fma_f32 v163, -v158, v162, v160
	v_fmac_f32_e32 v162, v163, v159
	v_fma_f32 v161, -v158, v162, v160
	v_div_fmas_f32 v164, v161, v159, v162
	v_div_fixup_f32 v165, v164, v157, 1.0
	s_mul_i32 s4, s5, 10
	s_add_u32 s4, s4, s3
	s_lshl_b32 s33, s4, 2
	s_add_u32 s36, s28, s33
	s_addc_u32 s37, s29, 0
	s_add_u32 s36, s36, 0x7c00000
	s_addc_u32 s37, s37, 0
	s_lshl_b32 s33, s4, 12
	s_add_u32 s16, s28, s33
	s_addc_u32 s17, s29, 0
	s_add_u32 s16, s16, 0x8800000
	s_addc_u32 s17, s17, 0
	s_mov_b64 exec, 1
	global_store_dword v4, v165, s[36:37]
	s_mov_b64 exec, -1
	v_bfe_u32 v166, v72, 16, 1
	v_add3_u32 v72, v72, v166, v5
	v_bfe_u32 v166, v73, 16, 1
	v_add3_u32 v73, v73, v166, v5
	v_bfe_u32 v166, v74, 16, 1
	v_add3_u32 v74, v74, v166, v5
	v_bfe_u32 v166, v75, 16, 1
	v_add3_u32 v75, v75, v166, v5
	v_lshrrev_b32_e32 v72, 16, v72
	v_lshrrev_b32_e32 v74, 16, v74
	v_and_or_b32 v72, v73, v6, v72
	v_and_or_b32 v73, v75, v6, v74
	global_store_dwordx2 v3, v[72:73], s[16:17]
	v_bfe_u32 v166, v76, 16, 1
	v_add3_u32 v76, v76, v166, v5
	v_bfe_u32 v166, v77, 16, 1
	v_add3_u32 v77, v77, v166, v5
	v_bfe_u32 v166, v78, 16, 1
	v_add3_u32 v78, v78, v166, v5
	v_bfe_u32 v166, v79, 16, 1
	v_add3_u32 v79, v79, v166, v5
	v_lshrrev_b32_e32 v76, 16, v76
	v_lshrrev_b32_e32 v78, 16, v78
	v_and_or_b32 v76, v77, v6, v76
	v_and_or_b32 v77, v79, v6, v78
	global_store_dwordx2 v3, v[76:77], s[16:17] offset:512
	v_bfe_u32 v166, v80, 16, 1
	v_add3_u32 v80, v80, v166, v5
	v_bfe_u32 v166, v81, 16, 1
	v_add3_u32 v81, v81, v166, v5
	v_bfe_u32 v166, v82, 16, 1
	v_add3_u32 v82, v82, v166, v5
	v_bfe_u32 v166, v83, 16, 1
	v_add3_u32 v83, v83, v166, v5
	v_lshrrev_b32_e32 v80, 16, v80
	v_lshrrev_b32_e32 v82, 16, v82
	v_and_or_b32 v80, v81, v6, v80
	v_and_or_b32 v81, v83, v6, v82
	global_store_dwordx2 v3, v[80:81], s[16:17] offset:1024
	v_bfe_u32 v166, v84, 16, 1
	v_add3_u32 v84, v84, v166, v5
	v_bfe_u32 v166, v85, 16, 1
	v_add3_u32 v85, v85, v166, v5
	v_bfe_u32 v166, v86, 16, 1
	v_add3_u32 v86, v86, v166, v5
	v_bfe_u32 v166, v87, 16, 1
	v_add3_u32 v87, v87, v166, v5
	v_lshrrev_b32_e32 v84, 16, v84
	v_lshrrev_b32_e32 v86, 16, v86
	v_and_or_b32 v84, v85, v6, v84
	v_and_or_b32 v85, v87, v6, v86
	global_store_dwordx2 v3, v[84:85], s[16:17] offset:1536
	v_bfe_u32 v166, v88, 16, 1
	v_add3_u32 v88, v88, v166, v5
	v_bfe_u32 v166, v89, 16, 1
	v_add3_u32 v89, v89, v166, v5
	v_bfe_u32 v166, v90, 16, 1
	v_add3_u32 v90, v90, v166, v5
	v_bfe_u32 v166, v91, 16, 1
	v_add3_u32 v91, v91, v166, v5
	v_lshrrev_b32_e32 v88, 16, v88
	v_lshrrev_b32_e32 v90, 16, v90
	v_and_or_b32 v88, v89, v6, v88
	v_and_or_b32 v89, v91, v6, v90
	global_store_dwordx2 v3, v[88:89], s[16:17] offset:2048
	v_bfe_u32 v166, v92, 16, 1
	v_add3_u32 v92, v92, v166, v5
	v_bfe_u32 v166, v93, 16, 1
	v_add3_u32 v93, v93, v166, v5
	v_bfe_u32 v166, v94, 16, 1
	v_add3_u32 v94, v94, v166, v5
	v_bfe_u32 v166, v95, 16, 1
	v_add3_u32 v95, v95, v166, v5
	v_lshrrev_b32_e32 v92, 16, v92
	v_lshrrev_b32_e32 v94, 16, v94
	v_and_or_b32 v92, v93, v6, v92
	v_and_or_b32 v93, v95, v6, v94
	global_store_dwordx2 v3, v[92:93], s[16:17] offset:2560
	v_bfe_u32 v166, v96, 16, 1
	v_add3_u32 v96, v96, v166, v5
	v_bfe_u32 v166, v97, 16, 1
	v_add3_u32 v97, v97, v166, v5
	v_bfe_u32 v166, v98, 16, 1
	v_add3_u32 v98, v98, v166, v5
	v_bfe_u32 v166, v99, 16, 1
	v_add3_u32 v99, v99, v166, v5
	v_lshrrev_b32_e32 v96, 16, v96
	v_lshrrev_b32_e32 v98, 16, v98
	v_and_or_b32 v96, v97, v6, v96
	v_and_or_b32 v97, v99, v6, v98
	global_store_dwordx2 v3, v[96:97], s[16:17] offset:3072
	v_bfe_u32 v166, v100, 16, 1
	v_add3_u32 v100, v100, v166, v5
	v_bfe_u32 v166, v101, 16, 1
	v_add3_u32 v101, v101, v166, v5
	v_bfe_u32 v166, v102, 16, 1
	v_add3_u32 v102, v102, v166, v5
	v_bfe_u32 v166, v103, 16, 1
	v_add3_u32 v103, v103, v166, v5
	v_lshrrev_b32_e32 v100, 16, v100
	v_lshrrev_b32_e32 v102, 16, v102
	v_and_or_b32 v100, v101, v6, v100
	v_and_or_b32 v101, v103, v6, v102
	global_store_dwordx2 v3, v[100:101], s[16:17] offset:3584
	s_mul_i32 s4, s5, 14
	s_add_u32 s4, s4, s3
	s_lshl_b32 s4, s4, 13
	s_add_u32 s12, s68, s4
	s_addc_u32 s13, s69, 0
	s_waitcnt vmcnt(52)
; __device__ __forceinline__ unsigned pk2(float lo, float hi) { return f2bf(lo) | (f2bf(hi) << 16); }
; __device__ __forceinline__ void phase_prologue(const Params& p, LAS unsigned char* lds) {
;     ...
;           for (int u = 0; u < UR; ++u) { const int row = row0 + u * NGW; s[u] = 0.f;
; #pragma unroll
;               for (int j = 0; j < 8; ++j) s[u] += (v[u][j][0] * v[u][j][0] + v[u][j][1] * v[u][j][1]) + (v[u][j][2] * v[u][j][2] + v[u][j][3] * v[u][j][3]);
;               s[u] = wave_sum(s[u]); if (lane == 0) rstd[row] = 1.0f / sqrtf(s[u] * (1.0f / DM) + 1e-6f);
;               u32x2* o = (u32x2*)(xb + (size_t)row * DM) + lane;
; #pragma unroll
;               for (int j = 0; j < 8; ++j) { u32x2 w; w.x = pk2(v[u][j][0], v[u][j][1]); w.y = pk2(v[u][j][2], v[u][j][3]); o[64 * j] = w; } } } }
	global_load_dwordx4 v[72:75], v1, s[12:13] nt
	global_load_dwordx4 v[76:79], v1, s[12:13] offset:1024 nt
	global_load_dwordx4 v[80:83], v1, s[12:13] offset:2048 nt
	global_load_dwordx4 v[84:87], v1, s[12:13] offset:3072 nt
	global_load_dwordx4 v[88:91], v2, s[12:13] nt
	global_load_dwordx4 v[92:95], v2, s[12:13] offset:1024 nt
	global_load_dwordx4 v[96:99], v2, s[12:13] offset:2048 nt
	global_load_dwordx4 v[100:103], v2, s[12:13] offset:3072 nt
	s_waitcnt vmcnt(58)
	v_mul_f32_e32 v138, v105, v105
	v_mul_f32_e32 v139, v107, v107
	v_fmac_f32_e32 v138, v104, v104
	v_fmac_f32_e32 v139, v106, v106
	v_add_f32_e32 v140, v138, v139
	s_waitcnt vmcnt(57)
	v_mul_f32_e32 v138, v109, v109
	v_mul_f32_e32 v139, v111, v111
	v_fmac_f32_e32 v138, v108, v108
	v_fmac_f32_e32 v139, v110, v110
	v_add_f32_e32 v141, v138, v139
	v_add_f32_e32 v140, v140, v141
	s_waitcnt vmcnt(56)
	v_mul_f32_e32 v138, v113, v113
	v_mul_f32_e32 v139, v115, v115
	v_fmac_f32_e32 v138, v112, v112
	v_fmac_f32_e32 v139, v114, v114
	v_add_f32_e32 v141, v138, v139
	v_add_f32_e32 v140, v140, v141
	s_waitcnt vmcnt(55)
	v_mul_f32_e32 v138, v117, v117
	v_mul_f32_e32 v139, v119, v119
	v_fmac_f32_e32 v138, v116, v116
	v_fmac_f32_e32 v139, v118, v118
	v_add_f32_e32 v141, v138, v139
	v_add_f32_e32 v140, v140, v141
	s_waitcnt vmcnt(54)
	v_mul_f32_e32 v138, v121, v121
	v_mul_f32_e32 v139, v123, v123
	v_fmac_f32_e32 v138, v120, v120
	v_fmac_f32_e32 v139, v122, v122
	v_add_f32_e32 v141, v138, v139
	v_add_f32_e32 v140, v140, v141
	s_waitcnt vmcnt(53)
	v_mul_f32_e32 v138, v125, v125
	v_mul_f32_e32 v139, v127, v127
	v_fmac_f32_e32 v138, v124, v124
	v_fmac_f32_e32 v139, v126, v126
	v_add_f32_e32 v141, v138, v139
	v_add_f32_e32 v140, v140, v141
	s_waitcnt vmcnt(52)
	v_mul_f32_e32 v138, v129, v129
	v_mul_f32_e32 v139, v131, v131
	v_fmac_f32_e32 v138, v128, v128
	v_fmac_f32_e32 v139, v130, v130
	v_add_f32_e32 v141, v138, v139
	v_add_f32_e32 v140, v140, v141
	s_waitcnt vmcnt(51)
	v_mul_f32_e32 v138, v133, v133
	v_mul_f32_e32 v139, v135, v135
	v_fmac_f32_e32 v138, v132, v132
	v_fmac_f32_e32 v139, v134, v134
	v_add_f32_e32 v141, v138, v139
	v_add_f32_e32 v140, v140, v141
	s_nop 1
	v_add_f32_dpp v140, v140, v140 quad_perm:[1,0,3,2] row_mask:0xf bank_mask:0xf
	s_nop 1
	v_add_f32_dpp v140, v140, v140 quad_perm:[2,3,0,1] row_mask:0xf bank_mask:0xf
	s_nop 1
	v_add_f32_dpp v140, v140, v140 row_half_mirror row_mask:0xf bank_mask:0xf
	s_nop 1
	v_add_f32_dpp v140, v140, v140 row_mirror row_mask:0xf bank_mask:0xf
	s_nop 1
	v_readlane_b32 s38, v140, 0
	v_readlane_b32 s39, v140, 16
	v_readlane_b32 s52, v140, 32
	v_readlane_b32 s53, v140, 48
	s_nop 1
	v_mov_b32_e32 v161, s39
	v_mov_b32_e32 v163, s53
	v_add_f32_e32 v161, s38, v161
	v_add_f32_e32 v163, s52, v163
	v_add_f32_e32 v146, v161, v163
	v_fmamk_f32 v147, v146, 0x3a000000, v136
	v_mul_f32_e32 v148, 0x4f800000, v147
	v_cmp_gt_f32_e32 vcc, v7, v147
	s_nop 1
	v_cndmask_b32_e32 v149, v147, v148, vcc
	v_sqrt_f32_e32 v150, v149
	s_nop 0
	v_add_u32_e32 v151, -1, v150
	v_add_u32_e32 v152, 1, v150
	v_fma_f32 v153, -v151, v150, v149
	v_fma_f32 v154, -v152, v150, v149
	v_cmp_ge_f32_e64 s[0:1], 0, v153
	s_nop 1
	v_cndmask_b32_e64 v155, v150, v151, s[0:1]
	v_cmp_lt_f32_e64 s[0:1], 0, v154
	s_nop 1
	v_cndmask_b32_e64 v155, v155, v152, s[0:1]
	v_mul_f32_e32 v156, 0x37800000, v155
	v_cndmask_b32_e32 v155, v155, v156, vcc
	v_cmp_class_f32_e32 vcc, v149, v137
	s_nop 1
	v_cndmask_b32_e32 v157, v155, v149, vcc
	v_div_scale_f32 v158, s[0:1], v157, v157, 1.0
	v_rcp_f32_e32 v159, v158
	v_div_scale_f32 v160, vcc, 1.0, v157, 1.0
	v_fma_f32 v161, -v158, v159, 1.0
	v_fmac_f32_e32 v159, v161, v159
	v_mul_f32_e32 v162, v160, v159
	v_fma_f32 v163, -v158, v162, v160
	v_fmac_f32_e32 v162, v163, v159
	v_fma_f32 v161, -v158, v162, v160
	v_div_fmas_f32 v164, v161, v159, v162
	v_div_fixup_f32 v165, v164, v157, 1.0
	s_mul_i32 s4, s5, 11
	s_add_u32 s4, s4, s3
	s_lshl_b32 s33, s4, 2
	s_add_u32 s36, s28, s33
	s_addc_u32 s37, s29, 0
	s_add_u32 s36, s36, 0x7c00000
	s_addc_u32 s37, s37, 0
	s_lshl_b32 s33, s4, 12
	s_add_u32 s18, s28, s33
	s_addc_u32 s19, s29, 0
	s_add_u32 s18, s18, 0x8800000
	s_addc_u32 s19, s19, 0
	s_mov_b64 exec, 1
	global_store_dword v4, v165, s[36:37]
	s_mov_b64 exec, -1
	v_bfe_u32 v166, v104, 16, 1
	v_add3_u32 v104, v104, v166, v5
	v_bfe_u32 v166, v105, 16, 1
	v_add3_u32 v105, v105, v166, v5
	v_bfe_u32 v166, v106, 16, 1
	v_add3_u32 v106, v106, v166, v5
	v_bfe_u32 v166, v107, 16, 1
	v_add3_u32 v107, v107, v166, v5
	v_lshrrev_b32_e32 v104, 16, v104
	v_lshrrev_b32_e32 v106, 16, v106
	v_and_or_b32 v104, v105, v6, v104
	v_and_or_b32 v105, v107, v6, v106
	global_store_dwordx2 v3, v[104:105], s[18:19]
	v_bfe_u32 v166, v108, 16, 1
	v_add3_u32 v108, v108, v166, v5
	v_bfe_u32 v166, v109, 16, 1
	v_add3_u32 v109, v109, v166, v5
	v_bfe_u32 v166, v110, 16, 1
	v_add3_u32 v110, v110, v166, v5
	v_bfe_u32 v166, v111, 16, 1
	v_add3_u32 v111, v111, v166, v5
	v_lshrrev_b32_e32 v108, 16, v108
	v_lshrrev_b32_e32 v110, 16, v110
	v_and_or_b32 v108, v109, v6, v108
	v_and_or_b32 v109, v111, v6, v110
	global_store_dwordx2 v3, v[108:109], s[18:19] offset:512
	v_bfe_u32 v166, v112, 16, 1
	v_add3_u32 v112, v112, v166, v5
	v_bfe_u32 v166, v113, 16, 1
	v_add3_u32 v113, v113, v166, v5
	v_bfe_u32 v166, v114, 16, 1
	v_add3_u32 v114, v114, v166, v5
	v_bfe_u32 v166, v115, 16, 1
	v_add3_u32 v115, v115, v166, v5
	v_lshrrev_b32_e32 v112, 16, v112
	v_lshrrev_b32_e32 v114, 16, v114
	v_and_or_b32 v112, v113, v6, v112
	v_and_or_b32 v113, v115, v6, v114
	global_store_dwordx2 v3, v[112:113], s[18:19] offset:1024
	v_bfe_u32 v166, v116, 16, 1
	v_add3_u32 v116, v116, v166, v5
	v_bfe_u32 v166, v117, 16, 1
	v_add3_u32 v117, v117, v166, v5
; __device__ __forceinline__ unsigned pk2(float lo, float hi) { return f2bf(lo) | (f2bf(hi) << 16); }
; __device__ __forceinline__ void phase_prologue(const Params& p, LAS unsigned char* lds) {
;     ...
;           for (int u = 0; u < UR; ++u) { const int row = row0 + u * NGW; s[u] = 0.f;
; #pragma unroll
;               for (int j = 0; j < 8; ++j) s[u] += (v[u][j][0] * v[u][j][0] + v[u][j][1] * v[u][j][1]) + (v[u][j][2] * v[u][j][2] + v[u][j][3] * v[u][j][3]);
;               s[u] = wave_sum(s[u]); if (lane == 0) rstd[row] = 1.0f / sqrtf(s[u] * (1.0f / DM) + 1e-6f);
;               u32x2* o = (u32x2*)(xb + (size_t)row * DM) + lane;
; #pragma unroll
;               for (int j = 0; j < 8; ++j) { u32x2 w; w.x = pk2(v[u][j][0], v[u][j][1]); w.y = pk2(v[u][j][2], v[u][j][3]); o[64 * j] = w; } } } }
	v_bfe_u32 v166, v118, 16, 1
	v_add3_u32 v118, v118, v166, v5
	v_bfe_u32 v166, v119, 16, 1
	v_add3_u32 v119, v119, v166, v5
	v_lshrrev_b32_e32 v116, 16, v116
	v_lshrrev_b32_e32 v118, 16, v118
	v_and_or_b32 v116, v117, v6, v116
	v_and_or_b32 v117, v119, v6, v118
	global_store_dwordx2 v3, v[116:117], s[18:19] offset:1536
	v_bfe_u32 v166, v120, 16, 1
	v_add3_u32 v120, v120, v166, v5
	v_bfe_u32 v166, v121, 16, 1
	v_add3_u32 v121, v121, v166, v5
	v_bfe_u32 v166, v122, 16, 1
	v_add3_u32 v122, v122, v166, v5
	v_bfe_u32 v166, v123, 16, 1
	v_add3_u32 v123, v123, v166, v5
	v_lshrrev_b32_e32 v120, 16, v120
	v_lshrrev_b32_e32 v122, 16, v122
	v_and_or_b32 v120, v121, v6, v120
	v_and_or_b32 v121, v123, v6, v122
	global_store_dwordx2 v3, v[120:121], s[18:19] offset:2048
	v_bfe_u32 v166, v124, 16, 1
	v_add3_u32 v124, v124, v166, v5
	v_bfe_u32 v166, v125, 16, 1
	v_add3_u32 v125, v125, v166, v5
	v_bfe_u32 v166, v126, 16, 1
	v_add3_u32 v126, v126, v166, v5
	v_bfe_u32 v166, v127, 16, 1
	v_add3_u32 v127, v127, v166, v5
	v_lshrrev_b32_e32 v124, 16, v124
	v_lshrrev_b32_e32 v126, 16, v126
	v_and_or_b32 v124, v125, v6, v124
	v_and_or_b32 v125, v127, v6, v126
	global_store_dwordx2 v3, v[124:125], s[18:19] offset:2560
	v_bfe_u32 v166, v128, 16, 1
	v_add3_u32 v128, v128, v166, v5
	v_bfe_u32 v166, v129, 16, 1
	v_add3_u32 v129, v129, v166, v5
	v_bfe_u32 v166, v130, 16, 1
	v_add3_u32 v130, v130, v166, v5
	v_bfe_u32 v166, v131, 16, 1
	v_add3_u32 v131, v131, v166, v5
	v_lshrrev_b32_e32 v128, 16, v128
	v_lshrrev_b32_e32 v130, 16, v130
	v_and_or_b32 v128, v129, v6, v128
	v_and_or_b32 v129, v131, v6, v130
	global_store_dwordx2 v3, v[128:129], s[18:19] offset:3072
	v_bfe_u32 v166, v132, 16, 1
	v_add3_u32 v132, v132, v166, v5
	v_bfe_u32 v166, v133, 16, 1
	v_add3_u32 v133, v133, v166, v5
	v_bfe_u32 v166, v134, 16, 1
	v_add3_u32 v134, v134, v166, v5
	v_bfe_u32 v166, v135, 16, 1
	v_add3_u32 v135, v135, v166, v5
	v_lshrrev_b32_e32 v132, 16, v132
	v_lshrrev_b32_e32 v134, 16, v134
	v_and_or_b32 v132, v133, v6, v132
	v_and_or_b32 v133, v135, v6, v134
	global_store_dwordx2 v3, v[132:133], s[18:19] offset:3584
	s_mul_i32 s4, s5, 15
	s_add_u32 s4, s4, s3
	s_lshl_b32 s4, s4, 13
	s_add_u32 s14, s68, s4
	s_addc_u32 s15, s69, 0
	s_waitcnt vmcnt(52)
	global_load_dwordx4 v[104:107], v1, s[14:15] nt
	global_load_dwordx4 v[108:111], v1, s[14:15] offset:1024 nt
	global_load_dwordx4 v[112:115], v1, s[14:15] offset:2048 nt
	global_load_dwordx4 v[116:119], v1, s[14:15] offset:3072 nt
	global_load_dwordx4 v[120:123], v2, s[14:15] nt
	global_load_dwordx4 v[124:127], v2, s[14:15] offset:1024 nt
	global_load_dwordx4 v[128:131], v2, s[14:15] offset:2048 nt
	global_load_dwordx4 v[132:135], v2, s[14:15] offset:3072 nt
	s_waitcnt vmcnt(58)
	v_mul_f32_e32 v138, v9, v9
	v_mul_f32_e32 v139, v11, v11
	v_fmac_f32_e32 v138, v8, v8
	v_fmac_f32_e32 v139, v10, v10
	v_add_f32_e32 v140, v138, v139
	s_waitcnt vmcnt(57)
	v_mul_f32_e32 v138, v13, v13
	v_mul_f32_e32 v139, v15, v15
	v_fmac_f32_e32 v138, v12, v12
	v_fmac_f32_e32 v139, v14, v14
	v_add_f32_e32 v141, v138, v139
	v_add_f32_e32 v140, v140, v141
	s_waitcnt vmcnt(56)
	v_mul_f32_e32 v138, v17, v17
	v_mul_f32_e32 v139, v19, v19
	v_fmac_f32_e32 v138, v16, v16
	v_fmac_f32_e32 v139, v18, v18
	v_add_f32_e32 v141, v138, v139
	v_add_f32_e32 v140, v140, v141
	s_waitcnt vmcnt(55)
	v_mul_f32_e32 v138, v21, v21
	v_mul_f32_e32 v139, v23, v23
	v_fmac_f32_e32 v138, v20, v20
	v_fmac_f32_e32 v139, v22, v22
	v_add_f32_e32 v141, v138, v139
	v_add_f32_e32 v140, v140, v141
	s_waitcnt vmcnt(54)
	v_mul_f32_e32 v138, v25, v25
	v_mul_f32_e32 v139, v27, v27
	v_fmac_f32_e32 v138, v24, v24
	v_fmac_f32_e32 v139, v26, v26
	v_add_f32_e32 v141, v138, v139
	v_add_f32_e32 v140, v140, v141
	s_waitcnt vmcnt(53)
	v_mul_f32_e32 v138, v29, v29
	v_mul_f32_e32 v139, v31, v31
	v_fmac_f32_e32 v138, v28, v28
	v_fmac_f32_e32 v139, v30, v30
	v_add_f32_e32 v141, v138, v139
	v_add_f32_e32 v140, v140, v141
	s_waitcnt vmcnt(52)
	v_mul_f32_e32 v138, v33, v33
	v_mul_f32_e32 v139, v35, v35
	v_fmac_f32_e32 v138, v32, v32
	v_fmac_f32_e32 v139, v34, v34
	v_add_f32_e32 v141, v138, v139
	v_add_f32_e32 v140, v140, v141
	s_waitcnt vmcnt(51)
	v_mul_f32_e32 v138, v37, v37
	v_mul_f32_e32 v139, v39, v39
	v_fmac_f32_e32 v138, v36, v36
	v_fmac_f32_e32 v139, v38, v38
	v_add_f32_e32 v141, v138, v139
	v_add_f32_e32 v140, v140, v141
	s_nop 1
	v_add_f32_dpp v140, v140, v140 quad_perm:[1,0,3,2] row_mask:0xf bank_mask:0xf
	s_nop 1
	v_add_f32_dpp v140, v140, v140 quad_perm:[2,3,0,1] row_mask:0xf bank_mask:0xf
	s_nop 1
	v_add_f32_dpp v140, v140, v140 row_half_mirror row_mask:0xf bank_mask:0xf
	s_nop 1
	v_add_f32_dpp v140, v140, v140 row_mirror row_mask:0xf bank_mask:0xf
	s_nop 1
	v_readlane_b32 s38, v140, 0
	v_readlane_b32 s39, v140, 16
	v_readlane_b32 s52, v140, 32
	v_readlane_b32 s53, v140, 48
	s_nop 1
	v_mov_b32_e32 v161, s39
	v_mov_b32_e32 v163, s53
	v_add_f32_e32 v161, s38, v161
	v_add_f32_e32 v163, s52, v163
	v_add_f32_e32 v146, v161, v163
	v_fmamk_f32 v147, v146, 0x3a000000, v136
	v_mul_f32_e32 v148, 0x4f800000, v147
	v_cmp_gt_f32_e32 vcc, v7, v147
	s_nop 1
	v_cndmask_b32_e32 v149, v147, v148, vcc
	v_sqrt_f32_e32 v150, v149
	s_nop 0
	v_add_u32_e32 v151, -1, v150
	v_add_u32_e32 v152, 1, v150
	v_fma_f32 v153, -v151, v150, v149
	v_fma_f32 v154, -v152, v150, v149
	v_cmp_ge_f32_e64 s[0:1], 0, v153
	s_nop 1
	v_cndmask_b32_e64 v155, v150, v151, s[0:1]
	v_cmp_lt_f32_e64 s[0:1], 0, v154
	s_nop 1
	v_cndmask_b32_e64 v155, v155, v152, s[0:1]
	v_mul_f32_e32 v156, 0x37800000, v155
	v_cndmask_b32_e32 v155, v155, v156, vcc
	v_cmp_class_f32_e32 vcc, v149, v137
	s_nop 1
	v_cndmask_b32_e32 v157, v155, v149, vcc
	v_div_scale_f32 v158, s[0:1], v157, v157, 1.0
; __device__ __forceinline__ unsigned pk2(float lo, float hi) { return f2bf(lo) | (f2bf(hi) << 16); }
; __device__ __forceinline__ void phase_prologue(const Params& p, LAS unsigned char* lds) {
;     ...
;           for (int u = 0; u < UR; ++u) { const int row = row0 + u * NGW; s[u] = 0.f;
; #pragma unroll
;               for (int j = 0; j < 8; ++j) s[u] += (v[u][j][0] * v[u][j][0] + v[u][j][1] * v[u][j][1]) + (v[u][j][2] * v[u][j][2] + v[u][j][3] * v[u][j][3]);
;               s[u] = wave_sum(s[u]); if (lane == 0) rstd[row] = 1.0f / sqrtf(s[u] * (1.0f / DM) + 1e-6f);
;               u32x2* o = (u32x2*)(xb + (size_t)row * DM) + lane;
; #pragma unroll
;               for (int j = 0; j < 8; ++j) { u32x2 w; w.x = pk2(v[u][j][0], v[u][j][1]); w.y = pk2(v[u][j][2], v[u][j][3]); o[64 * j] = w; } } } }
	v_rcp_f32_e32 v159, v158
	v_div_scale_f32 v160, vcc, 1.0, v157, 1.0
	v_fma_f32 v161, -v158, v159, 1.0
	v_fmac_f32_e32 v159, v161, v159
	v_mul_f32_e32 v162, v160, v159
	v_fma_f32 v163, -v158, v162, v160
	v_fmac_f32_e32 v162, v163, v159
	v_fma_f32 v161, -v158, v162, v160
	v_div_fmas_f32 v164, v161, v159, v162
	v_div_fixup_f32 v165, v164, v157, 1.0
	s_mul_i32 s4, s5, 12
	s_add_u32 s4, s4, s3
	s_lshl_b32 s33, s4, 2
	s_add_u32 s36, s28, s33
	s_addc_u32 s37, s29, 0
	s_add_u32 s36, s36, 0x7c00000
	s_addc_u32 s37, s37, 0
	s_lshl_b32 s33, s4, 12
	s_add_u32 s16, s28, s33
	s_addc_u32 s17, s29, 0
	s_add_u32 s16, s16, 0x8800000
	s_addc_u32 s17, s17, 0
	s_mov_b64 exec, 1
	global_store_dword v4, v165, s[36:37]
	s_mov_b64 exec, -1
	v_bfe_u32 v166, v8, 16, 1
	v_add3_u32 v8, v8, v166, v5
	v_bfe_u32 v166, v9, 16, 1
	v_add3_u32 v9, v9, v166, v5
	v_bfe_u32 v166, v10, 16, 1
	v_add3_u32 v10, v10, v166, v5
	v_bfe_u32 v166, v11, 16, 1
	v_add3_u32 v11, v11, v166, v5
	v_lshrrev_b32_e32 v8, 16, v8
	v_lshrrev_b32_e32 v10, 16, v10
	v_and_or_b32 v8, v9, v6, v8
	v_and_or_b32 v9, v11, v6, v10
	global_store_dwordx2 v3, v[8:9], s[16:17]
	v_bfe_u32 v166, v12, 16, 1
	v_add3_u32 v12, v12, v166, v5
	v_bfe_u32 v166, v13, 16, 1
	v_add3_u32 v13, v13, v166, v5
	v_bfe_u32 v166, v14, 16, 1
	v_add3_u32 v14, v14, v166, v5
	v_bfe_u32 v166, v15, 16, 1
	v_add3_u32 v15, v15, v166, v5
	v_lshrrev_b32_e32 v12, 16, v12
	v_lshrrev_b32_e32 v14, 16, v14
	v_and_or_b32 v12, v13, v6, v12
	v_and_or_b32 v13, v15, v6, v14
	global_store_dwordx2 v3, v[12:13], s[16:17] offset:512
	v_bfe_u32 v166, v16, 16, 1
	v_add3_u32 v16, v16, v166, v5
	v_bfe_u32 v166, v17, 16, 1
	v_add3_u32 v17, v17, v166, v5
	v_bfe_u32 v166, v18, 16, 1
	v_add3_u32 v18, v18, v166, v5
	v_bfe_u32 v166, v19, 16, 1
	v_add3_u32 v19, v19, v166, v5
	v_lshrrev_b32_e32 v16, 16, v16
	v_lshrrev_b32_e32 v18, 16, v18
	v_and_or_b32 v16, v17, v6, v16
	v_and_or_b32 v17, v19, v6, v18
	global_store_dwordx2 v3, v[16:17], s[16:17] offset:1024
	v_bfe_u32 v166, v20, 16, 1
	v_add3_u32 v20, v20, v166, v5
	v_bfe_u32 v166, v21, 16, 1
	v_add3_u32 v21, v21, v166, v5
	v_bfe_u32 v166, v22, 16, 1
	v_add3_u32 v22, v22, v166, v5
	v_bfe_u32 v166, v23, 16, 1
	v_add3_u32 v23, v23, v166, v5
	v_lshrrev_b32_e32 v20, 16, v20
	v_lshrrev_b32_e32 v22, 16, v22
	v_and_or_b32 v20, v21, v6, v20
	v_and_or_b32 v21, v23, v6, v22
	global_store_dwordx2 v3, v[20:21], s[16:17] offset:1536
	v_bfe_u32 v166, v24, 16, 1
	v_add3_u32 v24, v24, v166, v5
	v_bfe_u32 v166, v25, 16, 1
	v_add3_u32 v25, v25, v166, v5
	v_bfe_u32 v166, v26, 16, 1
	v_add3_u32 v26, v26, v166, v5
	v_bfe_u32 v166, v27, 16, 1
	v_add3_u32 v27, v27, v166, v5
	v_lshrrev_b32_e32 v24, 16, v24
	v_lshrrev_b32_e32 v26, 16, v26
	v_and_or_b32 v24, v25, v6, v24
	v_and_or_b32 v25, v27, v6, v26
	global_store_dwordx2 v3, v[24:25], s[16:17] offset:2048
	v_bfe_u32 v166, v28, 16, 1
	v_add3_u32 v28, v28, v166, v5
	v_bfe_u32 v166, v29, 16, 1
	v_add3_u32 v29, v29, v166, v5
	v_bfe_u32 v166, v30, 16, 1
	v_add3_u32 v30, v30, v166, v5
	v_bfe_u32 v166, v31, 16, 1
	v_add3_u32 v31, v31, v166, v5
	v_lshrrev_b32_e32 v28, 16, v28
	v_lshrrev_b32_e32 v30, 16, v30
	v_and_or_b32 v28, v29, v6, v28
	v_and_or_b32 v29, v31, v6, v30
	global_store_dwordx2 v3, v[28:29], s[16:17] offset:2560
	v_bfe_u32 v166, v32, 16, 1
	v_add3_u32 v32, v32, v166, v5
	v_bfe_u32 v166, v33, 16, 1
	v_add3_u32 v33, v33, v166, v5
	v_bfe_u32 v166, v34, 16, 1
	v_add3_u32 v34, v34, v166, v5
	v_bfe_u32 v166, v35, 16, 1
	v_add3_u32 v35, v35, v166, v5
	v_lshrrev_b32_e32 v32, 16, v32
	v_lshrrev_b32_e32 v34, 16, v34
	v_and_or_b32 v32, v33, v6, v32
	v_and_or_b32 v33, v35, v6, v34
	global_store_dwordx2 v3, v[32:33], s[16:17] offset:3072
	v_bfe_u32 v166, v36, 16, 1
	v_add3_u32 v36, v36, v166, v5
	v_bfe_u32 v166, v37, 16, 1
	v_add3_u32 v37, v37, v166, v5
	v_bfe_u32 v166, v38, 16, 1
	v_add3_u32 v38, v38, v166, v5
	v_bfe_u32 v166, v39, 16, 1
	v_add3_u32 v39, v39, v166, v5
	v_lshrrev_b32_e32 v36, 16, v36
	v_lshrrev_b32_e32 v38, 16, v38
	v_and_or_b32 v36, v37, v6, v36
	v_and_or_b32 v37, v39, v6, v38
	global_store_dwordx2 v3, v[36:37], s[16:17] offset:3584
	s_waitcnt vmcnt(50)
	v_mul_f32_e32 v138, v41, v41
	v_mul_f32_e32 v139, v43, v43
	v_fmac_f32_e32 v138, v40, v40
	v_fmac_f32_e32 v139, v42, v42
	v_add_f32_e32 v140, v138, v139
	s_waitcnt vmcnt(49)
	v_mul_f32_e32 v138, v45, v45
	v_mul_f32_e32 v139, v47, v47
	v_fmac_f32_e32 v138, v44, v44
	v_fmac_f32_e32 v139, v46, v46
	v_add_f32_e32 v141, v138, v139
	v_add_f32_e32 v140, v140, v141
	s_waitcnt vmcnt(48)
	v_mul_f32_e32 v138, v49, v49
	v_mul_f32_e32 v139, v51, v51
	v_fmac_f32_e32 v138, v48, v48
	v_fmac_f32_e32 v139, v50, v50
	v_add_f32_e32 v141, v138, v139
	v_add_f32_e32 v140, v140, v141
	s_waitcnt vmcnt(47)
	v_mul_f32_e32 v138, v53, v53
	v_mul_f32_e32 v139, v55, v55
	v_fmac_f32_e32 v138, v52, v52
	v_fmac_f32_e32 v139, v54, v54
	v_add_f32_e32 v141, v138, v139
	v_add_f32_e32 v140, v140, v141
	s_waitcnt vmcnt(46)
	v_mul_f32_e32 v138, v57, v57
	v_mul_f32_e32 v139, v59, v59
	v_fmac_f32_e32 v138, v56, v56
	v_fmac_f32_e32 v139, v58, v58
	v_add_f32_e32 v141, v138, v139
	v_add_f32_e32 v140, v140, v141
	s_waitcnt vmcnt(45)
	v_mul_f32_e32 v138, v61, v61
	v_mul_f32_e32 v139, v63, v63
	v_fmac_f32_e32 v138, v60, v60
	v_fmac_f32_e32 v139, v62, v62
	v_add_f32_e32 v141, v138, v139
	v_add_f32_e32 v140, v140, v141
	s_waitcnt vmcnt(44)
	v_mul_f32_e32 v138, v65, v65
	v_mul_f32_e32 v139, v67, v67
	v_fmac_f32_e32 v138, v64, v64
	v_fmac_f32_e32 v139, v66, v66
	v_add_f32_e32 v141, v138, v139
	v_add_f32_e32 v140, v140, v141
	s_waitcnt vmcnt(43)
; __device__ __forceinline__ unsigned pk2(float lo, float hi) { return f2bf(lo) | (f2bf(hi) << 16); }
; __device__ __forceinline__ void phase_prologue(const Params& p, LAS unsigned char* lds) {
;     ...
;           for (int u = 0; u < UR; ++u) { const int row = row0 + u * NGW; s[u] = 0.f;
; #pragma unroll
;               for (int j = 0; j < 8; ++j) s[u] += (v[u][j][0] * v[u][j][0] + v[u][j][1] * v[u][j][1]) + (v[u][j][2] * v[u][j][2] + v[u][j][3] * v[u][j][3]);
;               s[u] = wave_sum(s[u]); if (lane == 0) rstd[row] = 1.0f / sqrtf(s[u] * (1.0f / DM) + 1e-6f);
;               u32x2* o = (u32x2*)(xb + (size_t)row * DM) + lane;
; #pragma unroll
;               for (int j = 0; j < 8; ++j) { u32x2 w; w.x = pk2(v[u][j][0], v[u][j][1]); w.y = pk2(v[u][j][2], v[u][j][3]); o[64 * j] = w; } } } }
	v_mul_f32_e32 v138, v69, v69
	v_mul_f32_e32 v139, v71, v71
	v_fmac_f32_e32 v138, v68, v68
	v_fmac_f32_e32 v139, v70, v70
	v_add_f32_e32 v141, v138, v139
	v_add_f32_e32 v140, v140, v141
	s_nop 1
	v_add_f32_dpp v140, v140, v140 quad_perm:[1,0,3,2] row_mask:0xf bank_mask:0xf
	s_nop 1
	v_add_f32_dpp v140, v140, v140 quad_perm:[2,3,0,1] row_mask:0xf bank_mask:0xf
	s_nop 1
	v_add_f32_dpp v140, v140, v140 row_half_mirror row_mask:0xf bank_mask:0xf
	s_nop 1
	v_add_f32_dpp v140, v140, v140 row_mirror row_mask:0xf bank_mask:0xf
	s_nop 1
	v_readlane_b32 s38, v140, 0
	v_readlane_b32 s39, v140, 16
	v_readlane_b32 s52, v140, 32
	v_readlane_b32 s53, v140, 48
	s_nop 1
	v_mov_b32_e32 v161, s39
	v_mov_b32_e32 v163, s53
	v_add_f32_e32 v161, s38, v161
	v_add_f32_e32 v163, s52, v163
	v_add_f32_e32 v146, v161, v163
	v_fmamk_f32 v147, v146, 0x3a000000, v136
	v_mul_f32_e32 v148, 0x4f800000, v147
	v_cmp_gt_f32_e32 vcc, v7, v147
	s_nop 1
	v_cndmask_b32_e32 v149, v147, v148, vcc
	v_sqrt_f32_e32 v150, v149
	s_nop 0
	v_add_u32_e32 v151, -1, v150
	v_add_u32_e32 v152, 1, v150
	v_fma_f32 v153, -v151, v150, v149
	v_fma_f32 v154, -v152, v150, v149
	v_cmp_ge_f32_e64 s[0:1], 0, v153
	s_nop 1
	v_cndmask_b32_e64 v155, v150, v151, s[0:1]
	v_cmp_lt_f32_e64 s[0:1], 0, v154
	s_nop 1
	v_cndmask_b32_e64 v155, v155, v152, s[0:1]
	v_mul_f32_e32 v156, 0x37800000, v155
	v_cndmask_b32_e32 v155, v155, v156, vcc
	v_cmp_class_f32_e32 vcc, v149, v137
	s_nop 1
	v_cndmask_b32_e32 v157, v155, v149, vcc
	v_div_scale_f32 v158, s[0:1], v157, v157, 1.0
	v_rcp_f32_e32 v159, v158
	v_div_scale_f32 v160, vcc, 1.0, v157, 1.0
	v_fma_f32 v161, -v158, v159, 1.0
	v_fmac_f32_e32 v159, v161, v159
	v_mul_f32_e32 v162, v160, v159
	v_fma_f32 v163, -v158, v162, v160
	v_fmac_f32_e32 v162, v163, v159
	v_fma_f32 v161, -v158, v162, v160
	v_div_fmas_f32 v164, v161, v159, v162
	v_div_fixup_f32 v165, v164, v157, 1.0
	s_mul_i32 s4, s5, 13
	s_add_u32 s4, s4, s3
	s_lshl_b32 s33, s4, 2
	s_add_u32 s36, s28, s33
	s_addc_u32 s37, s29, 0
	s_add_u32 s36, s36, 0x7c00000
	s_addc_u32 s37, s37, 0
	s_lshl_b32 s33, s4, 12
	s_add_u32 s18, s28, s33
	s_addc_u32 s19, s29, 0
	s_add_u32 s18, s18, 0x8800000
	s_addc_u32 s19, s19, 0
	s_mov_b64 exec, 1
	global_store_dword v4, v165, s[36:37]
	s_mov_b64 exec, -1
	v_bfe_u32 v166, v40, 16, 1
	v_add3_u32 v40, v40, v166, v5
	v_bfe_u32 v166, v41, 16, 1
	v_add3_u32 v41, v41, v166, v5
	v_bfe_u32 v166, v42, 16, 1
	v_add3_u32 v42, v42, v166, v5
	v_bfe_u32 v166, v43, 16, 1
	v_add3_u32 v43, v43, v166, v5
	v_lshrrev_b32_e32 v40, 16, v40
	v_lshrrev_b32_e32 v42, 16, v42
	v_and_or_b32 v40, v41, v6, v40
	v_and_or_b32 v41, v43, v6, v42
	global_store_dwordx2 v3, v[40:41], s[18:19]
	v_bfe_u32 v166, v44, 16, 1
	v_add3_u32 v44, v44, v166, v5
	v_bfe_u32 v166, v45, 16, 1
	v_add3_u32 v45, v45, v166, v5
	v_bfe_u32 v166, v46, 16, 1
	v_add3_u32 v46, v46, v166, v5
	v_bfe_u32 v166, v47, 16, 1
	v_add3_u32 v47, v47, v166, v5
	v_lshrrev_b32_e32 v44, 16, v44
	v_lshrrev_b32_e32 v46, 16, v46
	v_and_or_b32 v44, v45, v6, v44
	v_and_or_b32 v45, v47, v6, v46
	global_store_dwordx2 v3, v[44:45], s[18:19] offset:512
	v_bfe_u32 v166, v48, 16, 1
	v_add3_u32 v48, v48, v166, v5
	v_bfe_u32 v166, v49, 16, 1
	v_add3_u32 v49, v49, v166, v5
	v_bfe_u32 v166, v50, 16, 1
	v_add3_u32 v50, v50, v166, v5
	v_bfe_u32 v166, v51, 16, 1
	v_add3_u32 v51, v51, v166, v5
	v_lshrrev_b32_e32 v48, 16, v48
	v_lshrrev_b32_e32 v50, 16, v50
	v_and_or_b32 v48, v49, v6, v48
	v_and_or_b32 v49, v51, v6, v50
	global_store_dwordx2 v3, v[48:49], s[18:19] offset:1024
	v_bfe_u32 v166, v52, 16, 1
	v_add3_u32 v52, v52, v166, v5
	v_bfe_u32 v166, v53, 16, 1
	v_add3_u32 v53, v53, v166, v5
	v_bfe_u32 v166, v54, 16, 1
	v_add3_u32 v54, v54, v166, v5
	v_bfe_u32 v166, v55, 16, 1
	v_add3_u32 v55, v55, v166, v5
	v_lshrrev_b32_e32 v52, 16, v52
	v_lshrrev_b32_e32 v54, 16, v54
	v_and_or_b32 v52, v53, v6, v52
	v_and_or_b32 v53, v55, v6, v54
	global_store_dwordx2 v3, v[52:53], s[18:19] offset:1536
	v_bfe_u32 v166, v56, 16, 1
	v_add3_u32 v56, v56, v166, v5
	v_bfe_u32 v166, v57, 16, 1
	v_add3_u32 v57, v57, v166, v5
	v_bfe_u32 v166, v58, 16, 1
	v_add3_u32 v58, v58, v166, v5
	v_bfe_u32 v166, v59, 16, 1
	v_add3_u32 v59, v59, v166, v5
	v_lshrrev_b32_e32 v56, 16, v56
	v_lshrrev_b32_e32 v58, 16, v58
	v_and_or_b32 v56, v57, v6, v56
	v_and_or_b32 v57, v59, v6, v58
	global_store_dwordx2 v3, v[56:57], s[18:19] offset:2048
	v_bfe_u32 v166, v60, 16, 1
	v_add3_u32 v60, v60, v166, v5
	v_bfe_u32 v166, v61, 16, 1
	v_add3_u32 v61, v61, v166, v5
	v_bfe_u32 v166, v62, 16, 1
	v_add3_u32 v62, v62, v166, v5
	v_bfe_u32 v166, v63, 16, 1
	v_add3_u32 v63, v63, v166, v5
	v_lshrrev_b32_e32 v60, 16, v60
	v_lshrrev_b32_e32 v62, 16, v62
	v_and_or_b32 v60, v61, v6, v60
	v_and_or_b32 v61, v63, v6, v62
	global_store_dwordx2 v3, v[60:61], s[18:19] offset:2560
	v_bfe_u32 v166, v64, 16, 1
	v_add3_u32 v64, v64, v166, v5
	v_bfe_u32 v166, v65, 16, 1
	v_add3_u32 v65, v65, v166, v5
	v_bfe_u32 v166, v66, 16, 1
	v_add3_u32 v66, v66, v166, v5
	v_bfe_u32 v166, v67, 16, 1
	v_add3_u32 v67, v67, v166, v5
	v_lshrrev_b32_e32 v64, 16, v64
	v_lshrrev_b32_e32 v66, 16, v66
	v_and_or_b32 v64, v65, v6, v64
	v_and_or_b32 v65, v67, v6, v66
	global_store_dwordx2 v3, v[64:65], s[18:19] offset:3072
	v_bfe_u32 v166, v68, 16, 1
	v_add3_u32 v68, v68, v166, v5
	v_bfe_u32 v166, v69, 16, 1
	v_add3_u32 v69, v69, v166, v5
	v_bfe_u32 v166, v70, 16, 1
	v_add3_u32 v70, v70, v166, v5
	v_bfe_u32 v166, v71, 16, 1
	v_add3_u32 v71, v71, v166, v5
	v_lshrrev_b32_e32 v68, 16, v68
	v_lshrrev_b32_e32 v70, 16, v70
	v_and_or_b32 v68, v69, v6, v68
	v_and_or_b32 v69, v71, v6, v70
	global_store_dwordx2 v3, v[68:69], s[18:19] offset:3584
	s_waitcnt vmcnt(42)
; __device__ __forceinline__ unsigned pk2(float lo, float hi) { return f2bf(lo) | (f2bf(hi) << 16); }
; __device__ __forceinline__ void phase_prologue(const Params& p, LAS unsigned char* lds) {
;     ...
;           for (int u = 0; u < UR; ++u) { const int row = row0 + u * NGW; s[u] = 0.f;
; #pragma unroll
;               for (int j = 0; j < 8; ++j) s[u] += (v[u][j][0] * v[u][j][0] + v[u][j][1] * v[u][j][1]) + (v[u][j][2] * v[u][j][2] + v[u][j][3] * v[u][j][3]);
;               s[u] = wave_sum(s[u]); if (lane == 0) rstd[row] = 1.0f / sqrtf(s[u] * (1.0f / DM) + 1e-6f);
;               u32x2* o = (u32x2*)(xb + (size_t)row * DM) + lane;
; #pragma unroll
;               for (int j = 0; j < 8; ++j) { u32x2 w; w.x = pk2(v[u][j][0], v[u][j][1]); w.y = pk2(v[u][j][2], v[u][j][3]); o[64 * j] = w; } } } }
	v_mul_f32_e32 v138, v73, v73
	v_mul_f32_e32 v139, v75, v75
	v_fmac_f32_e32 v138, v72, v72
	v_fmac_f32_e32 v139, v74, v74
	v_add_f32_e32 v140, v138, v139
	s_waitcnt vmcnt(41)
	v_mul_f32_e32 v138, v77, v77
	v_mul_f32_e32 v139, v79, v79
	v_fmac_f32_e32 v138, v76, v76
	v_fmac_f32_e32 v139, v78, v78
	v_add_f32_e32 v141, v138, v139
	v_add_f32_e32 v140, v140, v141
	s_waitcnt vmcnt(40)
	v_mul_f32_e32 v138, v81, v81
	v_mul_f32_e32 v139, v83, v83
	v_fmac_f32_e32 v138, v80, v80
	v_fmac_f32_e32 v139, v82, v82
	v_add_f32_e32 v141, v138, v139
	v_add_f32_e32 v140, v140, v141
	s_waitcnt vmcnt(39)
	v_mul_f32_e32 v138, v85, v85
	v_mul_f32_e32 v139, v87, v87
	v_fmac_f32_e32 v138, v84, v84
	v_fmac_f32_e32 v139, v86, v86
	v_add_f32_e32 v141, v138, v139
	v_add_f32_e32 v140, v140, v141
	s_waitcnt vmcnt(38)
	v_mul_f32_e32 v138, v89, v89
	v_mul_f32_e32 v139, v91, v91
	v_fmac_f32_e32 v138, v88, v88
	v_fmac_f32_e32 v139, v90, v90
	v_add_f32_e32 v141, v138, v139
	v_add_f32_e32 v140, v140, v141
	s_waitcnt vmcnt(37)
	v_mul_f32_e32 v138, v93, v93
	v_mul_f32_e32 v139, v95, v95
	v_fmac_f32_e32 v138, v92, v92
	v_fmac_f32_e32 v139, v94, v94
	v_add_f32_e32 v141, v138, v139
	v_add_f32_e32 v140, v140, v141
	s_waitcnt vmcnt(36)
	v_mul_f32_e32 v138, v97, v97
	v_mul_f32_e32 v139, v99, v99
	v_fmac_f32_e32 v138, v96, v96
	v_fmac_f32_e32 v139, v98, v98
	v_add_f32_e32 v141, v138, v139
	v_add_f32_e32 v140, v140, v141
	s_waitcnt vmcnt(35)
	v_mul_f32_e32 v138, v101, v101
	v_mul_f32_e32 v139, v103, v103
	v_fmac_f32_e32 v138, v100, v100
	v_fmac_f32_e32 v139, v102, v102
	v_add_f32_e32 v141, v138, v139
	v_add_f32_e32 v140, v140, v141
	s_nop 1
	v_add_f32_dpp v140, v140, v140 quad_perm:[1,0,3,2] row_mask:0xf bank_mask:0xf
	s_nop 1
	v_add_f32_dpp v140, v140, v140 quad_perm:[2,3,0,1] row_mask:0xf bank_mask:0xf
	s_nop 1
	v_add_f32_dpp v140, v140, v140 row_half_mirror row_mask:0xf bank_mask:0xf
	s_nop 1
	v_add_f32_dpp v140, v140, v140 row_mirror row_mask:0xf bank_mask:0xf
	s_nop 1
	v_readlane_b32 s38, v140, 0
	v_readlane_b32 s39, v140, 16
	v_readlane_b32 s52, v140, 32
	v_readlane_b32 s53, v140, 48
	s_nop 1
	v_mov_b32_e32 v161, s39
	v_mov_b32_e32 v163, s53
	v_add_f32_e32 v161, s38, v161
	v_add_f32_e32 v163, s52, v163
	v_add_f32_e32 v146, v161, v163
	v_fmamk_f32 v147, v146, 0x3a000000, v136
	v_mul_f32_e32 v148, 0x4f800000, v147
	v_cmp_gt_f32_e32 vcc, v7, v147
	s_nop 1
	v_cndmask_b32_e32 v149, v147, v148, vcc
	v_sqrt_f32_e32 v150, v149
	s_nop 0
	v_add_u32_e32 v151, -1, v150
	v_add_u32_e32 v152, 1, v150
	v_fma_f32 v153, -v151, v150, v149
	v_fma_f32 v154, -v152, v150, v149
	v_cmp_ge_f32_e64 s[0:1], 0, v153
	s_nop 1
	v_cndmask_b32_e64 v155, v150, v151, s[0:1]
	v_cmp_lt_f32_e64 s[0:1], 0, v154
	s_nop 1
	v_cndmask_b32_e64 v155, v155, v152, s[0:1]
	v_mul_f32_e32 v156, 0x37800000, v155
	v_cndmask_b32_e32 v155, v155, v156, vcc
	v_cmp_class_f32_e32 vcc, v149, v137
	s_nop 1
	v_cndmask_b32_e32 v157, v155, v149, vcc
	v_div_scale_f32 v158, s[0:1], v157, v157, 1.0
	v_rcp_f32_e32 v159, v158
	v_div_scale_f32 v160, vcc, 1.0, v157, 1.0
	v_fma_f32 v161, -v158, v159, 1.0
	v_fmac_f32_e32 v159, v161, v159
	v_mul_f32_e32 v162, v160, v159
	v_fma_f32 v163, -v158, v162, v160
	v_fmac_f32_e32 v162, v163, v159
	v_fma_f32 v161, -v158, v162, v160
	v_div_fmas_f32 v164, v161, v159, v162
	v_div_fixup_f32 v165, v164, v157, 1.0
	s_mul_i32 s4, s5, 14
	s_add_u32 s4, s4, s3
	s_lshl_b32 s33, s4, 2
	s_add_u32 s36, s28, s33
	s_addc_u32 s37, s29, 0
	s_add_u32 s36, s36, 0x7c00000
	s_addc_u32 s37, s37, 0
	s_lshl_b32 s33, s4, 12
	s_add_u32 s16, s28, s33
	s_addc_u32 s17, s29, 0
	s_add_u32 s16, s16, 0x8800000
	s_addc_u32 s17, s17, 0
	s_mov_b64 exec, 1
	global_store_dword v4, v165, s[36:37]
	s_mov_b64 exec, -1
	v_bfe_u32 v166, v72, 16, 1
	v_add3_u32 v72, v72, v166, v5
	v_bfe_u32 v166, v73, 16, 1
	v_add3_u32 v73, v73, v166, v5
	v_bfe_u32 v166, v74, 16, 1
	v_add3_u32 v74, v74, v166, v5
	v_bfe_u32 v166, v75, 16, 1
	v_add3_u32 v75, v75, v166, v5
	v_lshrrev_b32_e32 v72, 16, v72
	v_lshrrev_b32_e32 v74, 16, v74
	v_and_or_b32 v72, v73, v6, v72
	v_and_or_b32 v73, v75, v6, v74
	global_store_dwordx2 v3, v[72:73], s[16:17]
	v_bfe_u32 v166, v76, 16, 1
	v_add3_u32 v76, v76, v166, v5
	v_bfe_u32 v166, v77, 16, 1
	v_add3_u32 v77, v77, v166, v5
	v_bfe_u32 v166, v78, 16, 1
	v_add3_u32 v78, v78, v166, v5
	v_bfe_u32 v166, v79, 16, 1
	v_add3_u32 v79, v79, v166, v5
	v_lshrrev_b32_e32 v76, 16, v76
	v_lshrrev_b32_e32 v78, 16, v78
	v_and_or_b32 v76, v77, v6, v76
	v_and_or_b32 v77, v79, v6, v78
	global_store_dwordx2 v3, v[76:77], s[16:17] offset:512
	v_bfe_u32 v166, v80, 16, 1
	v_add3_u32 v80, v80, v166, v5
	v_bfe_u32 v166, v81, 16, 1
	v_add3_u32 v81, v81, v166, v5
	v_bfe_u32 v166, v82, 16, 1
	v_add3_u32 v82, v82, v166, v5
	v_bfe_u32 v166, v83, 16, 1
	v_add3_u32 v83, v83, v166, v5
	v_lshrrev_b32_e32 v80, 16, v80
	v_lshrrev_b32_e32 v82, 16, v82
	v_and_or_b32 v80, v81, v6, v80
	v_and_or_b32 v81, v83, v6, v82
	global_store_dwordx2 v3, v[80:81], s[16:17] offset:1024
	v_bfe_u32 v166, v84, 16, 1
	v_add3_u32 v84, v84, v166, v5
	v_bfe_u32 v166, v85, 16, 1
	v_add3_u32 v85, v85, v166, v5
	v_bfe_u32 v166, v86, 16, 1
	v_add3_u32 v86, v86, v166, v5
	v_bfe_u32 v166, v87, 16, 1
	v_add3_u32 v87, v87, v166, v5
	v_lshrrev_b32_e32 v84, 16, v84
	v_lshrrev_b32_e32 v86, 16, v86
	v_and_or_b32 v84, v85, v6, v84
	v_and_or_b32 v85, v87, v6, v86
	global_store_dwordx2 v3, v[84:85], s[16:17] offset:1536
	v_bfe_u32 v166, v88, 16, 1
	v_add3_u32 v88, v88, v166, v5
	v_bfe_u32 v166, v89, 16, 1
	v_add3_u32 v89, v89, v166, v5
	v_bfe_u32 v166, v90, 16, 1
	v_add3_u32 v90, v90, v166, v5
	v_bfe_u32 v166, v91, 16, 1
	v_add3_u32 v91, v91, v166, v5
	v_lshrrev_b32_e32 v88, 16, v88
	v_lshrrev_b32_e32 v90, 16, v90
; __device__ __forceinline__ unsigned pk2(float lo, float hi) { return f2bf(lo) | (f2bf(hi) << 16); }
; __device__ __forceinline__ void phase_prologue(const Params& p, LAS unsigned char* lds) {
;     ...
;           for (int u = 0; u < UR; ++u) { const int row = row0 + u * NGW; s[u] = 0.f;
; #pragma unroll
;               for (int j = 0; j < 8; ++j) s[u] += (v[u][j][0] * v[u][j][0] + v[u][j][1] * v[u][j][1]) + (v[u][j][2] * v[u][j][2] + v[u][j][3] * v[u][j][3]);
;               s[u] = wave_sum(s[u]); if (lane == 0) rstd[row] = 1.0f / sqrtf(s[u] * (1.0f / DM) + 1e-6f);
;               u32x2* o = (u32x2*)(xb + (size_t)row * DM) + lane;
; #pragma unroll
;               for (int j = 0; j < 8; ++j) { u32x2 w; w.x = pk2(v[u][j][0], v[u][j][1]); w.y = pk2(v[u][j][2], v[u][j][3]); o[64 * j] = w; } } } }
	v_and_or_b32 v88, v89, v6, v88
	v_and_or_b32 v89, v91, v6, v90
	global_store_dwordx2 v3, v[88:89], s[16:17] offset:2048
	v_bfe_u32 v166, v92, 16, 1
	v_add3_u32 v92, v92, v166, v5
	v_bfe_u32 v166, v93, 16, 1
	v_add3_u32 v93, v93, v166, v5
	v_bfe_u32 v166, v94, 16, 1
	v_add3_u32 v94, v94, v166, v5
	v_bfe_u32 v166, v95, 16, 1
	v_add3_u32 v95, v95, v166, v5
	v_lshrrev_b32_e32 v92, 16, v92
	v_lshrrev_b32_e32 v94, 16, v94
	v_and_or_b32 v92, v93, v6, v92
	v_and_or_b32 v93, v95, v6, v94
	global_store_dwordx2 v3, v[92:93], s[16:17] offset:2560
	v_bfe_u32 v166, v96, 16, 1
	v_add3_u32 v96, v96, v166, v5
	v_bfe_u32 v166, v97, 16, 1
	v_add3_u32 v97, v97, v166, v5
	v_bfe_u32 v166, v98, 16, 1
	v_add3_u32 v98, v98, v166, v5
	v_bfe_u32 v166, v99, 16, 1
	v_add3_u32 v99, v99, v166, v5
	v_lshrrev_b32_e32 v96, 16, v96
	v_lshrrev_b32_e32 v98, 16, v98
	v_and_or_b32 v96, v97, v6, v96
	v_and_or_b32 v97, v99, v6, v98
	global_store_dwordx2 v3, v[96:97], s[16:17] offset:3072
	v_bfe_u32 v166, v100, 16, 1
	v_add3_u32 v100, v100, v166, v5
	v_bfe_u32 v166, v101, 16, 1
	v_add3_u32 v101, v101, v166, v5
	v_bfe_u32 v166, v102, 16, 1
	v_add3_u32 v102, v102, v166, v5
	v_bfe_u32 v166, v103, 16, 1
	v_add3_u32 v103, v103, v166, v5
	v_lshrrev_b32_e32 v100, 16, v100
	v_lshrrev_b32_e32 v102, 16, v102
	v_and_or_b32 v100, v101, v6, v100
	v_and_or_b32 v101, v103, v6, v102
	global_store_dwordx2 v3, v[100:101], s[16:17] offset:3584
	s_waitcnt vmcnt(34)
	v_mul_f32_e32 v138, v105, v105
	v_mul_f32_e32 v139, v107, v107
	v_fmac_f32_e32 v138, v104, v104
	v_fmac_f32_e32 v139, v106, v106
	v_add_f32_e32 v140, v138, v139
	s_waitcnt vmcnt(33)
	v_mul_f32_e32 v138, v109, v109
	v_mul_f32_e32 v139, v111, v111
	v_fmac_f32_e32 v138, v108, v108
	v_fmac_f32_e32 v139, v110, v110
	v_add_f32_e32 v141, v138, v139
	v_add_f32_e32 v140, v140, v141
	s_waitcnt vmcnt(32)
	v_mul_f32_e32 v138, v113, v113
	v_mul_f32_e32 v139, v115, v115
	v_fmac_f32_e32 v138, v112, v112
	v_fmac_f32_e32 v139, v114, v114
	v_add_f32_e32 v141, v138, v139
	v_add_f32_e32 v140, v140, v141
	s_waitcnt vmcnt(31)
	v_mul_f32_e32 v138, v117, v117
	v_mul_f32_e32 v139, v119, v119
	v_fmac_f32_e32 v138, v116, v116
	v_fmac_f32_e32 v139, v118, v118
	v_add_f32_e32 v141, v138, v139
	v_add_f32_e32 v140, v140, v141
	s_waitcnt vmcnt(30)
	v_mul_f32_e32 v138, v121, v121
	v_mul_f32_e32 v139, v123, v123
	v_fmac_f32_e32 v138, v120, v120
	v_fmac_f32_e32 v139, v122, v122
	v_add_f32_e32 v141, v138, v139
	v_add_f32_e32 v140, v140, v141
	s_waitcnt vmcnt(29)
	v_mul_f32_e32 v138, v125, v125
	v_mul_f32_e32 v139, v127, v127
	v_fmac_f32_e32 v138, v124, v124
	v_fmac_f32_e32 v139, v126, v126
	v_add_f32_e32 v141, v138, v139
	v_add_f32_e32 v140, v140, v141
	s_waitcnt vmcnt(28)
	v_mul_f32_e32 v138, v129, v129
	v_mul_f32_e32 v139, v131, v131
	v_fmac_f32_e32 v138, v128, v128
	v_fmac_f32_e32 v139, v130, v130
	v_add_f32_e32 v141, v138, v139
	v_add_f32_e32 v140, v140, v141
	s_waitcnt vmcnt(27)
; __device__ __forceinline__ unsigned pk2(float lo, float hi) { return f2bf(lo) | (f2bf(hi) << 16); }
; __device__ __forceinline__ void phase_prologue(const Params& p, LAS unsigned char* lds) {
;     ...
;           for (int u = 0; u < UR; ++u) { const int row = row0 + u * NGW; s[u] = 0.f;
; #pragma unroll
;               for (int j = 0; j < 8; ++j) s[u] += (v[u][j][0] * v[u][j][0] + v[u][j][1] * v[u][j][1]) + (v[u][j][2] * v[u][j][2] + v[u][j][3] * v[u][j][3]);
;               s[u] = wave_sum(s[u]); if (lane == 0) rstd[row] = 1.0f / sqrtf(s[u] * (1.0f / DM) + 1e-6f);
;               u32x2* o = (u32x2*)(xb + (size_t)row * DM) + lane;
; #pragma unroll
;               for (int j = 0; j < 8; ++j) { u32x2 w; w.x = pk2(v[u][j][0], v[u][j][1]); w.y = pk2(v[u][j][2], v[u][j][3]); o[64 * j] = w; } } } }
	v_mul_f32_e32 v138, v133, v133
	v_mul_f32_e32 v139, v135, v135
	v_fmac_f32_e32 v138, v132, v132
	v_fmac_f32_e32 v139, v134, v134
	v_add_f32_e32 v141, v138, v139
	v_add_f32_e32 v140, v140, v141
	s_nop 1
	v_add_f32_dpp v140, v140, v140 quad_perm:[1,0,3,2] row_mask:0xf bank_mask:0xf
	s_nop 1
	v_add_f32_dpp v140, v140, v140 quad_perm:[2,3,0,1] row_mask:0xf bank_mask:0xf
	s_nop 1
	v_add_f32_dpp v140, v140, v140 row_half_mirror row_mask:0xf bank_mask:0xf
	s_nop 1
	v_add_f32_dpp v140, v140, v140 row_mirror row_mask:0xf bank_mask:0xf
	s_nop 1
	v_readlane_b32 s38, v140, 0
	v_readlane_b32 s39, v140, 16
	v_readlane_b32 s52, v140, 32
	v_readlane_b32 s53, v140, 48
	s_nop 1
	v_mov_b32_e32 v161, s39
	v_mov_b32_e32 v163, s53
	v_add_f32_e32 v161, s38, v161
	v_add_f32_e32 v163, s52, v163
	v_add_f32_e32 v146, v161, v163
	v_fmamk_f32 v147, v146, 0x3a000000, v136
	v_mul_f32_e32 v148, 0x4f800000, v147
	v_cmp_gt_f32_e32 vcc, v7, v147
	s_nop 1
	v_cndmask_b32_e32 v149, v147, v148, vcc
	v_sqrt_f32_e32 v150, v149
	s_nop 0
	v_add_u32_e32 v151, -1, v150
	v_add_u32_e32 v152, 1, v150
	v_fma_f32 v153, -v151, v150, v149
	v_fma_f32 v154, -v152, v150, v149
	v_cmp_ge_f32_e64 s[0:1], 0, v153
	s_nop 1
	v_cndmask_b32_e64 v155, v150, v151, s[0:1]
	v_cmp_lt_f32_e64 s[0:1], 0, v154
	s_nop 1
	v_cndmask_b32_e64 v155, v155, v152, s[0:1]
	v_mul_f32_e32 v156, 0x37800000, v155
	v_cndmask_b32_e32 v155, v155, v156, vcc
	v_cmp_class_f32_e32 vcc, v149, v137
	s_nop 1
	v_cndmask_b32_e32 v157, v155, v149, vcc
	v_div_scale_f32 v158, s[0:1], v157, v157, 1.0
	v_rcp_f32_e32 v159, v158
	v_div_scale_f32 v160, vcc, 1.0, v157, 1.0
	v_fma_f32 v161, -v158, v159, 1.0
	v_fmac_f32_e32 v159, v161, v159
	v_mul_f32_e32 v162, v160, v159
	v_fma_f32 v163, -v158, v162, v160
	v_fmac_f32_e32 v162, v163, v159
	v_fma_f32 v161, -v158, v162, v160
	v_div_fmas_f32 v164, v161, v159, v162
	v_div_fixup_f32 v165, v164, v157, 1.0
	s_mul_i32 s4, s5, 15
	s_add_u32 s4, s4, s3
	s_lshl_b32 s33, s4, 2
	s_add_u32 s36, s28, s33
	s_addc_u32 s37, s29, 0
	s_add_u32 s36, s36, 0x7c00000
	s_addc_u32 s37, s37, 0
	s_lshl_b32 s33, s4, 12
	s_add_u32 s18, s28, s33
	s_addc_u32 s19, s29, 0
	s_add_u32 s18, s18, 0x8800000
	s_addc_u32 s19, s19, 0
	s_mov_b64 exec, 1
	global_store_dword v4, v165, s[36:37]
	s_mov_b64 exec, -1
	v_bfe_u32 v166, v104, 16, 1
	v_add3_u32 v104, v104, v166, v5
	v_bfe_u32 v166, v105, 16, 1
	v_add3_u32 v105, v105, v166, v5
	v_bfe_u32 v166, v106, 16, 1
	v_add3_u32 v106, v106, v166, v5
	v_bfe_u32 v166, v107, 16, 1
	v_add3_u32 v107, v107, v166, v5
	v_lshrrev_b32_e32 v104, 16, v104
	v_lshrrev_b32_e32 v106, 16, v106
	v_and_or_b32 v104, v105, v6, v104
	v_and_or_b32 v105, v107, v6, v106
	global_store_dwordx2 v3, v[104:105], s[18:19]
	v_bfe_u32 v166, v108, 16, 1
	v_add3_u32 v108, v108, v166, v5
	v_bfe_u32 v166, v109, 16, 1
	v_add3_u32 v109, v109, v166, v5
	v_bfe_u32 v166, v110, 16, 1
	v_add3_u32 v110, v110, v166, v5
	v_bfe_u32 v166, v111, 16, 1
	v_add3_u32 v111, v111, v166, v5
	v_lshrrev_b32_e32 v108, 16, v108
	v_lshrrev_b32_e32 v110, 16, v110
	v_and_or_b32 v108, v109, v6, v108
	v_and_or_b32 v109, v111, v6, v110
	global_store_dwordx2 v3, v[108:109], s[18:19] offset:512
	v_bfe_u32 v166, v112, 16, 1
	v_add3_u32 v112, v112, v166, v5
	v_bfe_u32 v166, v113, 16, 1
	v_add3_u32 v113, v113, v166, v5
	v_bfe_u32 v166, v114, 16, 1
	v_add3_u32 v114, v114, v166, v5
	v_bfe_u32 v166, v115, 16, 1
	v_add3_u32 v115, v115, v166, v5
	v_lshrrev_b32_e32 v112, 16, v112
	v_lshrrev_b32_e32 v114, 16, v114
	v_and_or_b32 v112, v113, v6, v112
	v_and_or_b32 v113, v115, v6, v114
	global_store_dwordx2 v3, v[112:113], s[18:19] offset:1024
	v_bfe_u32 v166, v116, 16, 1
	v_add3_u32 v116, v116, v166, v5
	v_bfe_u32 v166, v117, 16, 1
	v_add3_u32 v117, v117, v166, v5
	v_bfe_u32 v166, v118, 16, 1
	v_add3_u32 v118, v118, v166, v5
	v_bfe_u32 v166, v119, 16, 1
	v_add3_u32 v119, v119, v166, v5
	v_lshrrev_b32_e32 v116, 16, v116
	v_lshrrev_b32_e32 v118, 16, v118
	v_and_or_b32 v116, v117, v6, v116
	v_and_or_b32 v117, v119, v6, v118
	global_store_dwordx2 v3, v[116:117], s[18:19] offset:1536
	v_bfe_u32 v166, v120, 16, 1
	v_add3_u32 v120, v120, v166, v5
	v_bfe_u32 v166, v121, 16, 1
	v_add3_u32 v121, v121, v166, v5
	v_bfe_u32 v166, v122, 16, 1
	v_add3_u32 v122, v122, v166, v5
	v_bfe_u32 v166, v123, 16, 1
	v_add3_u32 v123, v123, v166, v5
	v_lshrrev_b32_e32 v120, 16, v120
	v_lshrrev_b32_e32 v122, 16, v122
	v_and_or_b32 v120, v121, v6, v120
	v_and_or_b32 v121, v123, v6, v122
	global_store_dwordx2 v3, v[120:121], s[18:19] offset:2048
	v_bfe_u32 v166, v124, 16, 1
	v_add3_u32 v124, v124, v166, v5
	v_bfe_u32 v166, v125, 16, 1
	v_add3_u32 v125, v125, v166, v5
	v_bfe_u32 v166, v126, 16, 1
	v_add3_u32 v126, v126, v166, v5
	v_bfe_u32 v166, v127, 16, 1
	v_add3_u32 v127, v127, v166, v5
	v_lshrrev_b32_e32 v124, 16, v124
	v_lshrrev_b32_e32 v126, 16, v126
	v_and_or_b32 v124, v125, v6, v124
	v_and_or_b32 v125, v127, v6, v126
	global_store_dwordx2 v3, v[124:125], s[18:19] offset:2560
	v_bfe_u32 v166, v128, 16, 1
	v_add3_u32 v128, v128, v166, v5
	v_bfe_u32 v166, v129, 16, 1
	v_add3_u32 v129, v129, v166, v5
	v_bfe_u32 v166, v130, 16, 1
	v_add3_u32 v130, v130, v166, v5
	v_bfe_u32 v166, v131, 16, 1
	v_add3_u32 v131, v131, v166, v5
	v_lshrrev_b32_e32 v128, 16, v128
	v_lshrrev_b32_e32 v130, 16, v130
	v_and_or_b32 v128, v129, v6, v128
	v_and_or_b32 v129, v131, v6, v130
	global_store_dwordx2 v3, v[128:129], s[18:19] offset:3072
	v_bfe_u32 v166, v132, 16, 1
	v_add3_u32 v132, v132, v166, v5
	v_bfe_u32 v166, v133, 16, 1
	v_add3_u32 v133, v133, v166, v5
	v_bfe_u32 v166, v134, 16, 1
	v_add3_u32 v134, v134, v166, v5
	v_bfe_u32 v166, v135, 16, 1
	v_add3_u32 v135, v135, v166, v5
	v_lshrrev_b32_e32 v132, 16, v132
	v_lshrrev_b32_e32 v134, 16, v134
	v_and_or_b32 v132, v133, v6, v132
	v_and_or_b32 v133, v135, v6, v134
	global_store_dwordx2 v3, v[132:133], s[18:19] offset:3584
